# gMLP item: u-gate loads of each 128-channel group issued together at the group top, and all 32 z-gate loads of the final stage issued up front (were one load + immediate wait per MFMA group)
# speedup vs baseline: 1.0084x; 1.0084x over previous
.LBB0_897:
	s_or_b64 exec, exec, s[12:13]
	v_bfe_u32 v32, v4, 2, 7
	v_lshl_add_u64 v[0:1], s[4:5], 0, v[32:33]
	v_mad_u64_u32 v[2:3], s[12:13], v0, s9, v[34:35]
	v_mov_b32_e32 v0, v3
	v_mad_u64_u32 v[0:1], s[12:13], v1, s9, v[0:1]
	v_mov_b32_e32 v3, v0
	v_lshlrev_b32_e32 v0, 3, v4
	v_and_b32_e32 v5, 24, v0
	v_lshlrev_b32_e32 v0, 1, v5
	v_mov_b32_e32 v1, v33
	v_lshl_add_u64 v[46:47], v[2:3], 0, v[0:1]
	global_load_dwordx4 v[8:11], v[46:47], off offset:2048
	v_lshlrev_b32_e32 v157, 2, v5
	global_load_dwordx4 v[12:15], v[46:47], off offset:2112
	global_load_dwordx4 v[16:19], v[46:47], off offset:2176
	global_load_dwordx4 v[0:3], v[46:47], off offset:2240
	s_waitcnt lgkmcnt(0)
	s_barrier
	global_load_dwordx4 v[20:23], v157, s[48:49]
	global_load_dwordx4 v[24:27], v157, s[50:51]
	global_load_dwordx4 v[28:31], v157, s[48:49] offset:16
	global_load_dwordx4 v[36:39], v157, s[50:51] offset:16
	v_lshl_add_u32 v6, v32, 3, 0
	v_lshlrev_b32_e32 v7, 1, v32
	v_add_u32_e32 v160, 0x11000, v6
	v_mul_u32_u24_e32 v5, 0x110, v5
	v_add3_u32 v155, 0, v7, v5
	ds_read_b64 v[6:7], v160
	v_ashrrev_i32_e32 v44, 2, v4
	v_and_b32_e32 v50, 15, v4
	v_mov_b32_e32 v49, v33
	v_readlane_b32 s56, v254, 12
	v_readlane_b32 s58, v254, 14
	v_readlane_b32 s59, v254, 15
	v_readlane_b32 s57, v254, 13
	v_readlane_b32 s60, v254, 16
	v_readlane_b32 s61, v254, 17
	v_readlane_b32 s62, v254, 18
	v_readlane_b32 s63, v254, 19
	v_readlane_b32 s64, v254, 20
	v_readlane_b32 s65, v254, 21
	v_readlane_b32 s66, v254, 22
	v_readlane_b32 s67, v254, 23
	v_readlane_b32 s68, v254, 24
	v_readlane_b32 s69, v254, 25
	v_readlane_b32 s70, v254, 26
	v_readlane_b32 s71, v254, 27
	s_waitcnt vmcnt(7)
	v_lshlrev_b32_e32 v5, 16, v8
	s_waitcnt lgkmcnt(0)
	v_sub_f32_e32 v5, v5, v6
	v_and_b32_e32 v8, 0xffff0000, v8
	v_mul_f32_e32 v5, v7, v5
	v_lshlrev_b32_e32 v32, 16, v9
	v_sub_f32_e32 v8, v8, v6
	s_waitcnt vmcnt(2)
	v_fma_f32 v5, v20, v5, v24
	v_and_b32_e32 v9, 0xffff0000, v9
	v_sub_f32_e32 v32, v32, v6
	v_mul_f32_e32 v8, v7, v8
	v_cvt_pk_bf16_f32 v5, v5, v33
	v_lshlrev_b32_e32 v40, 16, v10
	v_sub_f32_e32 v9, v9, v6
	v_mul_f32_e32 v32, v7, v32
	v_fma_f32 v8, v21, v8, v25
	ds_write_b16 v155, v5
	v_cvt_pk_bf16_f32 v5, v8, v33
	v_and_b32_e32 v10, 0xffff0000, v10
	v_sub_f32_e32 v40, v40, v6
	v_mul_f32_e32 v9, v7, v9
	v_fma_f32 v20, v22, v32, v26
	ds_write_b16 v155, v5 offset:272
	v_cvt_pk_bf16_f32 v5, v20, v33
	v_lshlrev_b32_e32 v41, 16, v11
	v_sub_f32_e32 v10, v10, v6
	v_mul_f32_e32 v40, v7, v40
	v_fmac_f32_e32 v27, v23, v9
	ds_write_b16 v155, v5 offset:544
	v_cvt_pk_bf16_f32 v5, v27, v33
	v_and_b32_e32 v11, 0xffff0000, v11
	v_sub_f32_e32 v41, v41, v6
	v_mul_f32_e32 v10, v7, v10
	s_waitcnt vmcnt(0)
	v_fma_f32 v9, v40, v28, v36
	ds_write_b16 v155, v5 offset:816
	v_cvt_pk_bf16_f32 v5, v9, v33
	v_sub_f32_e32 v11, v11, v6
	v_mul_f32_e32 v41, v7, v41
	v_fma_f32 v10, v10, v29, v37
	ds_write_b16 v155, v5 offset:1088
	v_cvt_pk_bf16_f32 v5, v10, v33
	v_mul_f32_e32 v11, v7, v11
	v_fma_f32 v21, v41, v30, v38
	ds_write_b16 v155, v5 offset:1360
	v_cvt_pk_bf16_f32 v5, v21, v33
	v_fmac_f32_e32 v39, v11, v31
	ds_write_b16 v155, v5 offset:1632
	v_cvt_pk_bf16_f32 v5, v39, v33
	global_load_dwordx4 v[8:11], v157, s[48:49] offset:128
	global_load_dwordx4 v[20:23], v157, s[50:51] offset:128
	global_load_dwordx4 v[24:27], v157, s[48:49] offset:144
	global_load_dwordx4 v[28:31], v157, s[50:51] offset:144
	v_lshlrev_b32_e32 v32, 16, v12
	v_sub_f32_e32 v32, v32, v6
	v_and_b32_e32 v12, 0xffff0000, v12
	v_mul_f32_e32 v32, v7, v32
	v_lshlrev_b32_e32 v36, 16, v13
	v_sub_f32_e32 v12, v12, v6
	ds_write_b16 v155, v5 offset:1904
	v_and_b32_e32 v13, 0xffff0000, v13
	v_sub_f32_e32 v36, v36, v6
	v_mul_f32_e32 v12, v7, v12
	v_lshlrev_b32_e32 v37, 16, v14
	v_sub_f32_e32 v13, v13, v6
	v_mul_f32_e32 v36, v7, v36
	v_and_b32_e32 v14, 0xffff0000, v14
	v_sub_f32_e32 v37, v37, v6
	v_mul_f32_e32 v13, v7, v13
	v_lshlrev_b32_e32 v38, 16, v15
	v_sub_f32_e32 v14, v14, v6
	v_mul_f32_e32 v37, v7, v37
	v_and_b32_e32 v15, 0xffff0000, v15
	v_sub_f32_e32 v38, v38, v6
	v_mul_f32_e32 v14, v7, v14
	v_sub_f32_e32 v15, v15, v6
	v_mul_f32_e32 v38, v7, v38
	v_mul_f32_e32 v15, v7, v15
	s_waitcnt vmcnt(2)
	v_fma_f32 v5, v32, v8, v20
	v_cvt_pk_bf16_f32 v5, v5, v33
	v_fma_f32 v8, v12, v9, v21
	ds_write_b16 v155, v5 offset:8704
	v_cvt_pk_bf16_f32 v5, v8, v33
	v_fma_f32 v9, v36, v10, v22
	ds_write_b16 v155, v5 offset:8976
	v_cvt_pk_bf16_f32 v5, v9, v33
	v_fmac_f32_e32 v23, v13, v11
	ds_write_b16 v155, v5 offset:9248
	v_cvt_pk_bf16_f32 v5, v23, v33
	s_waitcnt vmcnt(0)
	v_fma_f32 v10, v37, v24, v28
	ds_write_b16 v155, v5 offset:9520
	v_cvt_pk_bf16_f32 v5, v10, v33
	v_fma_f32 v11, v14, v25, v29
	ds_write_b16 v155, v5 offset:9792
	v_cvt_pk_bf16_f32 v5, v11, v33
	v_fma_f32 v12, v38, v26, v30
	ds_write_b16 v155, v5 offset:10064
	v_cvt_pk_bf16_f32 v5, v12, v33
	v_fmac_f32_e32 v31, v15, v27
	ds_write_b16 v155, v5 offset:10336
	v_cvt_pk_bf16_f32 v5, v31, v33
	global_load_dwordx4 v[8:11], v157, s[48:49] offset:256
	global_load_dwordx4 v[12:15], v157, s[50:51] offset:256
	global_load_dwordx4 v[20:23], v157, s[48:49] offset:272
	global_load_dwordx4 v[24:27], v157, s[50:51] offset:272
	v_lshlrev_b32_e32 v28, 16, v16
	v_sub_f32_e32 v28, v28, v6
	v_and_b32_e32 v16, 0xffff0000, v16
	v_mul_f32_e32 v28, v7, v28
	v_lshlrev_b32_e32 v29, 16, v17
	v_sub_f32_e32 v16, v16, v6
	ds_write_b16 v155, v5 offset:10608
	v_and_b32_e32 v17, 0xffff0000, v17
	v_sub_f32_e32 v29, v29, v6
	v_mul_f32_e32 v16, v7, v16
	v_lshlrev_b32_e32 v30, 16, v18
	v_sub_f32_e32 v17, v17, v6
	v_mul_f32_e32 v29, v7, v29
	v_and_b32_e32 v18, 0xffff0000, v18
	v_sub_f32_e32 v30, v30, v6
	v_mul_f32_e32 v17, v7, v17
	v_lshlrev_b32_e32 v31, 16, v19
	v_sub_f32_e32 v18, v18, v6
	v_mul_f32_e32 v30, v7, v30
	v_and_b32_e32 v19, 0xffff0000, v19
	v_sub_f32_e32 v31, v31, v6
	v_mul_f32_e32 v18, v7, v18
	v_sub_f32_e32 v19, v19, v6
	v_mul_f32_e32 v31, v7, v31
	v_mul_f32_e32 v19, v7, v19
	s_waitcnt vmcnt(2)
	v_fma_f32 v5, v28, v8, v12
	v_cvt_pk_bf16_f32 v5, v5, v33
	v_fma_f32 v8, v16, v9, v13
	ds_write_b16 v155, v5 offset:17408
	v_cvt_pk_bf16_f32 v5, v8, v33
	v_fma_f32 v9, v29, v10, v14
	ds_write_b16 v155, v5 offset:17680
	v_cvt_pk_bf16_f32 v5, v9, v33
	v_fmac_f32_e32 v15, v17, v11
	ds_write_b16 v155, v5 offset:17952
	v_cvt_pk_bf16_f32 v5, v15, v33
	s_waitcnt vmcnt(0)
	v_fma_f32 v10, v30, v20, v24
	ds_write_b16 v155, v5 offset:18224
	v_cvt_pk_bf16_f32 v5, v10, v33
	v_fma_f32 v11, v18, v21, v25
	ds_write_b16 v155, v5 offset:18496
	v_cvt_pk_bf16_f32 v5, v11, v33
	v_fma_f32 v12, v31, v22, v26
	ds_write_b16 v155, v5 offset:18768
	v_cvt_pk_bf16_f32 v5, v12, v33
	v_fmac_f32_e32 v27, v19, v23
	ds_write_b16 v155, v5 offset:19040
	v_cvt_pk_bf16_f32 v5, v27, v33
	global_load_dwordx4 v[8:11], v157, s[48:49] offset:384
	global_load_dwordx4 v[12:15], v157, s[50:51] offset:384
	global_load_dwordx4 v[16:19], v157, s[48:49] offset:400
	global_load_dwordx4 v[20:23], v157, s[50:51] offset:400
	v_bfe_u32 v24, v4, 4, 2
	v_and_b32_e32 v26, -16, v44
	v_lshlrev_b32_e32 v32, 3, v24
	v_lshlrev_b32_e32 v48, 4, v24
	v_ashrrev_i32_e32 v25, 31, v26
	v_or_b32_e32 v24, v26, v50
	v_lshl_add_u64 v[26:27], s[0:1], 0, v[48:49]
	v_lshl_add_u64 v[36:37], s[4:5], 0, v[24:25]
	v_lshlrev_b64 v[24:25], 8, v[24:25]
	v_lshl_add_u64 v[42:43], v[26:27], 0, v[24:25]
	v_lshlrev_b32_e32 v24, 16, v0
	v_and_b32_e32 v0, 0xffff0000, v0
	v_lshlrev_b32_e32 v27, 16, v3
	v_and_b32_e32 v3, 0xffff0000, v3
	v_sub_f32_e32 v0, v0, v6
	v_lshlrev_b32_e32 v25, 16, v1
	v_and_b32_e32 v1, 0xffff0000, v1
	v_lshlrev_b32_e32 v26, 16, v2
	v_and_b32_e32 v2, 0xffff0000, v2
	v_sub_f32_e32 v24, v24, v6
	v_sub_f32_e32 v3, v3, v6
	v_mul_f32_e32 v0, v7, v0
	v_sub_f32_e32 v25, v25, v6
	v_sub_f32_e32 v1, v1, v6
	v_sub_f32_e32 v26, v26, v6
	v_sub_f32_e32 v2, v2, v6
	v_sub_f32_e32 v27, v27, v6
	v_mul_f32_e32 v6, v7, v24
	v_mul_f32_e32 v3, v7, v3
	v_mul_f32_e32 v24, v7, v25
	ds_write_b16 v155, v5 offset:19312
	v_mul_f32_e32 v1, v7, v1
	v_mul_f32_e32 v25, v7, v26
	v_mul_f32_e32 v2, v7, v2
	v_mul_f32_e32 v26, v7, v27
	v_mad_u64_u32 v[38:39], s[12:13], v36, s9, v[34:35]
	s_waitcnt vmcnt(2)
	v_fma_f32 v0, v0, v9, v13
	v_fma_f32 v5, v6, v8, v12
	s_waitcnt vmcnt(0)
	v_fmac_f32_e32 v23, v3, v19
	v_cvt_pk_bf16_f32 v3, v5, v33
	ds_write_b16 v155, v3 offset:26112
	v_cvt_pk_bf16_f32 v0, v0, v33
	v_fma_f32 v6, v24, v10, v14
	ds_write_b16 v155, v0 offset:26384
	v_cvt_pk_bf16_f32 v0, v6, v33
	v_fmac_f32_e32 v15, v1, v11
	ds_write_b16 v155, v0 offset:26656
	v_cvt_pk_bf16_f32 v0, v15, v33
	v_fma_f32 v1, v25, v16, v20
	ds_write_b16 v155, v0 offset:26928
	v_cvt_pk_bf16_f32 v0, v1, v33
	v_fma_f32 v2, v2, v17, v21
	ds_write_b16 v155, v0 offset:27200
	v_cvt_pk_bf16_f32 v0, v2, v33
	v_fma_f32 v7, v26, v18, v22
	ds_write_b16 v155, v0 offset:27472
	v_cvt_pk_bf16_f32 v0, v7, v33
	ds_write_b16 v155, v0 offset:27744
	v_cvt_pk_bf16_f32 v0, v23, v33
	ds_write_b16 v155, v0 offset:28016
	s_waitcnt lgkmcnt(0)
	s_barrier
	global_load_dwordx4 v[20:23], v[42:43], off
	global_load_dwordx4 v[24:27], v[42:43], off offset:64
	v_mov_b32_e32 v0, v39
	v_mad_u64_u32 v[0:1], s[12:13], v37, s9, v[0:1]
	v_mov_b32_e32 v39, v0
	v_lshl_add_u64 v[40:41], v[38:39], 0, v[32:33]
	global_load_dwordx2 v[224:225], v[40:41], off offset:1056
	global_load_dwordx2 v[226:227], v[40:41], off offset:1088
	global_load_dwordx2 v[228:229], v[40:41], off offset:1120
	global_load_dwordx2 v[230:231], v[40:41], off offset:1152
	global_load_dwordx2 v[232:233], v[40:41], off offset:1184
	global_load_dwordx2 v[234:235], v[40:41], off offset:1216
	global_load_dwordx2 v[236:237], v[40:41], off offset:1248
	global_load_dwordx2 v[52:53], v[40:41], off offset:1024
	global_load_dwordx4 v[28:31], v[42:43], off offset:128
	global_load_dwordx4 v[16:19], v[42:43], off offset:192
	v_bfi_b32 v0, -16, v44, v4
	v_ashrrev_i32_e32 v1, 31, v0
	v_lshl_add_u64 v[44:45], v[0:1], 2, s[58:59]
	global_load_dword v54, v[44:45], off
	v_mul_u32_u24_e32 v0, 0x110, v50
	v_add3_u32 v152, 0, v48, v0
	ds_read_b128 v[0:3], v152
	ds_read_b128 v[4:7], v152 offset:64
	ds_read_b128 v[48:51], v152 offset:128
	s_waitcnt vmcnt(5) lgkmcnt(2)
	v_mfma_f32_16x16x32_bf16 v[0:3], v[0:3], v[20:23], 0
	global_load_dwordx4 v[12:15], v[46:47], off offset:2304
	global_load_dwordx4 v[8:11], v[46:47], off offset:2368
	ds_read_b128 v[56:59], v152 offset:192
	s_waitcnt vmcnt(5)
	v_lshlrev_b32_e32 v64, 16, v52
	s_waitcnt lgkmcnt(2)
	v_mfma_f32_16x16x32_bf16 v[60:63], v[4:7], v[24:27], v[0:3]
	v_and_b32_e32 v65, 0xffff0000, v52
	v_lshlrev_b32_e32 v52, 16, v53
	v_and_b32_e32 v53, 0xffff0000, v53
	s_waitcnt vmcnt(4) lgkmcnt(1)
	v_mfma_f32_16x16x32_bf16 v[48:51], v[48:51], v[28:31], v[60:63]
	global_load_dwordx4 v[4:7], v[46:47], off offset:2432
	global_load_dwordx4 v[0:3], v[46:47], off offset:2496
	s_waitcnt vmcnt(0)
	v_lshlrev_b32_e32 v101, 16, v2
	s_waitcnt lgkmcnt(0)
	v_mfma_f32_16x16x32_bf16 v[48:51], v[56:59], v[16:19], v[48:51]
	v_and_b32_e32 v102, 0xffff0000, v2
	v_and_b32_e32 v100, 0xffff0000, v1
	v_lshlrev_b32_e32 v103, 16, v3
	v_and_b32_e32 v104, 0xffff0000, v3
	s_nop 3
	v_pk_add_f32 v[48:49], v[54:55], v[48:49] op_sel_hi:[0,1]
	v_pk_add_f32 v[50:51], v[54:55], v[50:51] op_sel_hi:[0,1]
	v_pk_mul_f32 v[48:49], v[48:49], v[64:65]
	v_pk_mul_f32 v[50:51], v[50:51], v[52:53]
	v_cvt_pk_bf16_f32 v150, v48, v49
	v_mul_f32_e32 v2, v49, v49
	v_cvt_pk_bf16_f32 v148, v50, v51
	ds_read_b128 v[56:59], v152 offset:4352
	ds_read_b128 v[60:63], v152 offset:4416
	s_waitcnt lgkmcnt(1)
	v_mfma_f32_16x16x32_bf16 v[56:59], v[56:59], v[20:23], 0
	v_pk_fma_f32 v[2:3], v[48:49], v[48:49], v[2:3] op_sel_hi:[1,1,0]
	s_nop 0
	v_mov_b32_e32 v84, v2
	s_waitcnt lgkmcnt(0)
	v_mfma_f32_16x16x32_bf16 v[56:59], v[60:63], v[24:27], v[56:59]
	ds_read_b128 v[60:63], v152 offset:4480
	ds_read_b128 v[64:67], v152 offset:4544
	v_mov_b64_e32 v[52:53], v[224:225]
	s_waitcnt lgkmcnt(1)
	v_mfma_f32_16x16x32_bf16 v[56:59], v[60:63], v[28:31], v[56:59]
	s_waitcnt vmcnt(0)
	v_lshlrev_b32_e32 v60, 16, v52
	s_waitcnt lgkmcnt(0)
	v_mfma_f32_16x16x32_bf16 v[56:59], v[64:67], v[16:19], v[56:59]
	v_and_b32_e32 v61, 0xffff0000, v52
	v_lshlrev_b32_e32 v62, 16, v53
	v_and_b32_e32 v63, 0xffff0000, v53
	s_nop 4
	v_pk_add_f32 v[56:57], v[54:55], v[56:57] op_sel_hi:[0,1]
	v_pk_add_f32 v[58:59], v[54:55], v[58:59] op_sel_hi:[0,1]
	v_pk_mul_f32 v[52:53], v[56:57], v[60:61]
	v_pk_mul_f32 v[60:61], v[58:59], v[62:63]
	v_cvt_pk_bf16_f32 v145, v52, v53
	s_nop 0
	v_cvt_pk_bf16_f32 v142, v60, v61
	ds_read_b128 v[56:59], v152 offset:8704
	ds_read_b128 v[62:65], v152 offset:8768
	s_waitcnt lgkmcnt(1)
	v_mfma_f32_16x16x32_bf16 v[56:59], v[56:59], v[20:23], 0
	s_waitcnt lgkmcnt(0)
	v_mfma_f32_16x16x32_bf16 v[56:59], v[62:65], v[24:27], v[56:59]
	ds_read_b128 v[62:65], v152 offset:8832
	ds_read_b128 v[66:69], v152 offset:8896
	s_waitcnt lgkmcnt(1)
	v_mfma_f32_16x16x32_bf16 v[56:59], v[62:65], v[28:31], v[56:59]
	v_mov_b64_e32 v[62:63], v[226:227]
	s_waitcnt vmcnt(0)
	v_lshlrev_b32_e32 v65, 16, v63
	s_waitcnt lgkmcnt(0)
	v_mfma_f32_16x16x32_bf16 v[56:59], v[66:69], v[16:19], v[56:59]
	v_and_b32_e32 v63, 0xffff0000, v63
	s_nop 6
	v_add_f32_e32 v55, v54, v56
	v_add_f32_e32 v56, v54, v57
	v_add_f32_e32 v57, v54, v58
	v_add_f32_e32 v58, v54, v59
	v_lshlrev_b32_e32 v59, 16, v62
	v_and_b32_e32 v62, 0xffff0000, v62
	v_mul_f32_e32 v64, v55, v59
	v_mul_f32_e32 v68, v56, v62
	v_mul_f32_e32 v66, v57, v65
	v_mul_f32_e32 v62, v58, v63
	v_cvt_pk_bf16_f32 v139, v64, v68
	v_cvt_pk_bf16_f32 v137, v66, v62
	ds_read_b128 v[56:59], v152 offset:13056
	ds_read_b128 v[70:73], v152 offset:13120
	s_waitcnt lgkmcnt(1)
	v_mfma_f32_16x16x32_bf16 v[56:59], v[56:59], v[20:23], 0
	s_waitcnt lgkmcnt(0)
	v_mfma_f32_16x16x32_bf16 v[56:59], v[70:73], v[24:27], v[56:59]
	ds_read_b128 v[70:73], v152 offset:13184
	ds_read_b128 v[74:77], v152 offset:13248
	v_mov_b64_e32 v[78:79], v[228:229]
	s_waitcnt lgkmcnt(1)
	v_mfma_f32_16x16x32_bf16 v[56:59], v[70:73], v[28:31], v[56:59]
	v_mov_b32_e32 v70, v64
	v_mov_b32_e32 v72, v66
	s_waitcnt vmcnt(0)
	v_lshlrev_b32_e32 v71, 16, v79
	s_waitcnt lgkmcnt(0)
	v_mfma_f32_16x16x32_bf16 v[56:59], v[74:77], v[16:19], v[56:59]
	v_and_b32_e32 v73, 0xffff0000, v79
	s_nop 6
	v_add_f32_e32 v55, v54, v56
	v_add_f32_e32 v56, v54, v57
	v_add_f32_e32 v65, v54, v58
	v_add_f32_e32 v67, v54, v59
	v_lshlrev_b32_e32 v57, 16, v78
	v_and_b32_e32 v58, 0xffff0000, v78
	v_mul_f32_e32 v85, v55, v57
	v_mul_f32_e32 v75, v56, v58
	v_pk_mul_f32 v[86:87], v[64:65], v[70:71]
	v_pk_mul_f32 v[88:89], v[66:67], v[72:73]
	v_cvt_pk_bf16_f32 v136, v85, v75
	v_lshlrev_b32_e32 v72, 16, v15
	v_cvt_pk_bf16_f32 v133, v87, v89
	ds_read_b128 v[56:59], v152 offset:17408
	ds_read_b128 v[76:79], v152 offset:17472
	s_waitcnt lgkmcnt(1)
	v_mfma_f32_16x16x32_bf16 v[56:59], v[56:59], v[20:23], 0
	v_and_b32_e32 v15, 0xffff0000, v15
	v_pk_mul_f32 v[48:49], v[88:89], v[88:89]
	s_waitcnt lgkmcnt(0)
	v_mfma_f32_16x16x32_bf16 v[56:59], v[76:79], v[24:27], v[56:59]
	ds_read_b128 v[76:79], v152 offset:17536
	ds_read_b128 v[80:83], v152 offset:17600
	s_waitcnt lgkmcnt(1)
	v_mfma_f32_16x16x32_bf16 v[56:59], v[76:79], v[28:31], v[56:59]
	v_mov_b64_e32 v[76:77], v[230:231]
	s_waitcnt lgkmcnt(0)
	v_mfma_f32_16x16x32_bf16 v[56:59], v[80:83], v[16:19], v[56:59]
	s_nop 7
	v_mov_b32_e32 v78, v56
	v_mov_b32_e32 v79, v58
	v_mov_b32_e32 v58, v57
	v_pk_add_f32 v[56:57], v[54:55], v[78:79] op_sel_hi:[0,1]
	v_pk_add_f32 v[58:59], v[54:55], v[58:59] op_sel_hi:[0,1]
	s_waitcnt vmcnt(0)
	v_lshlrev_b32_e32 v79, 16, v77
	v_lshlrev_b32_e32 v78, 16, v76
	v_and_b32_e32 v77, 0xffff0000, v77
	v_and_b32_e32 v76, 0xffff0000, v76
	v_pk_mul_f32 v[90:91], v[56:57], v[78:79]
	v_pk_mul_f32 v[92:93], v[58:59], v[76:77]
	s_nop 0
	v_cvt_pk_bf16_f32 v134, v90, v92
	v_cvt_pk_bf16_f32 v132, v91, v93
	ds_read_b128 v[56:59], v152 offset:21760
	ds_read_b128 v[76:79], v152 offset:21824
	s_waitcnt lgkmcnt(1)
	v_mfma_f32_16x16x32_bf16 v[56:59], v[56:59], v[20:23], 0
	s_waitcnt lgkmcnt(0)
	v_mfma_f32_16x16x32_bf16 v[56:59], v[76:79], v[24:27], v[56:59]
	ds_read_b128 v[76:79], v152 offset:21888
	ds_read_b128 v[80:83], v152 offset:21952
	s_waitcnt lgkmcnt(1)
	v_mfma_f32_16x16x32_bf16 v[56:59], v[76:79], v[28:31], v[56:59]
	v_mov_b64_e32 v[76:77], v[232:233]
	s_waitcnt lgkmcnt(0)
	v_mfma_f32_16x16x32_bf16 v[56:59], v[80:83], v[16:19], v[56:59]
	s_nop 7
	v_pk_add_f32 v[56:57], v[54:55], v[56:57] op_sel_hi:[0,1]
	v_pk_add_f32 v[78:79], v[54:55], v[58:59] op_sel_hi:[0,1]
	s_waitcnt vmcnt(0)
	v_lshlrev_b32_e32 v58, 16, v76
	v_and_b32_e32 v59, 0xffff0000, v76
	v_lshlrev_b32_e32 v76, 16, v77
	v_and_b32_e32 v77, 0xffff0000, v77
	v_pk_mul_f32 v[58:59], v[56:57], v[58:59]
	v_pk_mul_f32 v[94:95], v[78:79], v[76:77]
	v_cvt_pk_bf16_f32 v130, v58, v59
	s_nop 0
	v_cvt_pk_bf16_f32 v129, v94, v95
	ds_read_b128 v[76:79], v152 offset:26112
	ds_read_b128 v[80:83], v152 offset:26176
	s_waitcnt lgkmcnt(1)
	v_mfma_f32_16x16x32_bf16 v[76:79], v[76:79], v[20:23], 0
	s_waitcnt lgkmcnt(0)
	v_mfma_f32_16x16x32_bf16 v[76:79], v[80:83], v[24:27], v[76:79]
	ds_read_b128 v[80:83], v152 offset:26240
	ds_read_b128 v[96:99], v152 offset:26304
	v_mov_b64_e32 v[56:57], v[234:235]
	s_waitcnt vmcnt(0)
	v_lshlrev_b32_e32 v66, 16, v56
	s_waitcnt lgkmcnt(1)
	v_mfma_f32_16x16x32_bf16 v[76:79], v[80:83], v[28:31], v[76:79]
	v_and_b32_e32 v56, 0xffff0000, v56
	v_lshlrev_b32_e32 v70, 16, v57
	v_and_b32_e32 v57, 0xffff0000, v57
	s_waitcnt lgkmcnt(0)
	v_mfma_f32_16x16x32_bf16 v[76:79], v[96:99], v[16:19], v[76:79]
	s_nop 7
	v_add_f32_e32 v55, v54, v76
	v_add_f32_e32 v63, v54, v77
	v_add_f32_e32 v64, v54, v78
	v_add_f32_e32 v69, v54, v79
	v_mul_f32_e32 v96, v55, v66
	v_mul_f32_e32 v66, v63, v56
	v_mul_f32_e32 v98, v64, v70
	v_mul_f32_e32 v64, v69, v57
	v_cvt_pk_bf16_f32 v128, v96, v66
	v_cvt_pk_bf16_f32 v127, v98, v64
	ds_read_b128 v[76:79], v152 offset:30464
	ds_read_b128 v[80:83], v152 offset:30528
	s_waitcnt lgkmcnt(1)
	v_mfma_f32_16x16x32_bf16 v[20:23], v[76:79], v[20:23], 0
	v_mov_b32_e32 v76, v96
	v_mov_b32_e32 v78, v98
	v_and_b32_e32 v56, 0xffff0000, v12
	s_waitcnt lgkmcnt(0)
	v_mfma_f32_16x16x32_bf16 v[20:23], v[80:83], v[24:27], v[20:23]
	ds_read_b128 v[24:27], v152 offset:30592
	ds_read_b128 v[80:83], v152 offset:30656
	v_lshlrev_b32_e32 v63, 16, v13
	v_and_b32_e32 v69, 0xffff0000, v13
	s_waitcnt lgkmcnt(1)
	v_mfma_f32_16x16x32_bf16 v[20:23], v[24:27], v[28:31], v[20:23]
	v_mov_b64_e32 v[24:25], v[236:237]
	v_lshlrev_b32_e32 v70, 16, v14
	v_and_b32_e32 v14, 0xffff0000, v14
	s_waitcnt lgkmcnt(0)
	v_mfma_f32_16x16x32_bf16 v[16:19], v[80:83], v[16:19], v[20:23]
	s_waitcnt vmcnt(0)
	v_lshlrev_b32_e32 v77, 16, v25
	s_nop 5
	v_add_f32_e32 v16, v54, v16
	v_add_f32_e32 v17, v54, v17
	v_add_f32_e32 v97, v54, v18
	v_add_f32_e32 v99, v54, v19
	v_lshlrev_b32_e32 v18, 16, v24
	v_and_b32_e32 v19, 0xffff0000, v24
	v_and_b32_e32 v79, 0xffff0000, v25
	v_mul_f32_e32 v57, v16, v18
	v_mul_f32_e32 v55, v17, v19
	v_pk_mul_f32 v[80:81], v[96:97], v[76:77]
	v_pk_mul_f32 v[82:83], v[98:99], v[78:79]
	v_cvt_pk_bf16_f32 v126, v57, v55
	v_lshlrev_b32_e32 v54, 16, v12
	v_cvt_pk_bf16_f32 v125, v81, v83
	global_load_dwordx4 v[16:19], v157, s[48:49] offset:512
	global_load_dwordx4 v[20:23], v157, s[50:51] offset:512
	global_load_dwordx4 v[24:27], v157, s[48:49] offset:528
	global_load_dwordx4 v[28:31], v157, s[50:51] offset:528
	ds_read_b64 v[12:13], v160
	v_and_b32_e32 v96, 0xffff0000, v0
	v_lshlrev_b32_e32 v98, 16, v1
	v_mov_b32_e32 v76, v66
	v_mov_b32_e32 v78, v64
	s_waitcnt lgkmcnt(0)
	v_sub_f32_e32 v54, v54, v12
	v_sub_f32_e32 v15, v15, v12
	v_sub_f32_e32 v56, v56, v12
	v_mul_f32_e32 v54, v13, v54
	v_mul_f32_e32 v15, v13, v15
	v_sub_f32_e32 v63, v63, v12
	v_mul_f32_e32 v56, v13, v56
	v_sub_f32_e32 v69, v69, v12
	v_sub_f32_e32 v14, v14, v12
	v_mul_f32_e32 v63, v13, v63
	v_sub_f32_e32 v70, v70, v12
	v_mul_f32_e32 v69, v13, v69
	v_mul_f32_e32 v14, v13, v14
	v_sub_f32_e32 v72, v72, v12
	v_mul_f32_e32 v70, v13, v70
	v_mul_f32_e32 v72, v13, v72
	s_waitcnt vmcnt(2)
	v_fma_f32 v16, v16, v54, v20
	v_fma_f32 v17, v17, v56, v21
	s_waitcnt vmcnt(0)
	v_fmac_f32_e32 v31, v27, v15
	v_cvt_pk_bf16_f32 v15, v16, v33
	ds_write_b16 v155, v15 offset:34816
	v_cvt_pk_bf16_f32 v15, v17, v33
	v_fma_f32 v18, v18, v63, v22
	ds_write_b16 v155, v15 offset:35088
	v_cvt_pk_bf16_f32 v15, v18, v33
	v_fmac_f32_e32 v23, v19, v69
	v_fma_f32 v14, v25, v14, v29
	ds_write_b16 v155, v15 offset:35360
	v_cvt_pk_bf16_f32 v15, v23, v33
	v_fma_f32 v19, v24, v70, v28
	ds_write_b16 v155, v15 offset:35632
	v_cvt_pk_bf16_f32 v15, v19, v33
	ds_write_b16 v155, v15 offset:35904
	v_cvt_pk_bf16_f32 v14, v14, v33
	v_fma_f32 v20, v26, v72, v30
	ds_write_b16 v155, v14 offset:36176
	v_cvt_pk_bf16_f32 v14, v20, v33
	ds_write_b16 v155, v14 offset:36448
	v_cvt_pk_bf16_f32 v30, v31, v33
	global_load_dwordx4 v[14:17], v157, s[48:49] offset:640
	global_load_dwordx4 v[18:21], v157, s[50:51] offset:640
	global_load_dwordx4 v[22:25], v157, s[48:49] offset:656
	global_load_dwordx4 v[26:29], v157, s[50:51] offset:656
	v_lshlrev_b32_e32 v31, 16, v8
	v_and_b32_e32 v8, 0xffff0000, v8
	v_lshlrev_b32_e32 v63, 16, v11
	v_and_b32_e32 v11, 0xffff0000, v11
	v_sub_f32_e32 v8, v8, v12
	v_lshlrev_b32_e32 v54, 16, v9
	v_sub_f32_e32 v31, v31, v12
	v_sub_f32_e32 v11, v11, v12
	v_mul_f32_e32 v8, v13, v8
	v_and_b32_e32 v9, 0xffff0000, v9
	v_sub_f32_e32 v54, v54, v12
	v_mul_f32_e32 v31, v13, v31
	v_mul_f32_e32 v11, v13, v11
	v_lshlrev_b32_e32 v56, 16, v10
	v_sub_f32_e32 v9, v9, v12
	v_mul_f32_e32 v54, v13, v54
	ds_write_b16 v155, v30 offset:36720
	v_and_b32_e32 v10, 0xffff0000, v10
	v_sub_f32_e32 v56, v56, v12
	v_mul_f32_e32 v9, v13, v9
	v_sub_f32_e32 v10, v10, v12
	v_mul_f32_e32 v56, v13, v56
	v_sub_f32_e32 v63, v63, v12
	v_mul_f32_e32 v10, v13, v10
	v_mul_f32_e32 v63, v13, v63
	v_lshlrev_b32_e32 v30, 16, v7
	v_and_b32_e32 v7, 0xffff0000, v7
	v_sub_f32_e32 v7, v7, v12
	v_mul_f32_e32 v7, v13, v7
	v_sub_f32_e32 v30, v30, v12
	v_mul_f32_e32 v30, v13, v30
	v_mov_b32_e32 v69, v65
	v_mov_b32_e32 v70, v68
	v_mov_b32_e32 v72, v62
	v_mov_b32_e32 v65, v99
	s_waitcnt vmcnt(2)
	v_fma_f32 v8, v8, v15, v19
	v_fma_f32 v14, v31, v14, v18
	s_waitcnt vmcnt(0)
	v_fmac_f32_e32 v29, v11, v25
	v_cvt_pk_bf16_f32 v11, v14, v33
	ds_write_b16 v155, v11 offset:43520
	v_cvt_pk_bf16_f32 v8, v8, v33
	v_fma_f32 v15, v54, v16, v20
	ds_write_b16 v155, v8 offset:43792
	v_cvt_pk_bf16_f32 v8, v15, v33
	v_fmac_f32_e32 v21, v9, v17
	ds_write_b16 v155, v8 offset:44064
	v_cvt_pk_bf16_f32 v8, v21, v33
	v_fma_f32 v9, v56, v22, v26
	ds_write_b16 v155, v8 offset:44336
	v_cvt_pk_bf16_f32 v8, v9, v33
	v_fma_f32 v10, v10, v23, v27
	ds_write_b16 v155, v8 offset:44608
	v_cvt_pk_bf16_f32 v8, v10, v33
	v_fma_f32 v16, v63, v24, v28
	ds_write_b16 v155, v8 offset:44880
	v_cvt_pk_bf16_f32 v8, v16, v33
	ds_write_b16 v155, v8 offset:45152
	v_cvt_pk_bf16_f32 v26, v29, v33
	global_load_dwordx4 v[8:11], v157, s[48:49] offset:768
	global_load_dwordx4 v[14:17], v157, s[50:51] offset:768
	global_load_dwordx4 v[18:21], v157, s[48:49] offset:784
	global_load_dwordx4 v[22:25], v157, s[50:51] offset:784
	v_lshlrev_b32_e32 v27, 16, v4
	v_and_b32_e32 v4, 0xffff0000, v4
	v_sub_f32_e32 v4, v4, v12
	v_lshlrev_b32_e32 v28, 16, v5
	v_sub_f32_e32 v27, v27, v12
	v_mul_f32_e32 v4, v13, v4
	v_and_b32_e32 v5, 0xffff0000, v5
	v_sub_f32_e32 v28, v28, v12
	v_mul_f32_e32 v27, v13, v27
	v_lshlrev_b32_e32 v29, 16, v6
	v_sub_f32_e32 v5, v5, v12
	v_mul_f32_e32 v28, v13, v28
	ds_write_b16 v155, v26 offset:45424
	v_and_b32_e32 v6, 0xffff0000, v6
	v_sub_f32_e32 v29, v29, v12
	v_mul_f32_e32 v5, v13, v5
	v_sub_f32_e32 v6, v6, v12
	v_mul_f32_e32 v29, v13, v29
	v_mul_f32_e32 v6, v13, v6
	v_lshlrev_b32_e32 v56, 16, v0
	v_mul_f32_e32 v0, v51, v51
	v_pk_fma_f32 v[0:1], v[50:51], v[50:51], v[0:1] op_sel_hi:[1,1,0]
	v_mov_b32_e32 v63, v67
	v_mov_b32_e32 v67, v97
	s_waitcnt vmcnt(2)
	v_fma_f32 v4, v4, v9, v15
	v_fma_f32 v8, v27, v8, v14
	s_waitcnt vmcnt(0)
	v_fmac_f32_e32 v25, v7, v21
	v_cvt_pk_bf16_f32 v7, v8, v33
	ds_write_b16 v155, v7 offset:52224
	v_cvt_pk_bf16_f32 v4, v4, v33
	v_fma_f32 v9, v28, v10, v16
	ds_write_b16 v155, v4 offset:52496
	v_cvt_pk_bf16_f32 v4, v9, v33
	v_fmac_f32_e32 v17, v5, v11
	ds_write_b16 v155, v4 offset:52768
	v_cvt_pk_bf16_f32 v4, v17, v33
	v_fma_f32 v5, v29, v18, v22
	ds_write_b16 v155, v4 offset:53040
	v_cvt_pk_bf16_f32 v4, v5, v33
	v_fma_f32 v6, v6, v19, v23
	ds_write_b16 v155, v4 offset:53312
	v_cvt_pk_bf16_f32 v4, v6, v33
	v_fma_f32 v10, v30, v20, v24
	ds_write_b16 v155, v4 offset:53584
	v_cvt_pk_bf16_f32 v4, v10, v33
	ds_write_b16 v155, v4 offset:53856
	v_cvt_pk_bf16_f32 v54, v25, v33
	global_load_dwordx4 v[4:7], v157, s[48:49] offset:896
	global_load_dwordx4 v[8:11], v157, s[50:51] offset:896
	global_load_dwordx4 v[14:17], v157, s[48:49] offset:912
	global_load_dwordx4 v[18:21], v157, s[50:51] offset:912
	v_mov_b32_e32 v22, v0
	v_pk_add_f32 v[0:1], v[2:3], v[0:1]
	v_mul_f32_e32 v2, v61, v61
	v_mul_f32_e32 v24, v53, v53
	v_pk_fma_f32 v[2:3], v[60:61], v[60:61], v[2:3] op_sel_hi:[1,1,0]
	v_pk_fma_f32 v[24:25], v[52:53], v[52:53], v[24:25] op_sel_hi:[1,1,0]
	v_mov_b32_e32 v26, v2
	v_mov_b32_e32 v74, v24
	v_mov_b32_e32 v23, v85
	v_mov_b32_e32 v27, v75
	v_pk_add_f32 v[2:3], v[24:25], v[2:3]
	v_pk_fma_f32 v[24:25], v[68:69], v[70:71], v[86:87]
	v_pk_mul_f32 v[28:29], v[86:87], v[86:87]
	v_pk_fma_f32 v[30:31], v[62:63], v[72:73], v[88:89]
	v_pk_mul_f32 v[22:23], v[84:85], v[22:23]
	v_pk_mul_f32 v[26:27], v[74:75], v[26:27]
	v_mov_b32_e32 v25, v29
	v_mov_b32_e32 v31, v49
	v_mov_b32_e32 v1, v23
	v_mov_b32_e32 v3, v27
	v_pk_add_f32 v[22:23], v[24:25], v[30:31]
	v_pk_add_f32 v[0:1], v[0:1], v[2:3]
	v_sub_f32_e32 v2, v98, v12
	v_pk_add_f32 v[88:89], v[0:1], v[22:23]
	v_pk_mul_f32 v[0:1], v[92:93], v[92:93]
	ds_write_b16 v155, v54 offset:54128
	v_pk_fma_f32 v[0:1], v[90:91], v[90:91], v[0:1]
	v_sub_f32_e32 v3, v100, v12
	v_pk_add_f32 v[86:87], v[0:1], v[0:1] op_sel:[0,1] op_sel_hi:[1,0]
	v_mul_f32_e32 v0, v95, v95
	v_pk_fma_f32 v[84:85], v[94:95], v[94:95], v[0:1] op_sel_hi:[1,1,0]
	v_sub_f32_e32 v0, v56, v12
	v_mul_f32_e32 v0, v13, v0
	v_sub_f32_e32 v1, v96, v12
	v_mul_f32_e32 v1, v13, v1
	v_mul_f32_e32 v2, v13, v2
	v_sub_f32_e32 v22, v101, v12
	v_mul_f32_e32 v3, v13, v3
	v_sub_f32_e32 v23, v102, v12
	v_mul_f32_e32 v22, v13, v22
	v_sub_f32_e32 v24, v103, v12
	v_mul_f32_e32 v23, v13, v23
	v_sub_f32_e32 v12, v104, v12
	v_mul_f32_e32 v24, v13, v24
	v_mul_f32_e32 v12, v13, v12
	s_waitcnt vmcnt(2)
	v_fma_f32 v0, v0, v4, v8
	v_cvt_pk_bf16_f32 v0, v0, v33
	v_fma_f32 v1, v1, v5, v9
	ds_write_b16 v155, v0 offset:60928
	v_cvt_pk_bf16_f32 v0, v1, v33
	v_fma_f32 v2, v2, v6, v10
	ds_write_b16 v155, v0 offset:61200
	v_cvt_pk_bf16_f32 v0, v2, v33
	v_fmac_f32_e32 v11, v3, v7
	ds_write_b16 v155, v0 offset:61472
	v_cvt_pk_bf16_f32 v0, v11, v33
	s_waitcnt vmcnt(0)
	v_fma_f32 v3, v22, v14, v18
	ds_write_b16 v155, v0 offset:61744
	v_cvt_pk_bf16_f32 v0, v3, v33
	v_fma_f32 v4, v23, v15, v19
	ds_write_b16 v155, v0 offset:62016
	v_cvt_pk_bf16_f32 v0, v4, v33
	v_fma_f32 v5, v24, v16, v20
	ds_write_b16 v155, v0 offset:62288
	v_cvt_pk_bf16_f32 v0, v5, v33
	v_fmac_f32_e32 v21, v12, v17
	ds_write_b16 v155, v0 offset:62560
	v_cvt_pk_bf16_f32 v0, v21, v33
	ds_write_b16 v155, v0 offset:62832
	s_waitcnt lgkmcnt(0)
	s_barrier
	v_add_co_u32_e32 v0, vcc, s26, v42
	v_pk_fma_f32 v[66:67], v[66:67], v[76:77], v[80:81]
	s_nop 0
	v_addc_co_u32_e32 v1, vcc, 0, v43, vcc
	global_load_dwordx2 v[224:225], v[40:41], off offset:1312
	global_load_dwordx2 v[226:227], v[40:41], off offset:1344
	global_load_dwordx2 v[228:229], v[40:41], off offset:1376
	global_load_dwordx2 v[230:231], v[40:41], off offset:1408
	global_load_dwordx2 v[232:233], v[40:41], off offset:1440
	global_load_dwordx2 v[234:235], v[40:41], off offset:1472
	global_load_dwordx2 v[236:237], v[40:41], off offset:1504
	global_load_dwordx4 v[20:23], v[0:1], off
	global_load_dwordx4 v[24:27], v[0:1], off offset:64
	global_load_dwordx2 v[72:73], v[40:41], off offset:1280
	global_load_dwordx4 v[28:31], v[0:1], off offset:128
	global_load_dwordx4 v[16:19], v[0:1], off offset:192
	global_load_dword v48, v[44:45], off offset:512
	ds_read_b128 v[0:3], v152 offset:34816
	ds_read_b128 v[4:7], v152 offset:34880
	ds_read_b128 v[50:53], v152 offset:34944
	global_load_dwordx4 v[12:15], v[46:47], off offset:2560
	global_load_dwordx4 v[8:11], v[46:47], off offset:2624
	ds_read_b128 v[60:63], v152 offset:35008
	v_pk_mul_f32 v[76:77], v[80:81], v[80:81]
	v_pk_fma_f32 v[64:65], v[64:65], v[78:79], v[82:83]
	v_pk_mul_f32 v[78:79], v[82:83], v[82:83]
	v_mov_b32_e32 v67, v77
	v_mov_b32_e32 v65, v79
	s_waitcnt vmcnt(7) lgkmcnt(3)
	v_mfma_f32_16x16x32_bf16 v[0:3], v[0:3], v[20:23], 0
	s_waitcnt vmcnt(5)
	v_lshlrev_b32_e32 v75, 16, v73
	v_lshlrev_b32_e32 v74, 16, v72
	s_waitcnt lgkmcnt(2)
	v_mfma_f32_16x16x32_bf16 v[68:71], v[4:7], v[24:27], v[0:3]
	global_load_dwordx4 v[4:7], v[46:47], off offset:2688
	s_nop 1
	global_load_dwordx4 v[0:3], v[46:47], off offset:2752
	s_waitcnt vmcnt(0)
	v_and_b32_e32 v76, 0xffff0000, v1
	s_waitcnt lgkmcnt(1)
	v_mfma_f32_16x16x32_bf16 v[50:53], v[50:53], v[28:31], v[68:71]
	v_lshlrev_b32_e32 v77, 16, v2
	v_and_b32_e32 v78, 0xffff0000, v2
	v_lshlrev_b32_e32 v79, 16, v3
	s_waitcnt lgkmcnt(0)
	v_mfma_f32_16x16x32_bf16 v[50:53], v[60:63], v[16:19], v[50:53]
	v_and_b32_e32 v69, 0xffff0000, v73
	v_and_b32_e32 v68, 0xffff0000, v72
	v_and_b32_e32 v80, 0xffff0000, v3
	s_nop 4
	v_mov_b32_e32 v60, v50
	v_mov_b32_e32 v61, v52
	v_mov_b32_e32 v52, v51
	v_pk_add_f32 v[50:51], v[48:49], v[60:61] op_sel_hi:[0,1]
	v_pk_add_f32 v[52:53], v[48:49], v[52:53] op_sel_hi:[0,1]
	v_pk_mul_f32 v[90:91], v[50:51], v[74:75]
	v_pk_mul_f32 v[92:93], v[52:53], v[68:69]
	s_nop 0
	v_cvt_pk_bf16_f32 v156, v90, v92
	v_cvt_pk_bf16_f32 v154, v91, v93
	ds_read_b128 v[50:53], v152 offset:39168
	ds_read_b128 v[60:63], v152 offset:39232
	s_waitcnt lgkmcnt(1)
	v_mfma_f32_16x16x32_bf16 v[50:53], v[50:53], v[20:23], 0
	s_waitcnt lgkmcnt(0)
	v_mfma_f32_16x16x32_bf16 v[50:53], v[60:63], v[24:27], v[50:53]
	ds_read_b128 v[60:63], v152 offset:39296
	ds_read_b128 v[68:71], v152 offset:39360
	s_waitcnt lgkmcnt(1)
	v_mfma_f32_16x16x32_bf16 v[50:53], v[60:63], v[28:31], v[50:53]
	v_mov_b64_e32 v[60:61], v[224:225]
	s_waitcnt vmcnt(0)
	v_lshlrev_b32_e32 v62, 16, v60
	s_waitcnt lgkmcnt(0)
	v_mfma_f32_16x16x32_bf16 v[50:53], v[68:71], v[16:19], v[50:53]
	v_and_b32_e32 v63, 0xffff0000, v60
	v_lshlrev_b32_e32 v60, 16, v61
	v_and_b32_e32 v61, 0xffff0000, v61
	s_nop 4
	v_pk_add_f32 v[50:51], v[48:49], v[50:51] op_sel_hi:[0,1]
	v_pk_add_f32 v[52:53], v[48:49], v[52:53] op_sel_hi:[0,1]
	v_pk_mul_f32 v[94:95], v[50:51], v[62:63]
	v_pk_mul_f32 v[96:97], v[52:53], v[60:61]
	v_cvt_pk_bf16_f32 v153, v94, v95
	s_nop 0
	v_cvt_pk_bf16_f32 v151, v96, v97
	ds_read_b128 v[50:53], v152 offset:43520
	ds_read_b128 v[60:63], v152 offset:43584
	s_waitcnt lgkmcnt(1)
	v_mfma_f32_16x16x32_bf16 v[50:53], v[50:53], v[20:23], 0
	s_waitcnt lgkmcnt(0)
	v_mfma_f32_16x16x32_bf16 v[50:53], v[60:63], v[24:27], v[50:53]
	ds_read_b128 v[60:63], v152 offset:43648
	ds_read_b128 v[68:71], v152 offset:43712
	s_waitcnt lgkmcnt(1)
	v_mfma_f32_16x16x32_bf16 v[50:53], v[60:63], v[28:31], v[50:53]
	v_mov_b64_e32 v[60:61], v[226:227]
	s_waitcnt vmcnt(0)
	v_and_b32_e32 v54, 0xffff0000, v60
	s_waitcnt lgkmcnt(0)
	v_mfma_f32_16x16x32_bf16 v[50:53], v[68:71], v[16:19], v[50:53]
	v_lshlrev_b32_e32 v56, 16, v61
	v_and_b32_e32 v61, 0xffff0000, v61
	s_nop 5
	v_add_f32_e32 v49, v48, v50
	v_add_f32_e32 v50, v48, v51
	v_add_f32_e32 v51, v48, v52
	v_add_f32_e32 v52, v48, v53
	v_lshlrev_b32_e32 v53, 16, v60
	v_mul_f32_e32 v60, v49, v53
	v_mul_f32_e32 v100, v50, v54
	v_mul_f32_e32 v62, v51, v56
	v_mul_f32_e32 v98, v52, v61
	v_cvt_pk_bf16_f32 v149, v60, v100
	v_cvt_pk_bf16_f32 v147, v62, v98
	ds_read_b128 v[50:53], v152 offset:47872
	ds_read_b128 v[68:71], v152 offset:47936
	s_waitcnt lgkmcnt(1)
	v_mfma_f32_16x16x32_bf16 v[50:53], v[50:53], v[20:23], 0
	v_mov_b32_e32 v102, v60
	v_mov_b32_e32 v104, v62
	s_waitcnt lgkmcnt(0)
	v_mfma_f32_16x16x32_bf16 v[50:53], v[68:71], v[24:27], v[50:53]
	ds_read_b128 v[68:71], v152 offset:48000
	ds_read_b128 v[72:75], v152 offset:48064
	s_waitcnt lgkmcnt(1)
	v_mfma_f32_16x16x32_bf16 v[50:53], v[68:71], v[28:31], v[50:53]
	v_mov_b64_e32 v[68:69], v[228:229]
	s_waitcnt vmcnt(0)
	v_lshlrev_b32_e32 v103, 16, v69
	s_waitcnt lgkmcnt(0)
	v_mfma_f32_16x16x32_bf16 v[50:53], v[72:75], v[16:19], v[50:53]
	v_and_b32_e32 v105, 0xffff0000, v69
	s_nop 6
	v_add_f32_e32 v49, v48, v50
	v_add_f32_e32 v50, v48, v51
	v_add_f32_e32 v61, v48, v52
	v_add_f32_e32 v63, v48, v53
	v_lshlrev_b32_e32 v51, 16, v68
	v_and_b32_e32 v52, 0xffff0000, v68
	v_mul_f32_e32 v109, v49, v51
	v_mul_f32_e32 v107, v50, v52
	v_pk_mul_f32 v[110:111], v[60:61], v[102:103]
	v_pk_mul_f32 v[112:113], v[62:63], v[104:105]
	v_cvt_pk_bf16_f32 v146, v109, v107
	v_mov_b32_e32 v101, v61
	v_cvt_pk_bf16_f32 v143, v111, v113
	ds_read_b128 v[50:53], v152 offset:52224
	ds_read_b128 v[68:71], v152 offset:52288
	s_waitcnt lgkmcnt(1)
	v_mfma_f32_16x16x32_bf16 v[50:53], v[50:53], v[20:23], 0
	v_mov_b32_e32 v99, v63
	v_mov_b32_e32 v102, v100
	v_mov_b32_e32 v104, v98
	s_waitcnt lgkmcnt(0)
	v_mfma_f32_16x16x32_bf16 v[50:53], v[68:71], v[24:27], v[50:53]
	ds_read_b128 v[68:71], v152 offset:52352
	ds_read_b128 v[72:75], v152 offset:52416
	v_mov_b32_e32 v3, v109
	s_waitcnt lgkmcnt(1)
	v_mfma_f32_16x16x32_bf16 v[50:53], v[68:71], v[28:31], v[50:53]
	v_mov_b64_e32 v[68:69], v[230:231]
	s_waitcnt lgkmcnt(0)
	v_mfma_f32_16x16x32_bf16 v[50:53], v[72:75], v[16:19], v[50:53]
	s_nop 7
	v_mov_b32_e32 v70, v50
	v_mov_b32_e32 v71, v52
	v_mov_b32_e32 v52, v51
	v_pk_add_f32 v[50:51], v[48:49], v[70:71] op_sel_hi:[0,1]
	v_pk_add_f32 v[52:53], v[48:49], v[52:53] op_sel_hi:[0,1]
	s_waitcnt vmcnt(0)
	v_lshlrev_b32_e32 v71, 16, v69
	v_lshlrev_b32_e32 v70, 16, v68
	v_and_b32_e32 v69, 0xffff0000, v69
	v_and_b32_e32 v68, 0xffff0000, v68
	v_pk_mul_f32 v[114:115], v[50:51], v[70:71]
	v_pk_mul_f32 v[116:117], v[52:53], v[68:69]
	s_nop 0
	v_cvt_pk_bf16_f32 v144, v114, v116
	v_cvt_pk_bf16_f32 v141, v115, v117
	ds_read_b128 v[50:53], v152 offset:56576
	ds_read_b128 v[68:71], v152 offset:56640
	s_waitcnt lgkmcnt(1)
	v_mfma_f32_16x16x32_bf16 v[50:53], v[50:53], v[20:23], 0
	s_waitcnt lgkmcnt(0)
	v_mfma_f32_16x16x32_bf16 v[50:53], v[68:71], v[24:27], v[50:53]
	ds_read_b128 v[68:71], v152 offset:56704
	ds_read_b128 v[72:75], v152 offset:56768
	s_waitcnt lgkmcnt(1)
	v_mfma_f32_16x16x32_bf16 v[50:53], v[68:71], v[28:31], v[50:53]
	v_mov_b64_e32 v[68:69], v[232:233]
	s_waitcnt lgkmcnt(0)
	v_mfma_f32_16x16x32_bf16 v[50:53], v[72:75], v[16:19], v[50:53]
	s_nop 7
	v_pk_add_f32 v[50:51], v[48:49], v[50:51] op_sel_hi:[0,1]
	v_pk_add_f32 v[70:71], v[48:49], v[52:53] op_sel_hi:[0,1]
	s_waitcnt vmcnt(0)
	v_lshlrev_b32_e32 v52, 16, v68
	v_and_b32_e32 v53, 0xffff0000, v68
	v_lshlrev_b32_e32 v68, 16, v69
	v_and_b32_e32 v69, 0xffff0000, v69
	v_pk_mul_f32 v[52:53], v[50:51], v[52:53]
	v_pk_mul_f32 v[118:119], v[70:71], v[68:69]
	v_cvt_pk_bf16_f32 v140, v52, v53
	s_nop 0
	v_cvt_pk_bf16_f32 v138, v118, v119
	ds_read_b128 v[68:71], v152 offset:60928
	ds_read_b128 v[72:75], v152 offset:60992
	s_waitcnt lgkmcnt(1)
	v_mfma_f32_16x16x32_bf16 v[68:71], v[68:71], v[20:23], 0
	s_waitcnt lgkmcnt(0)
	v_mfma_f32_16x16x32_bf16 v[68:71], v[72:75], v[24:27], v[68:71]
	ds_read_b128 v[72:75], v152 offset:61056
	ds_read_b128 v[120:123], v152 offset:61120
	v_mov_b64_e32 v[50:51], v[234:235]
	s_waitcnt vmcnt(0)
	v_lshlrev_b32_e32 v62, 16, v50
	s_waitcnt lgkmcnt(1)
	v_mfma_f32_16x16x32_bf16 v[68:71], v[72:75], v[28:31], v[68:71]
	v_and_b32_e32 v50, 0xffff0000, v50
	s_waitcnt lgkmcnt(0)
	v_mfma_f32_16x16x32_bf16 v[68:71], v[120:123], v[16:19], v[68:71]
	s_nop 7
	v_add_f32_e32 v49, v48, v68
	v_add_f32_e32 v54, v48, v69
	v_add_f32_e32 v56, v48, v70
	v_add_f32_e32 v60, v48, v71
	v_lshlrev_b32_e32 v68, 16, v51
	v_and_b32_e32 v51, 0xffff0000, v51
	v_mul_f32_e32 v120, v49, v62
	v_mul_f32_e32 v62, v54, v50
	v_mul_f32_e32 v122, v56, v68
	v_mul_f32_e32 v60, v60, v51
	v_cvt_pk_bf16_f32 v135, v120, v62
	v_cvt_pk_bf16_f32 v131, v122, v60
	ds_read_b128 v[68:71], v152 offset:65280
	ds_read_b128 v[72:75], v152 offset:65344
	s_waitcnt lgkmcnt(1)
	v_mfma_f32_16x16x32_bf16 v[20:23], v[68:71], v[20:23], 0
	v_mov_b32_e32 v68, v120
	v_mov_b32_e32 v70, v122
	v_and_b32_e32 v50, 0xffff0000, v12
	s_waitcnt lgkmcnt(0)
	v_mfma_f32_16x16x32_bf16 v[20:23], v[72:75], v[24:27], v[20:23]
	ds_read_b128 v[24:27], v152 offset:65408
	ds_read_b128 v[72:75], v152 offset:65472
	v_lshlrev_b32_e32 v54, 16, v13
	v_and_b32_e32 v56, 0xffff0000, v13
	s_waitcnt lgkmcnt(1)
	v_mfma_f32_16x16x32_bf16 v[20:23], v[24:27], v[28:31], v[20:23]
	v_mov_b64_e32 v[24:25], v[236:237]
	s_waitcnt vmcnt(0)
	v_lshlrev_b32_e32 v69, 16, v25
	s_waitcnt lgkmcnt(0)
	v_mfma_f32_16x16x32_bf16 v[16:19], v[72:75], v[16:19], v[20:23]
	v_and_b32_e32 v71, 0xffff0000, v25
	s_nop 6
	v_add_f32_e32 v16, v48, v16
	v_add_f32_e32 v17, v48, v17
	v_add_f32_e32 v121, v48, v18
	v_add_f32_e32 v123, v48, v19
	v_lshlrev_b32_e32 v18, 16, v24
	v_and_b32_e32 v19, 0xffff0000, v24
	v_mul_f32_e32 v51, v16, v18
	v_mul_f32_e32 v49, v17, v19
	v_pk_mul_f32 v[72:73], v[120:121], v[68:69]
	v_pk_mul_f32 v[74:75], v[122:123], v[70:71]
	v_cvt_pk_bf16_f32 v122, v51, v49
	v_lshlrev_b32_e32 v48, 16, v12
	v_cvt_pk_bf16_f32 v120, v73, v75
	global_load_dwordx4 v[16:19], v157, s[48:49] offset:1024
	global_load_dwordx4 v[20:23], v157, s[50:51] offset:1024
	global_load_dwordx4 v[24:27], v157, s[48:49] offset:1040
	global_load_dwordx4 v[28:31], v157, s[50:51] offset:1040
	ds_read_b64 v[12:13], v160
	v_lshlrev_b32_e32 v70, 16, v15
	v_and_b32_e32 v15, 0xffff0000, v15
	v_lshlrev_b32_e32 v68, 16, v14
	v_and_b32_e32 v14, 0xffff0000, v14
	s_waitcnt lgkmcnt(0)
	v_sub_f32_e32 v48, v48, v12
	v_sub_f32_e32 v15, v15, v12
	v_sub_f32_e32 v50, v50, v12
	v_mul_f32_e32 v48, v13, v48
	v_mul_f32_e32 v15, v13, v15
	v_sub_f32_e32 v54, v54, v12
	v_mul_f32_e32 v50, v13, v50
	v_sub_f32_e32 v56, v56, v12
	v_sub_f32_e32 v14, v14, v12
	v_mul_f32_e32 v54, v13, v54
	v_sub_f32_e32 v68, v68, v12
	v_mul_f32_e32 v56, v13, v56
	v_mul_f32_e32 v14, v13, v14
	v_sub_f32_e32 v70, v70, v12
	v_mul_f32_e32 v68, v13, v68
	v_mul_f32_e32 v70, v13, v70
	v_mov_b32_e32 v63, v121
	v_mov_b32_e32 v61, v123
	s_waitcnt vmcnt(2)
	v_fma_f32 v16, v16, v48, v20
	v_fma_f32 v17, v17, v50, v21
	s_waitcnt vmcnt(0)
	v_fmac_f32_e32 v31, v27, v15
	v_cvt_pk_bf16_f32 v15, v16, v33
	ds_write_b16 v155, v15
	v_cvt_pk_bf16_f32 v15, v17, v33
	v_fma_f32 v18, v18, v54, v22
	ds_write_b16 v155, v15 offset:272
	v_cvt_pk_bf16_f32 v15, v18, v33
	v_fmac_f32_e32 v23, v19, v56
	v_fma_f32 v14, v25, v14, v29
	ds_write_b16 v155, v15 offset:544
	v_cvt_pk_bf16_f32 v15, v23, v33
	v_fma_f32 v19, v24, v68, v28
	ds_write_b16 v155, v15 offset:816
	v_cvt_pk_bf16_f32 v15, v19, v33
	ds_write_b16 v155, v15 offset:1088
	v_cvt_pk_bf16_f32 v14, v14, v33
	v_fma_f32 v20, v26, v70, v30
	ds_write_b16 v155, v14 offset:1360
	v_cvt_pk_bf16_f32 v14, v20, v33
	ds_write_b16 v155, v14 offset:1632
	v_cvt_pk_bf16_f32 v30, v31, v33
	global_load_dwordx4 v[14:17], v157, s[48:49] offset:1152
	global_load_dwordx4 v[18:21], v157, s[50:51] offset:1152
	global_load_dwordx4 v[22:25], v157, s[48:49] offset:1168
	global_load_dwordx4 v[26:29], v157, s[50:51] offset:1168
	v_lshlrev_b32_e32 v31, 16, v8
	v_and_b32_e32 v8, 0xffff0000, v8
	v_lshlrev_b32_e32 v54, 16, v11
	v_and_b32_e32 v11, 0xffff0000, v11
	v_sub_f32_e32 v8, v8, v12
	v_lshlrev_b32_e32 v48, 16, v9
	v_sub_f32_e32 v31, v31, v12
	v_sub_f32_e32 v11, v11, v12
	v_mul_f32_e32 v8, v13, v8
	v_and_b32_e32 v9, 0xffff0000, v9
	v_sub_f32_e32 v48, v48, v12
	v_mul_f32_e32 v31, v13, v31
	v_mul_f32_e32 v11, v13, v11
	v_lshlrev_b32_e32 v50, 16, v10
	v_sub_f32_e32 v9, v9, v12
	v_mul_f32_e32 v48, v13, v48
	ds_write_b16 v155, v30 offset:1904
	v_and_b32_e32 v10, 0xffff0000, v10
	v_sub_f32_e32 v50, v50, v12
	v_mul_f32_e32 v9, v13, v9
	v_sub_f32_e32 v10, v10, v12
	v_mul_f32_e32 v50, v13, v50
	v_sub_f32_e32 v54, v54, v12
	v_mul_f32_e32 v10, v13, v10
	v_mul_f32_e32 v54, v13, v54
	v_mul_f32_e32 v30, v59, v59
	v_mov_b32_e32 v68, v62
	v_mov_b32_e32 v70, v60
	s_waitcnt vmcnt(2)
	v_fma_f32 v8, v8, v15, v19
	v_fma_f32 v14, v31, v14, v18
	s_waitcnt vmcnt(0)
	v_fmac_f32_e32 v29, v11, v25
	v_cvt_pk_bf16_f32 v11, v14, v33
	ds_write_b16 v155, v11 offset:8704
	v_cvt_pk_bf16_f32 v8, v8, v33
	v_fma_f32 v15, v48, v16, v20
	ds_write_b16 v155, v8 offset:8976
	v_cvt_pk_bf16_f32 v8, v15, v33
	v_fmac_f32_e32 v21, v9, v17
	ds_write_b16 v155, v8 offset:9248
	v_cvt_pk_bf16_f32 v8, v21, v33
	v_fma_f32 v9, v50, v22, v26
	ds_write_b16 v155, v8 offset:9520
	v_cvt_pk_bf16_f32 v8, v9, v33
	v_fma_f32 v10, v10, v23, v27
	ds_write_b16 v155, v8 offset:9792
	v_cvt_pk_bf16_f32 v8, v10, v33
	v_fma_f32 v16, v54, v24, v28
	ds_write_b16 v155, v8 offset:10064
	v_cvt_pk_bf16_f32 v8, v16, v33
	ds_write_b16 v155, v8 offset:10336
	v_cvt_pk_bf16_f32 v48, v29, v33
	global_load_dwordx4 v[8:11], v157, s[48:49] offset:1280
	global_load_dwordx4 v[14:17], v157, s[50:51] offset:1280
	global_load_dwordx4 v[18:21], v157, s[48:49] offset:1296
	global_load_dwordx4 v[22:25], v157, s[50:51] offset:1296
	v_pk_add_f32 v[26:27], v[88:89], v[88:89] op_sel:[0,1] op_sel_hi:[1,0]
	v_pk_fma_f32 v[30:31], v[58:59], v[58:59], v[30:31] op_sel_hi:[1,1,0]
	v_mov_b32_e32 v56, v26
	v_pk_add_f32 v[26:27], v[26:27], v[86:87]
	v_lshlrev_b32_e32 v58, 16, v7
	v_lshlrev_b32_e32 v27, 16, v4
	v_and_b32_e32 v4, 0xffff0000, v4
	v_and_b32_e32 v7, 0xffff0000, v7
	v_sub_f32_e32 v4, v4, v12
	v_lshlrev_b32_e32 v50, 16, v5
	v_sub_f32_e32 v27, v27, v12
	v_sub_f32_e32 v7, v7, v12
	v_mul_f32_e32 v4, v13, v4
	v_and_b32_e32 v5, 0xffff0000, v5
	v_sub_f32_e32 v50, v50, v12
	v_mul_f32_e32 v27, v13, v27
	v_mul_f32_e32 v7, v13, v7
	v_lshlrev_b32_e32 v54, 16, v6
	v_sub_f32_e32 v5, v5, v12
	v_mul_f32_e32 v50, v13, v50
	ds_write_b16 v155, v48 offset:10608
	v_and_b32_e32 v6, 0xffff0000, v6
	v_sub_f32_e32 v54, v54, v12
	v_mul_f32_e32 v5, v13, v5
	v_sub_f32_e32 v6, v6, v12
	v_mul_f32_e32 v54, v13, v54
	v_sub_f32_e32 v58, v58, v12
	v_mul_f32_e32 v6, v13, v6
	v_mul_f32_e32 v58, v13, v58
	v_mov_b32_e32 v28, v86
	v_mov_b32_e32 v29, v57
	v_mov_b32_e32 v88, v84
	v_mov_b32_e32 v89, v55
	s_waitcnt vmcnt(2)
	v_fma_f32 v4, v4, v9, v15
	v_fma_f32 v8, v27, v8, v14
	s_waitcnt vmcnt(0)
	v_fmac_f32_e32 v25, v7, v21
	v_cvt_pk_bf16_f32 v7, v8, v33
	ds_write_b16 v155, v7 offset:17408
	v_cvt_pk_bf16_f32 v4, v4, v33
	v_fma_f32 v9, v50, v10, v16
	ds_write_b16 v155, v4 offset:17680
	v_cvt_pk_bf16_f32 v4, v9, v33
	v_fmac_f32_e32 v17, v5, v11
	ds_write_b16 v155, v4 offset:17952
	v_cvt_pk_bf16_f32 v4, v17, v33
	v_fma_f32 v5, v54, v18, v22
	ds_write_b16 v155, v4 offset:18224
	v_cvt_pk_bf16_f32 v4, v5, v33
	v_fma_f32 v6, v6, v19, v23
	ds_write_b16 v155, v4 offset:18496
	v_cvt_pk_bf16_f32 v4, v6, v33
	v_fma_f32 v10, v58, v20, v24
	ds_write_b16 v155, v4 offset:18768
	v_cvt_pk_bf16_f32 v4, v10, v33
	ds_write_b16 v155, v4 offset:19040
	v_cvt_pk_bf16_f32 v48, v25, v33
	global_load_dwordx4 v[4:7], v157, s[48:49] offset:1408
	global_load_dwordx4 v[8:11], v157, s[50:51] offset:1408
	global_load_dwordx4 v[14:17], v157, s[48:49] offset:1424
	global_load_dwordx4 v[18:21], v157, s[50:51] offset:1424
	v_pk_mul_f32 v[22:23], v[56:57], v[28:29]
	v_mov_b32_e32 v54, v30
	v_pk_add_f32 v[24:25], v[30:31], v[84:85]
	v_mov_b32_e32 v27, v23
	v_pk_mul_f32 v[22:23], v[54:55], v[88:89]
	v_pk_add_f32 v[28:29], v[66:67], v[64:65]
	v_mov_b32_e32 v25, v23
	v_pk_add_f32 v[22:23], v[26:27], v[24:25]
	v_lshlrev_b32_e32 v50, 16, v0
	v_and_b32_e32 v56, 0xffff0000, v0
	v_lshlrev_b32_e32 v57, 16, v1
	v_pk_mul_f32 v[0:1], v[92:93], v[92:93]
	v_pk_add_f32 v[22:23], v[22:23], v[28:29]
	v_pk_fma_f32 v[0:1], v[90:91], v[90:91], v[0:1]
	v_pk_add_f32 v[22:23], v[22:23], v[22:23] op_sel:[0,1] op_sel_hi:[1,0]
	v_pk_add_f32 v[0:1], v[0:1], v[0:1] op_sel:[0,1] op_sel_hi:[1,0]
	v_mov_b32_e32 v108, v22
	v_mov_b32_e32 v2, v0
	v_pk_add_f32 v[0:1], v[22:23], v[0:1]
	v_mul_f32_e32 v22, v97, v97
	v_mul_f32_e32 v24, v95, v95
	v_pk_fma_f32 v[22:23], v[96:97], v[96:97], v[22:23] op_sel_hi:[1,1,0]
	v_pk_fma_f32 v[24:25], v[94:95], v[94:95], v[24:25] op_sel_hi:[1,1,0]
	v_mov_b32_e32 v26, v22
	v_mov_b32_e32 v106, v24
	v_mov_b32_e32 v27, v107
	v_pk_add_f32 v[22:23], v[24:25], v[22:23]
	v_pk_fma_f32 v[24:25], v[100:101], v[102:103], v[110:111]
	v_pk_mul_f32 v[28:29], v[110:111], v[110:111]
	v_pk_fma_f32 v[30:31], v[98:99], v[104:105], v[112:113]
	v_pk_mul_f32 v[54:55], v[112:113], v[112:113]
	v_pk_mul_f32 v[2:3], v[108:109], v[2:3]
	v_pk_mul_f32 v[26:27], v[106:107], v[26:27]
	v_mov_b32_e32 v25, v29
	v_mov_b32_e32 v31, v55
	v_mov_b32_e32 v1, v3
	v_mov_b32_e32 v23, v27
	v_pk_add_f32 v[2:3], v[24:25], v[30:31]
	v_pk_add_f32 v[0:1], v[0:1], v[22:23]
	ds_write_b16 v155, v48 offset:19312
	v_pk_add_f32 v[66:67], v[0:1], v[2:3]
	v_pk_mul_f32 v[0:1], v[116:117], v[116:117]
	v_sub_f32_e32 v2, v57, v12
	v_pk_fma_f32 v[0:1], v[114:115], v[114:115], v[0:1]
	v_sub_f32_e32 v3, v76, v12
	v_pk_add_f32 v[64:65], v[0:1], v[0:1] op_sel:[0,1] op_sel_hi:[1,0]
	v_mul_f32_e32 v0, v119, v119
	v_pk_fma_f32 v[58:59], v[118:119], v[118:119], v[0:1] op_sel_hi:[1,1,0]
	v_sub_f32_e32 v0, v50, v12
	v_mul_f32_e32 v0, v13, v0
	v_sub_f32_e32 v1, v56, v12
	v_mul_f32_e32 v1, v13, v1
	v_mul_f32_e32 v2, v13, v2
	v_sub_f32_e32 v22, v77, v12
	v_mul_f32_e32 v3, v13, v3
	v_sub_f32_e32 v23, v78, v12
	v_mul_f32_e32 v22, v13, v22
	v_sub_f32_e32 v24, v79, v12
	v_mul_f32_e32 v23, v13, v23
	v_sub_f32_e32 v12, v80, v12
	v_mul_f32_e32 v24, v13, v24
	v_mul_f32_e32 v12, v13, v12
	s_waitcnt vmcnt(2)
	v_fma_f32 v0, v0, v4, v8
	v_cvt_pk_bf16_f32 v0, v0, v33
	v_fma_f32 v1, v1, v5, v9
	ds_write_b16 v155, v0 offset:26112
	v_cvt_pk_bf16_f32 v0, v1, v33
	v_fma_f32 v2, v2, v6, v10
	ds_write_b16 v155, v0 offset:26384
	v_cvt_pk_bf16_f32 v0, v2, v33
	v_fmac_f32_e32 v11, v3, v7
	ds_write_b16 v155, v0 offset:26656
	v_cvt_pk_bf16_f32 v0, v11, v33
	s_waitcnt vmcnt(0)
	v_fma_f32 v3, v22, v14, v18
	ds_write_b16 v155, v0 offset:26928
	v_cvt_pk_bf16_f32 v0, v3, v33
	v_fma_f32 v4, v23, v15, v19
	ds_write_b16 v155, v0 offset:27200
	v_cvt_pk_bf16_f32 v0, v4, v33
	v_fma_f32 v5, v24, v16, v20
	ds_write_b16 v155, v0 offset:27472
	v_cvt_pk_bf16_f32 v0, v5, v33
	v_fmac_f32_e32 v21, v12, v17
	ds_write_b16 v155, v0 offset:27744
	v_cvt_pk_bf16_f32 v0, v21, v33
	ds_write_b16 v155, v0 offset:28016
	s_waitcnt lgkmcnt(0)
	s_barrier
	v_add_co_u32_e32 v0, vcc, s27, v42
	v_pk_fma_f32 v[68:69], v[62:63], v[68:69], v[72:73]
	s_nop 0
	v_addc_co_u32_e32 v1, vcc, 0, v43, vcc
	global_load_dwordx2 v[224:225], v[40:41], off offset:1568
	global_load_dwordx2 v[226:227], v[40:41], off offset:1600
	global_load_dwordx2 v[228:229], v[40:41], off offset:1632
	global_load_dwordx2 v[230:231], v[40:41], off offset:1664
	global_load_dwordx2 v[232:233], v[40:41], off offset:1696
	global_load_dwordx2 v[234:235], v[40:41], off offset:1728
	global_load_dwordx2 v[236:237], v[40:41], off offset:1760
	global_load_dwordx4 v[20:23], v[0:1], off
	global_load_dwordx4 v[24:27], v[0:1], off offset:64
	global_load_dwordx2 v[84:85], v[40:41], off offset:1536
	global_load_dwordx4 v[28:31], v[0:1], off offset:128
	global_load_dwordx4 v[16:19], v[0:1], off offset:192
	global_load_dword v48, v[44:45], off offset:1024
	ds_read_b128 v[0:3], v152
	ds_read_b128 v[4:7], v152 offset:64
	ds_read_b128 v[54:57], v152 offset:128
	global_load_dwordx4 v[12:15], v[46:47], off offset:2816
	global_load_dwordx4 v[8:11], v[46:47], off offset:2880
	ds_read_b128 v[76:79], v152 offset:192
	v_pk_mul_f32 v[62:63], v[72:73], v[72:73]
	v_pk_fma_f32 v[70:71], v[60:61], v[70:71], v[74:75]
	v_pk_mul_f32 v[60:61], v[74:75], v[74:75]
	v_mov_b32_e32 v69, v63
	v_mov_b32_e32 v71, v61
	s_waitcnt vmcnt(7) lgkmcnt(3)
	v_mfma_f32_16x16x32_bf16 v[0:3], v[0:3], v[20:23], 0
	s_waitcnt vmcnt(6) lgkmcnt(2)
	v_mfma_f32_16x16x32_bf16 v[80:83], v[4:7], v[24:27], v[0:3]
	global_load_dwordx4 v[4:7], v[46:47], off offset:2944
	s_nop 4
	global_load_dwordx4 v[0:3], v[46:47], off offset:3008
	s_waitcnt vmcnt(7)
	v_lshlrev_b32_e32 v47, 16, v85
	v_lshlrev_b32_e32 v46, 16, v84
	s_waitcnt vmcnt(6) lgkmcnt(1)
	v_mfma_f32_16x16x32_bf16 v[54:57], v[54:57], v[28:31], v[80:83]
	s_waitcnt vmcnt(0)
	v_and_b32_e32 v72, 0xffff0000, v2
	s_waitcnt lgkmcnt(0)
	v_mfma_f32_16x16x32_bf16 v[54:57], v[76:79], v[16:19], v[54:57]
	v_and_b32_e32 v81, 0xffff0000, v85
	v_and_b32_e32 v80, 0xffff0000, v84
	v_lshlrev_b32_e32 v73, 16, v3
	v_and_b32_e32 v74, 0xffff0000, v3
	s_nop 3
	v_mov_b32_e32 v76, v54
	v_mov_b32_e32 v77, v56
	v_mov_b32_e32 v56, v55
	v_pk_add_f32 v[54:55], v[48:49], v[76:77] op_sel_hi:[0,1]
	v_pk_add_f32 v[56:57], v[48:49], v[56:57] op_sel_hi:[0,1]
	v_pk_mul_f32 v[76:77], v[54:55], v[46:47]
	v_pk_mul_f32 v[78:79], v[56:57], v[80:81]
	s_nop 0
	v_cvt_pk_bf16_f32 v159, v76, v78
	v_cvt_pk_bf16_f32 v158, v77, v79
	ds_read_b128 v[54:57], v152 offset:4352
	ds_read_b128 v[80:83], v152 offset:4416
	s_waitcnt lgkmcnt(1)
	v_mfma_f32_16x16x32_bf16 v[54:57], v[54:57], v[20:23], 0
	s_waitcnt lgkmcnt(0)
	v_mfma_f32_16x16x32_bf16 v[54:57], v[80:83], v[24:27], v[54:57]
	ds_read_b128 v[80:83], v152 offset:4480
	ds_read_b128 v[84:87], v152 offset:4544
	v_mov_b64_e32 v[46:47], v[224:225]
	s_waitcnt lgkmcnt(1)
	v_mfma_f32_16x16x32_bf16 v[54:57], v[80:83], v[28:31], v[54:57]
	s_waitcnt vmcnt(0)
	v_lshlrev_b32_e32 v80, 16, v46
	s_waitcnt lgkmcnt(0)
	v_mfma_f32_16x16x32_bf16 v[54:57], v[84:87], v[16:19], v[54:57]
	v_and_b32_e32 v81, 0xffff0000, v46
	v_lshlrev_b32_e32 v46, 16, v47
	v_and_b32_e32 v47, 0xffff0000, v47
	s_nop 4
	v_pk_add_f32 v[54:55], v[48:49], v[54:55] op_sel_hi:[0,1]
	v_pk_add_f32 v[56:57], v[48:49], v[56:57] op_sel_hi:[0,1]
	v_pk_mul_f32 v[80:81], v[54:55], v[80:81]
	v_pk_mul_f32 v[82:83], v[56:57], v[46:47]
	v_cvt_pk_bf16_f32 v123, v80, v81
	s_nop 0
	v_cvt_pk_bf16_f32 v121, v82, v83
	ds_read_b128 v[54:57], v152 offset:8704
	ds_read_b128 v[84:87], v152 offset:8768
	s_waitcnt lgkmcnt(1)
	v_mfma_f32_16x16x32_bf16 v[54:57], v[54:57], v[20:23], 0
	s_waitcnt lgkmcnt(0)
	v_mfma_f32_16x16x32_bf16 v[54:57], v[84:87], v[24:27], v[54:57]
	ds_read_b128 v[84:87], v152 offset:8832
	ds_read_b128 v[88:91], v152 offset:8896
	v_mov_b64_e32 v[46:47], v[226:227]
	s_waitcnt lgkmcnt(1)
	v_mfma_f32_16x16x32_bf16 v[54:57], v[84:87], v[28:31], v[54:57]
	s_waitcnt vmcnt(0)
	v_lshlrev_b32_e32 v84, 16, v47
	s_waitcnt lgkmcnt(0)
	v_mfma_f32_16x16x32_bf16 v[54:57], v[88:91], v[16:19], v[54:57]
	v_and_b32_e32 v47, 0xffff0000, v47
	s_nop 6
	v_add_f32_e32 v50, v48, v54
	v_add_f32_e32 v55, v48, v55
	v_add_f32_e32 v56, v48, v56
	v_add_f32_e32 v57, v48, v57
	v_lshlrev_b32_e32 v54, 16, v46
	v_and_b32_e32 v46, 0xffff0000, v46
	v_mul_f32_e32 v54, v50, v54
	v_mul_f32_e32 v86, v55, v46
	v_mul_f32_e32 v56, v56, v84
	v_mul_f32_e32 v84, v57, v47
	v_cvt_pk_bf16_f32 v119, v54, v86
	v_cvt_pk_bf16_f32 v118, v56, v84
	ds_read_b128 v[88:91], v152 offset:13056
	ds_read_b128 v[92:95], v152 offset:13120
	s_waitcnt lgkmcnt(1)
	v_mfma_f32_16x16x32_bf16 v[88:91], v[88:91], v[20:23], 0
	s_waitcnt lgkmcnt(0)
	v_mfma_f32_16x16x32_bf16 v[88:91], v[92:95], v[24:27], v[88:91]
	ds_read_b128 v[92:95], v152 offset:13184
	ds_read_b128 v[96:99], v152 offset:13248
	v_mov_b64_e32 v[46:47], v[228:229]
	s_waitcnt vmcnt(0)
	v_lshlrev_b32_e32 v87, 16, v46
	s_waitcnt lgkmcnt(1)
	v_mfma_f32_16x16x32_bf16 v[92:95], v[92:95], v[28:31], v[88:91]
	v_and_b32_e32 v46, 0xffff0000, v46
	s_waitcnt lgkmcnt(0)
	v_mfma_f32_16x16x32_bf16 v[92:95], v[96:99], v[16:19], v[92:95]
	v_mov_b32_e32 v88, v54
	v_mov_b32_e32 v90, v56
	v_lshlrev_b32_e32 v89, 16, v47
	v_and_b32_e32 v91, 0xffff0000, v47
	s_nop 3
	v_add_f32_e32 v50, v48, v92
	v_add_f32_e32 v85, v48, v93
	v_add_f32_e32 v55, v48, v94
	v_add_f32_e32 v57, v48, v95
	v_mul_f32_e32 v95, v50, v87
	v_mul_f32_e32 v93, v85, v46
	v_pk_mul_f32 v[96:97], v[54:55], v[88:89]
	v_pk_mul_f32 v[98:99], v[56:57], v[90:91]
	v_cvt_pk_bf16_f32 v117, v95, v93
	v_mov_b32_e32 v3, v95
	v_cvt_pk_bf16_f32 v115, v97, v99
	ds_read_b128 v[100:103], v152 offset:17408
	ds_read_b128 v[104:107], v152 offset:17472
	s_waitcnt lgkmcnt(1)
	v_mfma_f32_16x16x32_bf16 v[100:103], v[100:103], v[20:23], 0
	s_waitcnt lgkmcnt(0)
	v_mfma_f32_16x16x32_bf16 v[100:103], v[104:107], v[24:27], v[100:103]
	ds_read_b128 v[104:107], v152 offset:17536
	ds_read_b128 v[108:111], v152 offset:17600
	v_mov_b64_e32 v[46:47], v[230:231]
	s_waitcnt lgkmcnt(1)
	v_mfma_f32_16x16x32_bf16 v[100:103], v[104:107], v[28:31], v[100:103]
	s_waitcnt lgkmcnt(0)
	v_mfma_f32_16x16x32_bf16 v[100:103], v[108:111], v[16:19], v[100:103]
	s_nop 7
	v_mov_b32_e32 v104, v100
	v_mov_b32_e32 v105, v102
	v_mov_b32_e32 v102, v101
	v_pk_add_f32 v[100:101], v[48:49], v[104:105] op_sel_hi:[0,1]
	v_pk_add_f32 v[102:103], v[48:49], v[102:103] op_sel_hi:[0,1]
	s_waitcnt vmcnt(0)
	v_lshlrev_b32_e32 v105, 16, v47
	v_lshlrev_b32_e32 v104, 16, v46
	v_and_b32_e32 v47, 0xffff0000, v47
	v_and_b32_e32 v46, 0xffff0000, v46
	v_pk_mul_f32 v[100:101], v[100:101], v[104:105]
	v_pk_mul_f32 v[102:103], v[102:103], v[46:47]
	s_nop 0
	v_cvt_pk_bf16_f32 v116, v100, v102
	v_cvt_pk_bf16_f32 v114, v101, v103
	ds_read_b128 v[104:107], v152 offset:21760
	ds_read_b128 v[108:111], v152 offset:21824
	s_waitcnt lgkmcnt(1)
	v_mfma_f32_16x16x32_bf16 v[104:107], v[104:107], v[20:23], 0
	s_waitcnt lgkmcnt(0)
	v_mfma_f32_16x16x32_bf16 v[104:107], v[108:111], v[24:27], v[104:107]
	ds_read_b128 v[108:111], v152 offset:21888
	ds_read_b128 v[162:165], v152 offset:21952
	v_mov_b64_e32 v[46:47], v[232:233]
	s_waitcnt lgkmcnt(1)
	v_mfma_f32_16x16x32_bf16 v[104:107], v[108:111], v[28:31], v[104:107]
	s_waitcnt vmcnt(0)
	v_lshlrev_b32_e32 v108, 16, v46
	s_waitcnt lgkmcnt(0)
	v_mfma_f32_16x16x32_bf16 v[104:107], v[162:165], v[16:19], v[104:107]
	v_and_b32_e32 v109, 0xffff0000, v46
	v_lshlrev_b32_e32 v110, 16, v47
	v_and_b32_e32 v111, 0xffff0000, v47
	s_nop 4
	v_pk_add_f32 v[104:105], v[48:49], v[104:105] op_sel_hi:[0,1]
	v_pk_add_f32 v[106:107], v[48:49], v[106:107] op_sel_hi:[0,1]
	v_pk_mul_f32 v[46:47], v[104:105], v[108:109]
	v_pk_mul_f32 v[104:105], v[106:107], v[110:111]
	v_cvt_pk_bf16_f32 v113, v46, v47
	s_nop 0
	v_cvt_pk_bf16_f32 v112, v104, v105
	ds_read_b128 v[106:109], v152 offset:26112
	ds_read_b128 v[162:165], v152 offset:26176
	s_waitcnt lgkmcnt(1)
	v_mfma_f32_16x16x32_bf16 v[106:109], v[106:109], v[20:23], 0
	s_waitcnt lgkmcnt(0)
	v_mfma_f32_16x16x32_bf16 v[106:109], v[162:165], v[24:27], v[106:109]
	ds_read_b128 v[162:165], v152 offset:26240
	ds_read_b128 v[166:169], v152 offset:26304
	v_mov_b64_e32 v[110:111], v[234:235]
	s_waitcnt vmcnt(0)
	v_lshlrev_b32_e32 v56, 16, v110
	s_waitcnt lgkmcnt(1)
	v_mfma_f32_16x16x32_bf16 v[106:109], v[162:165], v[28:31], v[106:109]
	v_and_b32_e32 v88, 0xffff0000, v110
	v_lshlrev_b32_e32 v90, 16, v111
	v_and_b32_e32 v92, 0xffff0000, v111
	s_waitcnt lgkmcnt(0)
	v_mfma_f32_16x16x32_bf16 v[106:109], v[166:169], v[16:19], v[106:109]
	s_nop 7
	v_add_f32_e32 v50, v48, v106
	v_add_f32_e32 v54, v48, v107
	v_add_f32_e32 v85, v48, v108
	v_add_f32_e32 v87, v48, v109
	v_mul_f32_e32 v106, v50, v56
	v_mul_f32_e32 v56, v54, v88
	v_mul_f32_e32 v108, v85, v90
	v_mul_f32_e32 v54, v87, v92
	v_cvt_pk_bf16_f32 v111, v106, v56
	v_cvt_pk_bf16_f32 v110, v108, v54
	ds_read_b128 v[162:165], v152 offset:30464
	ds_read_b128 v[166:169], v152 offset:30528
	s_waitcnt lgkmcnt(1)
	v_mfma_f32_16x16x32_bf16 v[20:23], v[162:165], v[20:23], 0
	v_mov_b32_e32 v87, v55
	v_mov_b32_e32 v85, v57
	v_mov_b32_e32 v88, v86
	s_waitcnt lgkmcnt(0)
	v_mfma_f32_16x16x32_bf16 v[20:23], v[166:169], v[24:27], v[20:23]
	ds_read_b128 v[24:27], v152 offset:30592
	ds_read_b128 v[162:165], v152 offset:30656
	v_mov_b32_e32 v90, v84
	s_waitcnt lgkmcnt(1)
	v_mfma_f32_16x16x32_bf16 v[24:27], v[24:27], v[28:31], v[20:23]
	v_mov_b64_e32 v[28:29], v[236:237]
	v_lshlrev_b32_e32 v30, 16, v15
	s_nop 0
	v_mov_b32_e32 v20, v106
	s_waitcnt lgkmcnt(0)
	v_mfma_f32_16x16x32_bf16 v[16:19], v[162:165], v[16:19], v[24:27]
	v_mov_b32_e32 v22, v108
	v_and_b32_e32 v15, 0xffff0000, v15
	v_mov_b32_e32 v31, v51
	s_waitcnt vmcnt(0)
	v_and_b32_e32 v24, 0xffff0000, v28
	s_nop 2
	v_add_f32_e32 v16, v48, v16
	v_add_f32_e32 v17, v48, v17
	v_add_f32_e32 v107, v48, v18
	v_add_f32_e32 v109, v48, v19
	v_lshlrev_b32_e32 v18, 16, v28
	v_lshlrev_b32_e32 v21, 16, v29
	v_and_b32_e32 v23, 0xffff0000, v29
	v_mul_f32_e32 v19, v16, v18
	v_mul_f32_e32 v17, v17, v24
	v_pk_mul_f32 v[26:27], v[106:107], v[20:21]
	v_pk_mul_f32 v[24:25], v[108:109], v[22:23]
	v_cvt_pk_bf16_f32 v106, v19, v17
	v_lshlrev_b32_e32 v16, 16, v12
	v_cvt_pk_bf16_f32 v29, v27, v25
	global_load_dwordx4 v[162:165], v157, s[48:49] offset:1536
	global_load_dwordx4 v[166:169], v157, s[50:51] offset:1536
	global_load_dwordx4 v[170:173], v157, s[48:49] offset:1552
	global_load_dwordx4 v[174:177], v157, s[50:51] offset:1552
	v_and_b32_e32 v18, 0xffff0000, v12
	v_lshlrev_b32_e32 v20, 16, v13
	v_and_b32_e32 v22, 0xffff0000, v13
	ds_read_b64 v[12:13], v160
	v_lshlrev_b32_e32 v28, 16, v14
	v_and_b32_e32 v14, 0xffff0000, v14
	v_mov_b32_e32 v57, v107
	v_mov_b32_e32 v55, v109
	s_waitcnt lgkmcnt(0)
	v_sub_f32_e32 v16, v16, v12
	v_sub_f32_e32 v15, v15, v12
	v_sub_f32_e32 v18, v18, v12
	v_mul_f32_e32 v16, v13, v16
	v_mul_f32_e32 v15, v13, v15
	v_sub_f32_e32 v20, v20, v12
	v_mul_f32_e32 v18, v13, v18
	v_sub_f32_e32 v22, v22, v12
	v_sub_f32_e32 v14, v14, v12
	v_mul_f32_e32 v20, v13, v20
	v_sub_f32_e32 v28, v28, v12
	v_mul_f32_e32 v22, v13, v22
	v_mul_f32_e32 v14, v13, v14
	v_sub_f32_e32 v30, v30, v12
	v_mul_f32_e32 v28, v13, v28
	v_mul_f32_e32 v30, v13, v30
	s_waitcnt vmcnt(2)
	v_fma_f32 v16, v162, v16, v166
	v_fma_f32 v18, v163, v18, v167
	s_waitcnt vmcnt(0)
	v_fmac_f32_e32 v177, v173, v15
	v_cvt_pk_bf16_f32 v15, v16, v33
	ds_write_b16 v155, v15 offset:34816
	v_cvt_pk_bf16_f32 v15, v18, v33
	v_fma_f32 v20, v164, v20, v168
	ds_write_b16 v155, v15 offset:35088
	v_cvt_pk_bf16_f32 v15, v20, v33
	v_fmac_f32_e32 v169, v165, v22
	v_fma_f32 v14, v171, v14, v175
	ds_write_b16 v155, v15 offset:35360
	v_cvt_pk_bf16_f32 v15, v169, v33
	v_fma_f32 v22, v170, v28, v174
	ds_write_b16 v155, v15 offset:35632
	v_cvt_pk_bf16_f32 v15, v22, v33
	ds_write_b16 v155, v15 offset:35904
	v_cvt_pk_bf16_f32 v14, v14, v33
	v_fma_f32 v28, v172, v30, v176
	ds_write_b16 v155, v14 offset:36176
	v_cvt_pk_bf16_f32 v14, v28, v33
	ds_write_b16 v155, v14 offset:36448
	v_cvt_pk_bf16_f32 v14, v177, v33
	global_load_dwordx4 v[160:163], v157, s[48:49] offset:1664
	global_load_dwordx4 v[164:167], v157, s[50:51] offset:1664
	global_load_dwordx4 v[168:171], v157, s[48:49] offset:1680
	global_load_dwordx4 v[172:175], v157, s[50:51] offset:1680
	v_lshlrev_b32_e32 v15, 16, v8
	v_and_b32_e32 v8, 0xffff0000, v8
	v_lshlrev_b32_e32 v20, 16, v11
	v_and_b32_e32 v11, 0xffff0000, v11
	v_sub_f32_e32 v8, v8, v12
	v_lshlrev_b32_e32 v16, 16, v9
	v_sub_f32_e32 v15, v15, v12
	v_sub_f32_e32 v11, v11, v12
	v_mul_f32_e32 v8, v13, v8
	v_and_b32_e32 v9, 0xffff0000, v9
	v_sub_f32_e32 v16, v16, v12
	v_mul_f32_e32 v15, v13, v15
	v_mul_f32_e32 v11, v13, v11
	v_lshlrev_b32_e32 v18, 16, v10
	v_sub_f32_e32 v9, v9, v12
	v_mul_f32_e32 v16, v13, v16
	ds_write_b16 v155, v14 offset:36720
	v_and_b32_e32 v10, 0xffff0000, v10
	v_sub_f32_e32 v18, v18, v12
	v_mul_f32_e32 v9, v13, v9
	v_sub_f32_e32 v10, v10, v12
	v_mul_f32_e32 v18, v13, v18
	v_sub_f32_e32 v20, v20, v12
	v_mul_f32_e32 v10, v13, v10
	v_mul_f32_e32 v20, v13, v20
	v_lshlrev_b32_e32 v22, 16, v7
	v_and_b32_e32 v7, 0xffff0000, v7
	v_sub_f32_e32 v7, v7, v12
	v_mul_f32_e32 v7, v13, v7
	v_sub_f32_e32 v22, v22, v12
	v_mul_f32_e32 v22, v13, v22
	v_mov_b32_e32 v30, v64
	v_lshlrev_b32_e32 v28, 16, v0
	s_waitcnt vmcnt(2)
	v_fma_f32 v8, v8, v161, v165
	v_fma_f32 v14, v15, v160, v164
	s_waitcnt vmcnt(0)
	v_fmac_f32_e32 v175, v11, v171
	v_cvt_pk_bf16_f32 v11, v14, v33
	ds_write_b16 v155, v11 offset:43520
	v_cvt_pk_bf16_f32 v8, v8, v33
	v_fma_f32 v15, v16, v162, v166
	ds_write_b16 v155, v8 offset:43792
	v_cvt_pk_bf16_f32 v8, v15, v33
	v_fmac_f32_e32 v167, v9, v163
	ds_write_b16 v155, v8 offset:44064
	v_cvt_pk_bf16_f32 v8, v167, v33
	v_fma_f32 v9, v18, v168, v172
	ds_write_b16 v155, v8 offset:44336
	v_cvt_pk_bf16_f32 v8, v9, v33
	v_fma_f32 v10, v10, v169, v173
	ds_write_b16 v155, v8 offset:44608
	v_cvt_pk_bf16_f32 v8, v10, v33
	v_fma_f32 v16, v20, v170, v174
	ds_write_b16 v155, v8 offset:44880
	v_cvt_pk_bf16_f32 v8, v16, v33
	ds_write_b16 v155, v8 offset:45152
	v_cvt_pk_bf16_f32 v18, v175, v33
	global_load_dwordx4 v[8:11], v157, s[48:49] offset:1792
	global_load_dwordx4 v[160:163], v157, s[50:51] offset:1792
	global_load_dwordx4 v[164:167], v157, s[48:49] offset:1808
	global_load_dwordx4 v[168:171], v157, s[50:51] offset:1808
	v_pk_add_f32 v[14:15], v[66:67], v[66:67] op_sel:[0,1] op_sel_hi:[1,0]
	v_mul_f32_e32 v16, v53, v53
	v_mov_b32_e32 v50, v14
	v_pk_add_f32 v[14:15], v[14:15], v[64:65]
	v_pk_fma_f32 v[52:53], v[52:53], v[52:53], v[16:17] op_sel_hi:[1,1,0]
	v_lshlrev_b32_e32 v15, 16, v4
	v_and_b32_e32 v4, 0xffff0000, v4
	v_sub_f32_e32 v4, v4, v12
	v_lshlrev_b32_e32 v16, 16, v5
	v_sub_f32_e32 v15, v15, v12
	v_mul_f32_e32 v4, v13, v4
	v_and_b32_e32 v5, 0xffff0000, v5
	v_sub_f32_e32 v16, v16, v12
	v_mul_f32_e32 v15, v13, v15
	v_lshlrev_b32_e32 v20, 16, v6
	v_sub_f32_e32 v5, v5, v12
	v_mul_f32_e32 v16, v13, v16
	ds_write_b16 v155, v18 offset:45424
	v_and_b32_e32 v6, 0xffff0000, v6
	v_sub_f32_e32 v20, v20, v12
	v_mul_f32_e32 v5, v13, v5
	v_sub_f32_e32 v6, v6, v12
	v_mul_f32_e32 v20, v13, v20
	v_mul_f32_e32 v6, v13, v6
	v_mov_b32_e32 v172, v58
	v_mov_b32_e32 v173, v49
	v_pk_mul_f32 v[30:31], v[50:51], v[30:31]
	v_mov_b32_e32 v48, v52
	v_pk_add_f32 v[50:51], v[52:53], v[58:59]
	v_pk_add_f32 v[52:53], v[68:69], v[70:71]
	v_and_b32_e32 v68, 0xffff0000, v0
	v_lshlrev_b32_e32 v69, 16, v1
	v_and_b32_e32 v70, 0xffff0000, v1
	v_pk_mul_f32 v[0:1], v[78:79], v[78:79]
	v_lshlrev_b32_e32 v71, 16, v2
	v_pk_fma_f32 v[0:1], v[76:77], v[76:77], v[0:1]
	v_pk_mul_f32 v[58:59], v[98:99], v[98:99]
	v_pk_add_f32 v[0:1], v[0:1], v[0:1] op_sel:[0,1] op_sel_hi:[1,0]
	s_waitcnt vmcnt(2)
	v_fma_f32 v4, v4, v9, v161
	v_fma_f32 v8, v15, v8, v160
	s_waitcnt vmcnt(0)
	v_fmac_f32_e32 v171, v7, v167
	v_cvt_pk_bf16_f32 v7, v8, v33
	ds_write_b16 v155, v7 offset:52224
	v_cvt_pk_bf16_f32 v4, v4, v33
	v_fma_f32 v9, v16, v10, v162
	ds_write_b16 v155, v4 offset:52496
	v_cvt_pk_bf16_f32 v4, v9, v33
	v_fmac_f32_e32 v163, v5, v11
	ds_write_b16 v155, v4 offset:52768
	v_cvt_pk_bf16_f32 v4, v163, v33
	v_fma_f32 v5, v20, v164, v168
	ds_write_b16 v155, v4 offset:53040
	v_cvt_pk_bf16_f32 v4, v5, v33
	v_fma_f32 v6, v6, v165, v169
	ds_write_b16 v155, v4 offset:53312
	v_cvt_pk_bf16_f32 v4, v6, v33
	v_fma_f32 v10, v22, v166, v170
	ds_write_b16 v155, v4 offset:53584
	v_cvt_pk_bf16_f32 v4, v10, v33
	ds_write_b16 v155, v4 offset:53856
	v_cvt_pk_bf16_f32 v18, v171, v33
	global_load_dwordx4 v[4:7], v157, s[48:49] offset:1920
	global_load_dwordx4 v[8:11], v157, s[50:51] offset:1920
	global_load_dwordx4 v[60:63], v157, s[48:49] offset:1936
	global_load_dwordx4 v[64:67], v157, s[50:51] offset:1936
	v_mov_b32_e32 v15, v31
	v_pk_mul_f32 v[30:31], v[48:49], v[172:173]
	v_mov_b32_e32 v2, v0
	v_mov_b32_e32 v51, v31
	v_pk_add_f32 v[14:15], v[14:15], v[50:51]
	v_mul_f32_e32 v16, v81, v81
	v_pk_add_f32 v[14:15], v[14:15], v[52:53]
	v_pk_fma_f32 v[30:31], v[80:81], v[80:81], v[16:17] op_sel_hi:[1,1,0]
	v_pk_add_f32 v[14:15], v[14:15], v[14:15] op_sel:[0,1] op_sel_hi:[1,0]
	v_mov_b32_e32 v92, v30
	v_mov_b32_e32 v94, v14
	v_pk_add_f32 v[0:1], v[14:15], v[0:1]
	v_mul_f32_e32 v14, v83, v83
	v_pk_fma_f32 v[14:15], v[82:83], v[82:83], v[14:15] op_sel_hi:[1,1,0]
	v_mov_b32_e32 v49, v93
	v_mov_b32_e32 v48, v14
	v_pk_add_f32 v[14:15], v[30:31], v[14:15]
	v_pk_fma_f32 v[30:31], v[86:87], v[88:89], v[96:97]
	v_pk_mul_f32 v[50:51], v[96:97], v[96:97]
	v_pk_fma_f32 v[52:53], v[84:85], v[90:91], v[98:99]
	v_pk_mul_f32 v[2:3], v[94:95], v[2:3]
	v_pk_mul_f32 v[48:49], v[92:93], v[48:49]
	v_mov_b32_e32 v31, v51
	v_mov_b32_e32 v53, v59
	v_mov_b32_e32 v1, v3
	v_mov_b32_e32 v15, v49
	v_pk_add_f32 v[2:3], v[30:31], v[52:53]
	v_pk_add_f32 v[0:1], v[0:1], v[14:15]
	ds_write_b16 v155, v18 offset:54128
	v_pk_add_f32 v[50:51], v[0:1], v[2:3]
	v_pk_mul_f32 v[0:1], v[102:103], v[102:103]
	v_sub_f32_e32 v2, v69, v12
	v_pk_fma_f32 v[0:1], v[100:101], v[100:101], v[0:1]
	v_sub_f32_e32 v3, v70, v12
	v_pk_add_f32 v[48:49], v[0:1], v[0:1] op_sel:[0,1] op_sel_hi:[1,0]
	v_mul_f32_e32 v0, v105, v105
	v_pk_fma_f32 v[30:31], v[104:105], v[104:105], v[0:1] op_sel_hi:[1,1,0]
	v_sub_f32_e32 v0, v28, v12
	v_mul_f32_e32 v0, v13, v0
	v_sub_f32_e32 v1, v68, v12
	v_mul_f32_e32 v1, v13, v1
	v_mul_f32_e32 v2, v13, v2
	v_sub_f32_e32 v14, v71, v12
	v_mul_f32_e32 v3, v13, v3
	v_sub_f32_e32 v15, v72, v12
	v_mul_f32_e32 v14, v13, v14
	v_sub_f32_e32 v16, v73, v12
	v_mul_f32_e32 v15, v13, v15
	v_sub_f32_e32 v12, v74, v12
	v_mul_f32_e32 v16, v13, v16
	v_mul_f32_e32 v12, v13, v12
	v_mov_b32_e32 v20, v56
	v_mov_b32_e32 v22, v54
	s_waitcnt vmcnt(2)
	v_fma_f32 v0, v0, v4, v8
	v_cvt_pk_bf16_f32 v0, v0, v33
	v_fma_f32 v1, v1, v5, v9
	ds_write_b16 v155, v0 offset:60928
	v_cvt_pk_bf16_f32 v0, v1, v33
	v_fma_f32 v2, v2, v6, v10
	ds_write_b16 v155, v0 offset:61200
	v_cvt_pk_bf16_f32 v0, v2, v33
	v_fmac_f32_e32 v11, v3, v7
	ds_write_b16 v155, v0 offset:61472
	v_cvt_pk_bf16_f32 v0, v11, v33
	s_waitcnt vmcnt(0)
	v_fma_f32 v3, v14, v60, v64
	ds_write_b16 v155, v0 offset:61744
	v_cvt_pk_bf16_f32 v0, v3, v33
	v_fma_f32 v4, v15, v61, v65
	ds_write_b16 v155, v0 offset:62016
	v_cvt_pk_bf16_f32 v0, v4, v33
	v_fma_f32 v5, v16, v62, v66
	ds_write_b16 v155, v0 offset:62288
	v_cvt_pk_bf16_f32 v0, v5, v33
	v_fmac_f32_e32 v67, v12, v63
	ds_write_b16 v155, v0 offset:62560
	v_cvt_pk_bf16_f32 v0, v67, v33
	ds_write_b16 v155, v0 offset:62832
	s_waitcnt lgkmcnt(0)
	s_barrier
	v_add_co_u32_e32 v4, vcc, s28, v42
	v_pk_fma_f32 v[56:57], v[56:57], v[20:21], v[26:27]
	s_nop 0
	v_addc_co_u32_e32 v5, vcc, 0, v43, vcc
	global_load_dwordx2 v[224:225], v[40:41], off offset:1824
	global_load_dwordx2 v[226:227], v[40:41], off offset:1856
	global_load_dwordx2 v[228:229], v[40:41], off offset:1888
	global_load_dwordx2 v[230:231], v[40:41], off offset:1920
	global_load_dwordx2 v[232:233], v[40:41], off offset:1952
	global_load_dwordx2 v[234:235], v[40:41], off offset:1984
	global_load_dwordx2 v[236:237], v[40:41], off offset:2016
	global_load_dwordx4 v[8:11], v[4:5], off
	global_load_dwordx4 v[0:3], v[4:5], off offset:64
	global_load_dwordx2 v[52:53], v[40:41], off offset:1792
	global_load_dwordx4 v[12:15], v[4:5], off offset:128
	s_nop 0
	global_load_dwordx4 v[4:7], v[4:5], off offset:192
	s_nop 0
	global_load_dword v28, v[44:45], off offset:1536
	ds_read_b128 v[42:45], v152 offset:34816
	ds_read_b128 v[58:61], v152 offset:34880
	ds_read_b128 v[62:65], v152 offset:34944
	v_pk_fma_f32 v[54:55], v[54:55], v[22:23], v[24:25]
	v_pk_mul_f32 v[24:25], v[24:25], v[24:25]
	v_pk_mul_f32 v[26:27], v[26:27], v[26:27]
	v_pk_add_f32 v[50:51], v[50:51], v[50:51] op_sel:[0,1] op_sel_hi:[1,0]
	v_mov_b32_e32 v168, v48
	v_mov_b32_e32 v169, v19
	v_mov_b32_e32 v170, v30
	v_mov_b32_e32 v171, v17
	s_waitcnt vmcnt(5) lgkmcnt(2)
	v_mfma_f32_16x16x32_bf16 v[42:45], v[42:45], v[8:11], 0
	s_waitcnt vmcnt(3)
	v_lshlrev_b32_e32 v67, 16, v53
	v_lshlrev_b32_e32 v66, 16, v52
	s_waitcnt lgkmcnt(1)
	v_mfma_f32_16x16x32_bf16 v[42:45], v[58:61], v[0:3], v[42:45]
	ds_read_b128 v[58:61], v152 offset:35008
	v_and_b32_e32 v53, 0xffff0000, v53
	v_and_b32_e32 v52, 0xffff0000, v52
	s_waitcnt vmcnt(2) lgkmcnt(1)
	v_mfma_f32_16x16x32_bf16 v[42:45], v[62:65], v[12:15], v[42:45]
	s_waitcnt vmcnt(1) lgkmcnt(0)
	v_mfma_f32_16x16x32_bf16 v[42:45], v[58:61], v[4:7], v[42:45]
	s_nop 7
	v_mov_b32_e32 v58, v42
	v_mov_b32_e32 v59, v44
	v_mov_b32_e32 v44, v43
	s_waitcnt vmcnt(0)
	v_pk_add_f32 v[42:43], v[28:29], v[58:59] op_sel_hi:[0,1]
	v_pk_add_f32 v[44:45], v[28:29], v[44:45] op_sel_hi:[0,1]
	v_pk_mul_f32 v[42:43], v[42:43], v[66:67]
	v_pk_mul_f32 v[44:45], v[44:45], v[52:53]
	s_nop 0
	v_cvt_pk_bf16_f32 v77, v42, v44
	v_cvt_pk_bf16_f32 v76, v43, v45
	ds_read_b128 v[58:61], v152 offset:39168
	ds_read_b128 v[62:65], v152 offset:39232
	s_waitcnt lgkmcnt(1)
	v_mfma_f32_16x16x32_bf16 v[58:61], v[58:61], v[8:11], 0
	s_waitcnt lgkmcnt(0)
	v_mfma_f32_16x16x32_bf16 v[58:61], v[62:65], v[0:3], v[58:61]
	ds_read_b128 v[62:65], v152 offset:39296
	ds_read_b128 v[66:69], v152 offset:39360
	v_mov_b64_e32 v[52:53], v[224:225]
	s_waitcnt lgkmcnt(1)
	v_mfma_f32_16x16x32_bf16 v[58:61], v[62:65], v[12:15], v[58:61]
	s_waitcnt vmcnt(0)
	v_lshlrev_b32_e32 v62, 16, v52
	s_waitcnt lgkmcnt(0)
	v_mfma_f32_16x16x32_bf16 v[58:61], v[66:69], v[4:7], v[58:61]
	v_and_b32_e32 v63, 0xffff0000, v52
	v_lshlrev_b32_e32 v64, 16, v53
	v_and_b32_e32 v65, 0xffff0000, v53
	s_nop 4
	v_pk_add_f32 v[58:59], v[28:29], v[58:59] op_sel_hi:[0,1]
	v_pk_add_f32 v[60:61], v[28:29], v[60:61] op_sel_hi:[0,1]
	v_pk_mul_f32 v[52:53], v[58:59], v[62:63]
	v_pk_mul_f32 v[58:59], v[60:61], v[64:65]
	v_cvt_pk_bf16_f32 v75, v52, v53
	s_nop 0
	v_cvt_pk_bf16_f32 v74, v58, v59
	ds_read_b128 v[60:63], v152 offset:43520
	ds_read_b128 v[64:67], v152 offset:43584
	s_waitcnt lgkmcnt(1)
	v_mfma_f32_16x16x32_bf16 v[60:63], v[60:63], v[8:11], 0
	s_waitcnt lgkmcnt(0)
	v_mfma_f32_16x16x32_bf16 v[60:63], v[64:67], v[0:3], v[60:63]
	ds_read_b128 v[64:67], v152 offset:43648
	ds_read_b128 v[68:71], v152 offset:43712
	s_waitcnt lgkmcnt(1)
	v_mfma_f32_16x16x32_bf16 v[60:63], v[64:67], v[12:15], v[60:63]
	v_mov_b64_e32 v[64:65], v[226:227]
	s_waitcnt vmcnt(0)
	v_lshlrev_b32_e32 v66, 16, v65
	s_waitcnt lgkmcnt(0)
	v_mfma_f32_16x16x32_bf16 v[60:63], v[68:71], v[4:7], v[60:63]
	v_and_b32_e32 v65, 0xffff0000, v65
	s_nop 6
	v_add_f32_e32 v16, v28, v60
	v_add_f32_e32 v18, v28, v61
	v_add_f32_e32 v60, v28, v62
	v_add_f32_e32 v61, v28, v63
	v_lshlrev_b32_e32 v62, 16, v64
	v_and_b32_e32 v63, 0xffff0000, v64
	v_mul_f32_e32 v64, v16, v62
	v_mul_f32_e32 v62, v18, v63
	v_mul_f32_e32 v66, v60, v66
	v_mul_f32_e32 v60, v61, v65
	v_cvt_pk_bf16_f32 v73, v64, v62
	v_cvt_pk_bf16_f32 v72, v66, v60
	ds_read_b128 v[68:71], v152 offset:47872
	ds_read_b128 v[78:81], v152 offset:47936
	s_waitcnt lgkmcnt(1)
	v_mfma_f32_16x16x32_bf16 v[68:71], v[68:71], v[8:11], 0
	v_mov_b32_e32 v94, v64
	v_mov_b32_e32 v96, v66
	s_waitcnt lgkmcnt(0)
	v_mfma_f32_16x16x32_bf16 v[68:71], v[78:81], v[0:3], v[68:71]
	ds_read_b128 v[78:81], v152 offset:48000
	ds_read_b128 v[82:85], v152 offset:48064
	s_waitcnt lgkmcnt(1)
	v_mfma_f32_16x16x32_bf16 v[68:71], v[78:81], v[12:15], v[68:71]
	v_mov_b64_e32 v[78:79], v[228:229]
	s_waitcnt vmcnt(0)
	v_lshlrev_b32_e32 v61, 16, v78
	s_waitcnt lgkmcnt(0)
	v_mfma_f32_16x16x32_bf16 v[68:71], v[82:85], v[4:7], v[68:71]
	v_and_b32_e32 v63, 0xffff0000, v78
	v_lshlrev_b32_e32 v95, 16, v79
	v_and_b32_e32 v97, 0xffff0000, v79
	s_nop 4
	v_add_f32_e32 v16, v28, v68
	v_add_f32_e32 v18, v28, v69
	v_add_f32_e32 v65, v28, v70
	v_add_f32_e32 v67, v28, v71
	v_mul_f32_e32 v99, v16, v61
	v_mul_f32_e32 v101, v18, v63
	v_pk_mul_f32 v[102:103], v[64:65], v[94:95]
	v_pk_mul_f32 v[104:105], v[66:67], v[96:97]
	v_cvt_pk_bf16_f32 v71, v99, v101
	v_mul_f32_e32 v16, v47, v47
	v_cvt_pk_bf16_f32 v69, v103, v105
	ds_read_b128 v[78:81], v152 offset:52224
	ds_read_b128 v[82:85], v152 offset:52288
	s_waitcnt lgkmcnt(1)
	v_mfma_f32_16x16x32_bf16 v[78:81], v[78:81], v[8:11], 0
	v_mov_b32_e32 v18, v50
	v_pk_mul_f32 v[18:19], v[18:19], v[168:169]
	v_mov_b32_e32 v63, v65
	s_waitcnt lgkmcnt(0)
	v_mfma_f32_16x16x32_bf16 v[78:81], v[82:85], v[0:3], v[78:81]
	ds_read_b128 v[82:85], v152 offset:52352
	ds_read_b128 v[86:89], v152 offset:52416
	v_mov_b32_e32 v94, v62
	v_mov_b32_e32 v96, v60
	s_waitcnt lgkmcnt(1)
	v_mfma_f32_16x16x32_bf16 v[78:81], v[82:85], v[12:15], v[78:81]
	v_mov_b64_e32 v[82:83], v[230:231]
	s_waitcnt lgkmcnt(0)
	v_mfma_f32_16x16x32_bf16 v[78:81], v[86:89], v[4:7], v[78:81]
	s_nop 7
	v_mov_b32_e32 v84, v78
	v_mov_b32_e32 v85, v80
	v_mov_b32_e32 v80, v79
	v_pk_add_f32 v[78:79], v[28:29], v[84:85] op_sel_hi:[0,1]
	v_pk_add_f32 v[80:81], v[28:29], v[80:81] op_sel_hi:[0,1]
	s_waitcnt vmcnt(0)
	v_lshlrev_b32_e32 v85, 16, v83
	v_lshlrev_b32_e32 v84, 16, v82
	v_and_b32_e32 v83, 0xffff0000, v83
	v_and_b32_e32 v82, 0xffff0000, v82
	v_pk_mul_f32 v[108:109], v[78:79], v[84:85]
	v_pk_mul_f32 v[160:161], v[80:81], v[82:83]
	s_nop 0
	v_cvt_pk_bf16_f32 v70, v108, v160
	v_cvt_pk_bf16_f32 v68, v109, v161
	ds_read_b128 v[78:81], v152 offset:56576
	ds_read_b128 v[82:85], v152 offset:56640
	s_waitcnt lgkmcnt(1)
	v_mfma_f32_16x16x32_bf16 v[78:81], v[78:81], v[8:11], 0
	s_waitcnt lgkmcnt(0)
	v_mfma_f32_16x16x32_bf16 v[78:81], v[82:85], v[0:3], v[78:81]
	ds_read_b128 v[82:85], v152 offset:56704
	ds_read_b128 v[86:89], v152 offset:56768
	s_waitcnt lgkmcnt(1)
	v_mfma_f32_16x16x32_bf16 v[78:81], v[82:85], v[12:15], v[78:81]
	v_mov_b64_e32 v[82:83], v[232:233]
	s_waitcnt vmcnt(0)
	v_lshlrev_b32_e32 v84, 16, v82
	s_waitcnt lgkmcnt(0)
	v_mfma_f32_16x16x32_bf16 v[78:81], v[86:89], v[4:7], v[78:81]
	v_and_b32_e32 v85, 0xffff0000, v82
	v_lshlrev_b32_e32 v82, 16, v83
	v_and_b32_e32 v83, 0xffff0000, v83
	s_nop 4
	v_pk_add_f32 v[78:79], v[28:29], v[78:79] op_sel_hi:[0,1]
	v_pk_add_f32 v[80:81], v[28:29], v[80:81] op_sel_hi:[0,1]
	v_pk_mul_f32 v[162:163], v[78:79], v[84:85]
	v_pk_mul_f32 v[164:165], v[80:81], v[82:83]
	v_cvt_pk_bf16_f32 v66, v162, v163
	s_nop 0
	v_cvt_pk_bf16_f32 v64, v164, v165
	v_mov_b64_e32 v[166:167], v[234:235]
	ds_read_b128 v[78:81], v152 offset:60928
	ds_read_b128 v[82:85], v152 offset:60992
	ds_read_b128 v[86:89], v152 offset:61056
	ds_read_b128 v[90:93], v152 offset:61120
	s_waitcnt lgkmcnt(3)
	v_mfma_f32_16x16x32_bf16 v[78:81], v[78:81], v[8:11], 0
	s_waitcnt vmcnt(0)
	v_lshlrev_b32_e32 v24, 16, v166
	s_waitcnt lgkmcnt(2)
	v_mfma_f32_16x16x32_bf16 v[78:81], v[82:85], v[0:3], v[78:81]
	v_and_b32_e32 v55, 0xffff0000, v166
	v_lshlrev_b32_e32 v57, 16, v167
	v_and_b32_e32 v61, 0xffff0000, v167
	s_waitcnt lgkmcnt(1)
	v_mfma_f32_16x16x32_bf16 v[78:81], v[86:89], v[12:15], v[78:81]
	s_waitcnt lgkmcnt(0)
	v_mfma_f32_16x16x32_bf16 v[20:23], v[90:93], v[4:7], v[78:81]
	s_nop 7
	v_add_f32_e32 v20, v28, v20
	v_add_f32_e32 v21, v28, v21
	v_add_f32_e32 v22, v28, v22
	v_add_f32_e32 v23, v28, v23
	v_mul_f32_e32 v26, v20, v24
	v_mul_f32_e32 v78, v21, v55
	v_mul_f32_e32 v80, v22, v57
	v_mul_f32_e32 v82, v23, v61
	v_cvt_pk_bf16_f32 v21, v26, v78
	v_cvt_pk_bf16_f32 v20, v80, v82
	v_mov_b64_e32 v[84:85], v[236:237]
	v_pk_fma_f32 v[40:41], v[46:47], v[46:47], v[16:17] op_sel_hi:[1,1,0]
	v_pk_add_f32 v[22:23], v[50:51], v[48:49]
	v_mov_b32_e32 v16, v40
	v_mov_b32_e32 v55, v25
	v_pk_add_f32 v[24:25], v[40:41], v[30:31]
	v_pk_mul_f32 v[16:17], v[16:17], v[170:171]
	v_mov_b32_e32 v57, v27
	v_mov_b32_e32 v23, v19
	v_mov_b32_e32 v25, v17
	v_pk_add_f32 v[30:31], v[56:57], v[54:55]
	v_pk_add_f32 v[16:17], v[22:23], v[24:25]
	v_pk_mul_f32 v[18:19], v[44:45], v[44:45]
	v_pk_add_f32 v[16:17], v[16:17], v[30:31]
	v_pk_fma_f32 v[18:19], v[42:43], v[42:43], v[18:19]
	v_pk_add_f32 v[16:17], v[16:17], v[16:17] op_sel:[0,1] op_sel_hi:[1,0]
	v_pk_add_f32 v[18:19], v[18:19], v[18:19] op_sel:[0,1] op_sel_hi:[1,0]
	v_mov_b32_e32 v98, v16
	v_mov_b32_e32 v22, v18
	v_pk_add_f32 v[16:17], v[16:17], v[18:19]
	v_mul_f32_e32 v18, v59, v59
	v_mul_f32_e32 v24, v53, v53
	v_pk_fma_f32 v[18:19], v[58:59], v[58:59], v[18:19] op_sel_hi:[1,1,0]
	v_pk_fma_f32 v[24:25], v[52:53], v[52:53], v[24:25] op_sel_hi:[1,1,0]
	v_mov_b32_e32 v30, v18
	v_mov_b32_e32 v100, v24
	v_mov_b32_e32 v61, v67
	v_mov_b32_e32 v23, v99
	v_mov_b32_e32 v31, v101
	v_pk_add_f32 v[18:19], v[24:25], v[18:19]
	v_pk_fma_f32 v[24:25], v[62:63], v[94:95], v[102:103]
	v_pk_mul_f32 v[40:41], v[102:103], v[102:103]
	v_pk_fma_f32 v[42:43], v[60:61], v[96:97], v[104:105]
	v_pk_mul_f32 v[44:45], v[104:105], v[104:105]
	v_pk_mul_f32 v[22:23], v[98:99], v[22:23]
	v_pk_mul_f32 v[30:31], v[100:101], v[30:31]
	v_mov_b32_e32 v25, v41
	v_mov_b32_e32 v43, v45
	v_mov_b32_e32 v17, v23
	v_mov_b32_e32 v19, v31
	v_pk_add_f32 v[22:23], v[24:25], v[42:43]
	v_pk_add_f32 v[16:17], v[16:17], v[18:19]
	v_mul_f32_e32 v48, v165, v165
	v_pk_add_f32 v[16:17], v[16:17], v[22:23]
	v_pk_mul_f32 v[22:23], v[160:161], v[160:161]
	v_pk_add_f32 v[30:31], v[16:17], v[16:17] op_sel:[0,1] op_sel_hi:[1,0]
	ds_read_b128 v[16:19], v152 offset:65280
	v_pk_fma_f32 v[22:23], v[108:109], v[108:109], v[22:23]
	v_mov_b32_e32 v44, v30
	v_pk_add_f32 v[40:41], v[22:23], v[22:23] op_sel:[0,1] op_sel_hi:[1,0]
	ds_read_b128 v[22:25], v152 offset:65344
	v_mov_b32_e32 v46, v40
	v_pk_add_f32 v[30:31], v[30:31], v[40:41]
	ds_read_b128 v[40:43], v152 offset:65408
	s_waitcnt lgkmcnt(2)
	v_mfma_f32_16x16x32_bf16 v[8:11], v[16:19], v[8:11], 0
	ds_read_b128 v[16:19], v152 offset:65472
	v_mul_f32_e32 v50, v163, v163
	v_pk_fma_f32 v[48:49], v[164:165], v[164:165], v[48:49] op_sel_hi:[1,1,0]
	s_waitcnt lgkmcnt(2)
	v_mfma_f32_16x16x32_bf16 v[0:3], v[22:25], v[0:3], v[8:11]
	v_mov_b32_e32 v22, v48
	s_waitcnt lgkmcnt(1)
	v_mfma_f32_16x16x32_bf16 v[0:3], v[40:43], v[12:15], v[0:3]
	v_fma_f32 v8, v162, v162, v50
	v_fma_f32 v9, v163, v163, v50
	v_mov_b32_e32 v12, v26
	v_mov_b32_e32 v14, v80
	s_waitcnt lgkmcnt(0)
	v_mfma_f32_16x16x32_bf16 v[0:3], v[16:19], v[4:7], v[0:3]
	v_mov_b32_e32 v10, v8
	v_pk_add_f32 v[8:9], v[8:9], v[48:49]
	s_waitcnt vmcnt(0)
	v_lshlrev_b32_e32 v13, 16, v85
	s_nop 3
	v_add_f32_e32 v0, v28, v0
	v_add_f32_e32 v1, v28, v1
	v_add_f32_e32 v27, v28, v2
	v_add_f32_e32 v81, v28, v3
	v_lshlrev_b32_e32 v2, 16, v84
	v_and_b32_e32 v3, 0xffff0000, v84
	v_and_b32_e32 v15, 0xffff0000, v85
	v_mul_f32_e32 v45, v0, v2
	v_mul_f32_e32 v11, v1, v3
	v_mov_b32_e32 v79, v27
	v_mov_b32_e32 v83, v81
	v_pk_mul_f32 v[0:1], v[26:27], v[12:13]
	v_mov_b32_e32 v12, v78
	v_pk_mul_f32 v[2:3], v[80:81], v[14:15]
	v_mov_b32_e32 v14, v82
	v_mov_b32_e32 v47, v45
	v_mov_b32_e32 v23, v11
	v_cvt_pk_bf16_f32 v7, v45, v11
	v_cvt_pk_bf16_f32 v6, v1, v3
	v_pk_fma_f32 v[4:5], v[78:79], v[12:13], v[0:1]
	v_pk_mul_f32 v[0:1], v[0:1], v[0:1]
	v_pk_fma_f32 v[12:13], v[82:83], v[14:15], v[2:3]
	v_pk_mul_f32 v[2:3], v[2:3], v[2:3]
	v_pk_mul_f32 v[14:15], v[44:45], v[46:47]
	v_pk_mul_f32 v[10:11], v[10:11], v[22:23]
	v_mov_b32_e32 v5, v1
	v_mov_b32_e32 v13, v3
	v_mov_b32_e32 v31, v15
	v_mov_b32_e32 v9, v11
	v_pk_add_f32 v[0:1], v[4:5], v[12:13]
	v_pk_add_f32 v[2:3], v[30:31], v[8:9]
	s_nop 0
	v_pk_add_f32 v[0:1], v[2:3], v[0:1]
	s_barrier
	v_add_f32_e32 v8, v0, v1
	v_lshl_add_u64 v[4:5], v[38:39], 0, s[10:11]
	v_lshl_add_u64 v[0:1], v[4:5], 0, v[32:33]
	global_load_dwordx2 v[0:1], v[0:1], off
	v_or_b32_e32 v160, 0x20, v32
	v_mov_b32_e32 v161, v33
	v_lshl_add_u64 v[160:161], v[4:5], 0, v[160:161]
	global_load_dwordx2 v[160:161], v[160:161], off
	v_or_b32_e32 v162, 0x40, v32
	v_mov_b32_e32 v163, v33
	v_lshl_add_u64 v[162:163], v[4:5], 0, v[162:163]
	global_load_dwordx2 v[162:163], v[162:163], off
	v_or_b32_e32 v164, 0x60, v32
	v_mov_b32_e32 v165, v33
	v_lshl_add_u64 v[164:165], v[4:5], 0, v[164:165]
	global_load_dwordx2 v[164:165], v[164:165], off
	v_or_b32_e32 v166, 0x80, v32
	v_mov_b32_e32 v167, v33
	v_lshl_add_u64 v[166:167], v[4:5], 0, v[166:167]
	global_load_dwordx2 v[166:167], v[166:167], off
	v_or_b32_e32 v168, 0xa0, v32
	v_mov_b32_e32 v169, v33
	v_lshl_add_u64 v[168:169], v[4:5], 0, v[168:169]
	global_load_dwordx2 v[168:169], v[168:169], off
	v_or_b32_e32 v170, 0xc0, v32
	v_mov_b32_e32 v171, v33
	v_lshl_add_u64 v[170:171], v[4:5], 0, v[170:171]
	global_load_dwordx2 v[170:171], v[170:171], off
	v_or_b32_e32 v172, 0xe0, v32
	v_mov_b32_e32 v173, v33
	v_lshl_add_u64 v[172:173], v[4:5], 0, v[172:173]
	global_load_dwordx2 v[172:173], v[172:173], off
	v_or_b32_e32 v174, 0x100, v32
	v_mov_b32_e32 v175, v33
	v_lshl_add_u64 v[174:175], v[4:5], 0, v[174:175]
	global_load_dwordx2 v[174:175], v[174:175], off
	v_or_b32_e32 v176, 0x120, v32
	v_mov_b32_e32 v177, v33
	v_lshl_add_u64 v[176:177], v[4:5], 0, v[176:177]
	global_load_dwordx2 v[176:177], v[176:177], off
	v_or_b32_e32 v178, 0x140, v32
	v_mov_b32_e32 v179, v33
	v_lshl_add_u64 v[178:179], v[4:5], 0, v[178:179]
	global_load_dwordx2 v[178:179], v[178:179], off
	v_or_b32_e32 v180, 0x160, v32
	v_mov_b32_e32 v181, v33
	v_lshl_add_u64 v[180:181], v[4:5], 0, v[180:181]
	global_load_dwordx2 v[180:181], v[180:181], off
	v_or_b32_e32 v182, 0x180, v32
	v_mov_b32_e32 v183, v33
	v_lshl_add_u64 v[182:183], v[4:5], 0, v[182:183]
	global_load_dwordx2 v[182:183], v[182:183], off
	v_or_b32_e32 v184, 0x1a0, v32
	v_mov_b32_e32 v185, v33
	v_lshl_add_u64 v[184:185], v[4:5], 0, v[184:185]
	global_load_dwordx2 v[184:185], v[184:185], off
	v_or_b32_e32 v186, 0x1c0, v32
	v_mov_b32_e32 v187, v33
	v_lshl_add_u64 v[186:187], v[4:5], 0, v[186:187]
	global_load_dwordx2 v[186:187], v[186:187], off
	v_or_b32_e32 v188, 0x1e0, v32
	v_mov_b32_e32 v189, v33
	v_lshl_add_u64 v[188:189], v[4:5], 0, v[188:189]
	global_load_dwordx2 v[188:189], v[188:189], off
	v_or_b32_e32 v190, 0x200, v32
	v_mov_b32_e32 v191, v33
	v_lshl_add_u64 v[190:191], v[4:5], 0, v[190:191]
	global_load_dwordx2 v[190:191], v[190:191], off
	v_or_b32_e32 v192, 0x220, v32
	v_mov_b32_e32 v193, v33
	v_lshl_add_u64 v[192:193], v[4:5], 0, v[192:193]
	global_load_dwordx2 v[192:193], v[192:193], off
	v_or_b32_e32 v194, 0x240, v32
	v_mov_b32_e32 v195, v33
	v_lshl_add_u64 v[194:195], v[4:5], 0, v[194:195]
	global_load_dwordx2 v[194:195], v[194:195], off
	v_or_b32_e32 v196, 0x260, v32
	v_mov_b32_e32 v197, v33
	v_lshl_add_u64 v[196:197], v[4:5], 0, v[196:197]
	global_load_dwordx2 v[196:197], v[196:197], off
	v_or_b32_e32 v198, 0x280, v32
	v_mov_b32_e32 v199, v33
	v_lshl_add_u64 v[198:199], v[4:5], 0, v[198:199]
	global_load_dwordx2 v[198:199], v[198:199], off
	v_or_b32_e32 v200, 0x2a0, v32
	v_mov_b32_e32 v201, v33
	v_lshl_add_u64 v[200:201], v[4:5], 0, v[200:201]
	global_load_dwordx2 v[200:201], v[200:201], off
	v_or_b32_e32 v202, 0x2c0, v32
	v_mov_b32_e32 v203, v33
	v_lshl_add_u64 v[202:203], v[4:5], 0, v[202:203]
	global_load_dwordx2 v[202:203], v[202:203], off
	v_or_b32_e32 v204, 0x2e0, v32
	v_mov_b32_e32 v205, v33
	v_lshl_add_u64 v[204:205], v[4:5], 0, v[204:205]
	global_load_dwordx2 v[204:205], v[204:205], off
	v_or_b32_e32 v206, 0x300, v32
	v_mov_b32_e32 v207, v33
	v_lshl_add_u64 v[206:207], v[4:5], 0, v[206:207]
	global_load_dwordx2 v[206:207], v[206:207], off
	v_or_b32_e32 v208, 0x320, v32
	v_mov_b32_e32 v209, v33
	v_lshl_add_u64 v[208:209], v[4:5], 0, v[208:209]
	global_load_dwordx2 v[208:209], v[208:209], off
	v_or_b32_e32 v210, 0x340, v32
	v_mov_b32_e32 v211, v33
	v_lshl_add_u64 v[210:211], v[4:5], 0, v[210:211]
	global_load_dwordx2 v[210:211], v[210:211], off
	v_or_b32_e32 v212, 0x360, v32
	v_mov_b32_e32 v213, v33
	v_lshl_add_u64 v[212:213], v[4:5], 0, v[212:213]
	global_load_dwordx2 v[212:213], v[212:213], off
	v_or_b32_e32 v214, 0x380, v32
	v_mov_b32_e32 v215, v33
	v_lshl_add_u64 v[214:215], v[4:5], 0, v[214:215]
	global_load_dwordx2 v[214:215], v[214:215], off
	v_or_b32_e32 v216, 0x3a0, v32
	v_mov_b32_e32 v217, v33
	v_lshl_add_u64 v[216:217], v[4:5], 0, v[216:217]
	global_load_dwordx2 v[216:217], v[216:217], off
	v_or_b32_e32 v218, 0x3c0, v32
	v_mov_b32_e32 v219, v33
	v_lshl_add_u64 v[218:219], v[4:5], 0, v[218:219]
	global_load_dwordx2 v[218:219], v[218:219], off
	v_or_b32_e32 v220, 0x3e0, v32
	v_mov_b32_e32 v221, v33
	v_lshl_add_u64 v[220:221], v[4:5], 0, v[220:221]
	global_load_dwordx2 v[220:221], v[220:221], off
	v_lshlrev_b64 v[2:3], 11, v[36:37]
	v_lshl_add_u64 v[18:19], s[86:87], 0, v[2:3]
	v_lshlrev_b32_e32 v9, 16, v150
	v_and_b32_e32 v11, 0xffff0000, v150
	s_waitcnt lgkmcnt(0)
	v_mov_b32_e32 v10, v8
	s_nop 1
	v_permlane16_swap_b32_e32 v8, v10
	v_add_f32_e32 v8, v8, v10
	v_mov_b32_e32 v10, v8
	s_nop 1
	v_permlane32_swap_b32_e32 v8, v10
	v_add_f32_e32 v8, v8, v10
	v_fmamk_f32 v8, v8, 0x3b000000, v124
	v_mul_f32_e32 v10, 0x4b800000, v8
	v_cmp_gt_f32_e32 vcc, s3, v8
	v_lshlrev_b32_e32 v13, 16, v148
	v_and_b32_e32 v15, 0xffff0000, v148
	v_cndmask_b32_e32 v8, v8, v10, vcc
	v_rsq_f32_e32 v8, v8
	v_or_b32_e32 v16, 32, v32
	v_mov_b32_e32 v17, v33
	v_lshl_add_u64 v[16:17], v[4:5], 0, v[16:17]
	v_mul_f32_e32 v2, 0x45800000, v8
	v_cndmask_b32_e32 v3, v8, v2, vcc
	v_mov_b32_e32 v24, v3
	v_mov_b32_e32 v26, v3
	v_mov_b32_e32 v30, v3
	s_add_i32 s54, s54, s52
	s_add_u32 s4, s4, s6
	s_addc_u32 s5, s5, s7
	s_cmpk_gt_i32 s54, 0xff
	s_waitcnt vmcnt(0)
	v_lshlrev_b32_e32 v8, 16, v0
	v_and_b32_e32 v10, 0xffff0000, v0
	v_mul_f32_e32 v0, 0xbfb8aa3b, v8
	v_exp_f32_e32 v0, v0
	v_lshlrev_b32_e32 v12, 16, v1
	v_and_b32_e32 v14, 0xffff0000, v1
	v_mul_f32_e32 v1, 0xbfb8aa3b, v10
	v_exp_f32_e32 v1, v1
	v_add_f32_e32 v0, 1.0, v0
	v_rcp_f32_e32 v2, v0
	v_mul_f32_e32 v0, 0xbfb8aa3b, v12
	v_exp_f32_e32 v0, v0
	v_add_f32_e32 v1, 1.0, v1
	v_pk_mul_f32 v[8:9], v[2:3], v[8:9]
	v_rcp_f32_e32 v2, v1
	v_mul_f32_e32 v1, 0xbfb8aa3b, v14
	v_exp_f32_e32 v22, v1
	v_add_f32_e32 v0, 1.0, v0
	v_pk_mul_f32 v[10:11], v[2:3], v[10:11]
	v_rcp_f32_e32 v2, v0
	v_lshl_add_u64 v[0:1], v[18:19], 0, v[32:33]
	v_add_f32_e32 v18, 1.0, v22
	v_mul_f32_e32 v19, v8, v9
	v_pk_mul_f32 v[8:9], v[2:3], v[12:13]
	v_rcp_f32_e32 v2, v18
	v_mul_f32_e32 v10, v10, v11
	v_mul_f32_e32 v11, v8, v9
	v_cvt_pk_bf16_f32 v10, v19, v10
	v_pk_mul_f32 v[8:9], v[2:3], v[14:15]
	v_and_b32_e32 v12, 0xffff0000, v145
	v_mul_f32_e32 v2, v8, v9
	v_cvt_pk_bf16_f32 v11, v11, v2
	global_store_dwordx2 v[0:1], v[10:11], off offset:1024
	v_mov_b64_e32 v[8:9], v[160:161]
	v_lshlrev_b32_e32 v10, 16, v145
	v_lshlrev_b32_e32 v14, 16, v142
	v_mov_b32_e32 v22, v3
	v_and_b32_e32 v16, 0xffff0000, v142
	v_or_b32_e32 v18, 64, v32
	v_mov_b32_e32 v19, v33
	v_lshl_add_u64 v[18:19], v[4:5], 0, v[18:19]
	v_lshlrev_b32_e32 v11, 16, v8
	v_and_b32_e32 v13, 0xffff0000, v8
	v_lshlrev_b32_e32 v15, 16, v9
	v_and_b32_e32 v17, 0xffff0000, v9
	v_mul_f32_e32 v2, 0xbfb8aa3b, v11
	v_mul_f32_e32 v8, 0xbfb8aa3b, v13
	v_mul_f32_e32 v9, 0xbfb8aa3b, v15
	v_mul_f32_e32 v23, 0xbfb8aa3b, v17
	v_exp_f32_e32 v2, v2
	v_exp_f32_e32 v8, v8
	v_exp_f32_e32 v9, v9
	v_exp_f32_e32 v23, v23
	v_add_f32_e32 v2, 1.0, v2
	v_add_f32_e32 v8, 1.0, v8
	v_add_f32_e32 v9, 1.0, v9
	v_add_f32_e32 v28, 1.0, v23
	v_rcp_f32_e32 v23, v2
	v_rcp_f32_e32 v25, v8
	v_rcp_f32_e32 v27, v9
	v_rcp_f32_e32 v31, v28
	v_pk_mul_f32 v[8:9], v[22:23], v[10:11]
	v_pk_mul_f32 v[10:11], v[24:25], v[12:13]
	v_pk_mul_f32 v[12:13], v[26:27], v[14:15]
	v_pk_mul_f32 v[14:15], v[30:31], v[16:17]
	v_mul_f32_e32 v2, v8, v9
	v_mul_f32_e32 v8, v10, v11
	v_mul_f32_e32 v9, v12, v13
	v_mul_f32_e32 v10, v14, v15
	v_cvt_pk_bf16_f32 v8, v2, v8
	v_cvt_pk_bf16_f32 v9, v9, v10
	global_store_dwordx2 v[0:1], v[8:9], off offset:1056
	v_mov_b64_e32 v[8:9], v[162:163]
	v_lshlrev_b32_e32 v10, 16, v139
	v_and_b32_e32 v12, 0xffff0000, v139
	v_lshlrev_b32_e32 v14, 16, v137
	v_and_b32_e32 v16, 0xffff0000, v137
	v_or_b32_e32 v18, 0x60, v32
	v_mov_b32_e32 v19, v33
	v_lshl_add_u64 v[18:19], v[4:5], 0, v[18:19]
	v_lshlrev_b32_e32 v11, 16, v8
	v_and_b32_e32 v13, 0xffff0000, v8
	v_lshlrev_b32_e32 v15, 16, v9
	v_and_b32_e32 v17, 0xffff0000, v9
	v_mul_f32_e32 v2, 0xbfb8aa3b, v11
	v_mul_f32_e32 v8, 0xbfb8aa3b, v13
	v_mul_f32_e32 v9, 0xbfb8aa3b, v15
	v_mul_f32_e32 v23, 0xbfb8aa3b, v17
	v_exp_f32_e32 v2, v2
	v_exp_f32_e32 v8, v8
	v_exp_f32_e32 v9, v9
	v_exp_f32_e32 v23, v23
	v_add_f32_e32 v2, 1.0, v2
	v_add_f32_e32 v8, 1.0, v8
	v_add_f32_e32 v9, 1.0, v9
	v_add_f32_e32 v28, 1.0, v23
	v_rcp_f32_e32 v23, v2
	v_rcp_f32_e32 v25, v8
	v_rcp_f32_e32 v27, v9
	v_rcp_f32_e32 v31, v28
	v_pk_mul_f32 v[8:9], v[22:23], v[10:11]
	v_pk_mul_f32 v[10:11], v[24:25], v[12:13]
	v_pk_mul_f32 v[12:13], v[26:27], v[14:15]
	v_pk_mul_f32 v[14:15], v[30:31], v[16:17]
	v_mul_f32_e32 v2, v8, v9
	v_mul_f32_e32 v8, v10, v11
	v_mul_f32_e32 v9, v12, v13
	v_mul_f32_e32 v10, v14, v15
	v_cvt_pk_bf16_f32 v8, v2, v8
	v_cvt_pk_bf16_f32 v9, v9, v10
	global_store_dwordx2 v[0:1], v[8:9], off offset:1088
	v_mov_b64_e32 v[8:9], v[164:165]
	v_lshlrev_b32_e32 v10, 16, v136
	v_and_b32_e32 v12, 0xffff0000, v136
	v_lshlrev_b32_e32 v14, 16, v133
	v_and_b32_e32 v16, 0xffff0000, v133
	v_or_b32_e32 v18, 0x80, v32
	v_mov_b32_e32 v19, v33
	v_lshl_add_u64 v[18:19], v[4:5], 0, v[18:19]
	v_lshlrev_b32_e32 v11, 16, v8
	v_and_b32_e32 v13, 0xffff0000, v8
	v_lshlrev_b32_e32 v15, 16, v9
	v_and_b32_e32 v17, 0xffff0000, v9
	v_mul_f32_e32 v2, 0xbfb8aa3b, v11
	v_mul_f32_e32 v8, 0xbfb8aa3b, v13
	v_mul_f32_e32 v9, 0xbfb8aa3b, v15
	v_mul_f32_e32 v23, 0xbfb8aa3b, v17
	v_exp_f32_e32 v2, v2
	v_exp_f32_e32 v8, v8
	v_exp_f32_e32 v9, v9
	v_exp_f32_e32 v23, v23
	v_add_f32_e32 v2, 1.0, v2
	v_add_f32_e32 v8, 1.0, v8
	v_add_f32_e32 v9, 1.0, v9
	v_add_f32_e32 v28, 1.0, v23
	v_rcp_f32_e32 v23, v2
	v_rcp_f32_e32 v25, v8
	v_rcp_f32_e32 v27, v9
	v_rcp_f32_e32 v31, v28
	v_pk_mul_f32 v[8:9], v[22:23], v[10:11]
	v_pk_mul_f32 v[10:11], v[24:25], v[12:13]
	v_pk_mul_f32 v[12:13], v[26:27], v[14:15]
	v_pk_mul_f32 v[14:15], v[30:31], v[16:17]
	v_mul_f32_e32 v2, v8, v9
	v_mul_f32_e32 v8, v10, v11
	v_mul_f32_e32 v9, v12, v13
	v_mul_f32_e32 v10, v14, v15
	v_cvt_pk_bf16_f32 v8, v2, v8
	v_cvt_pk_bf16_f32 v9, v9, v10
	global_store_dwordx2 v[0:1], v[8:9], off offset:1120
	v_mov_b64_e32 v[8:9], v[166:167]
	v_lshlrev_b32_e32 v10, 16, v134
	v_and_b32_e32 v12, 0xffff0000, v134
	v_lshlrev_b32_e32 v14, 16, v132
	v_and_b32_e32 v16, 0xffff0000, v132
	v_or_b32_e32 v18, 0xa0, v32
	v_mov_b32_e32 v19, v33
	v_lshl_add_u64 v[18:19], v[4:5], 0, v[18:19]
	v_lshlrev_b32_e32 v11, 16, v8
	v_and_b32_e32 v13, 0xffff0000, v8
	v_lshlrev_b32_e32 v15, 16, v9
	v_and_b32_e32 v17, 0xffff0000, v9
	v_mul_f32_e32 v2, 0xbfb8aa3b, v11
	v_mul_f32_e32 v8, 0xbfb8aa3b, v13
	v_mul_f32_e32 v9, 0xbfb8aa3b, v15
	v_mul_f32_e32 v23, 0xbfb8aa3b, v17
	v_exp_f32_e32 v2, v2
	v_exp_f32_e32 v8, v8
	v_exp_f32_e32 v9, v9
	v_exp_f32_e32 v23, v23
	v_add_f32_e32 v2, 1.0, v2
	v_add_f32_e32 v8, 1.0, v8
	v_add_f32_e32 v9, 1.0, v9
	v_add_f32_e32 v28, 1.0, v23
	v_rcp_f32_e32 v23, v2
	v_rcp_f32_e32 v25, v8
	v_rcp_f32_e32 v27, v9
	v_rcp_f32_e32 v31, v28
	v_pk_mul_f32 v[8:9], v[22:23], v[10:11]
	v_pk_mul_f32 v[10:11], v[24:25], v[12:13]
	v_pk_mul_f32 v[12:13], v[26:27], v[14:15]
	v_pk_mul_f32 v[14:15], v[30:31], v[16:17]
	v_mul_f32_e32 v2, v8, v9
	v_mul_f32_e32 v8, v10, v11
	v_mul_f32_e32 v9, v12, v13
	v_mul_f32_e32 v10, v14, v15
	v_cvt_pk_bf16_f32 v8, v2, v8
	v_cvt_pk_bf16_f32 v9, v9, v10
	global_store_dwordx2 v[0:1], v[8:9], off offset:1152
	v_mov_b64_e32 v[8:9], v[168:169]
	v_lshlrev_b32_e32 v10, 16, v130
	v_and_b32_e32 v12, 0xffff0000, v130
	v_lshlrev_b32_e32 v14, 16, v129
	v_and_b32_e32 v16, 0xffff0000, v129
	v_or_b32_e32 v18, 0xc0, v32
	v_mov_b32_e32 v19, v33
	v_lshl_add_u64 v[18:19], v[4:5], 0, v[18:19]
	v_lshlrev_b32_e32 v11, 16, v8
	v_and_b32_e32 v13, 0xffff0000, v8
	v_lshlrev_b32_e32 v15, 16, v9
	v_and_b32_e32 v17, 0xffff0000, v9
	v_mul_f32_e32 v2, 0xbfb8aa3b, v11
	v_mul_f32_e32 v8, 0xbfb8aa3b, v13
	v_mul_f32_e32 v9, 0xbfb8aa3b, v15
	v_mul_f32_e32 v23, 0xbfb8aa3b, v17
	v_exp_f32_e32 v2, v2
	v_exp_f32_e32 v8, v8
	v_exp_f32_e32 v9, v9
	v_exp_f32_e32 v23, v23
	v_add_f32_e32 v2, 1.0, v2
	v_add_f32_e32 v8, 1.0, v8
	v_add_f32_e32 v9, 1.0, v9
	v_add_f32_e32 v28, 1.0, v23
	v_rcp_f32_e32 v23, v2
	v_rcp_f32_e32 v25, v8
	v_rcp_f32_e32 v27, v9
	v_rcp_f32_e32 v31, v28
	v_pk_mul_f32 v[8:9], v[22:23], v[10:11]
	v_pk_mul_f32 v[10:11], v[24:25], v[12:13]
	v_pk_mul_f32 v[12:13], v[26:27], v[14:15]
	v_pk_mul_f32 v[14:15], v[30:31], v[16:17]
	v_mul_f32_e32 v2, v8, v9
	v_mul_f32_e32 v8, v10, v11
	v_mul_f32_e32 v9, v12, v13
	v_mul_f32_e32 v10, v14, v15
	v_cvt_pk_bf16_f32 v8, v2, v8
	v_cvt_pk_bf16_f32 v9, v9, v10
	global_store_dwordx2 v[0:1], v[8:9], off offset:1184
	v_mov_b64_e32 v[8:9], v[170:171]
	v_lshlrev_b32_e32 v10, 16, v128
	v_and_b32_e32 v12, 0xffff0000, v128
	v_lshlrev_b32_e32 v14, 16, v127
	v_and_b32_e32 v16, 0xffff0000, v127
	v_or_b32_e32 v18, 0xe0, v32
	v_mov_b32_e32 v19, v33
	v_lshl_add_u64 v[18:19], v[4:5], 0, v[18:19]
	v_lshlrev_b32_e32 v11, 16, v8
	v_and_b32_e32 v13, 0xffff0000, v8
	v_lshlrev_b32_e32 v15, 16, v9
	v_and_b32_e32 v17, 0xffff0000, v9
	v_mul_f32_e32 v2, 0xbfb8aa3b, v11
	v_mul_f32_e32 v8, 0xbfb8aa3b, v13
	v_mul_f32_e32 v9, 0xbfb8aa3b, v15
	v_mul_f32_e32 v23, 0xbfb8aa3b, v17
	v_exp_f32_e32 v2, v2
	v_exp_f32_e32 v8, v8
	v_exp_f32_e32 v9, v9
	v_exp_f32_e32 v23, v23
	v_add_f32_e32 v2, 1.0, v2
	v_add_f32_e32 v8, 1.0, v8
	v_add_f32_e32 v9, 1.0, v9
	v_add_f32_e32 v28, 1.0, v23
	v_rcp_f32_e32 v23, v2
	v_rcp_f32_e32 v25, v8
	v_rcp_f32_e32 v27, v9
	v_rcp_f32_e32 v31, v28
	v_pk_mul_f32 v[8:9], v[22:23], v[10:11]
	v_pk_mul_f32 v[10:11], v[24:25], v[12:13]
	v_pk_mul_f32 v[12:13], v[26:27], v[14:15]
	v_pk_mul_f32 v[14:15], v[30:31], v[16:17]
	v_mul_f32_e32 v2, v8, v9
	v_mul_f32_e32 v8, v10, v11
	v_mul_f32_e32 v9, v12, v13
	v_mul_f32_e32 v10, v14, v15
	v_cvt_pk_bf16_f32 v8, v2, v8
	v_cvt_pk_bf16_f32 v9, v9, v10
	global_store_dwordx2 v[0:1], v[8:9], off offset:1216
	v_mov_b64_e32 v[8:9], v[172:173]
	v_lshlrev_b32_e32 v10, 16, v126
	v_and_b32_e32 v12, 0xffff0000, v126
	v_lshlrev_b32_e32 v14, 16, v125
	v_and_b32_e32 v16, 0xffff0000, v125
	v_or_b32_e32 v18, 0x100, v32
	v_mov_b32_e32 v19, v33
	v_lshl_add_u64 v[18:19], v[4:5], 0, v[18:19]
	v_lshlrev_b32_e32 v11, 16, v8
	v_and_b32_e32 v13, 0xffff0000, v8
	v_lshlrev_b32_e32 v15, 16, v9
	v_and_b32_e32 v17, 0xffff0000, v9
	v_mul_f32_e32 v2, 0xbfb8aa3b, v11
	v_mul_f32_e32 v8, 0xbfb8aa3b, v13
	v_mul_f32_e32 v9, 0xbfb8aa3b, v15
	v_mul_f32_e32 v23, 0xbfb8aa3b, v17
	v_exp_f32_e32 v2, v2
	v_exp_f32_e32 v8, v8
	v_exp_f32_e32 v9, v9
	v_exp_f32_e32 v23, v23
	v_add_f32_e32 v2, 1.0, v2
	v_add_f32_e32 v8, 1.0, v8
	v_add_f32_e32 v9, 1.0, v9
	v_add_f32_e32 v28, 1.0, v23
	v_rcp_f32_e32 v23, v2
	v_rcp_f32_e32 v25, v8
	v_rcp_f32_e32 v27, v9
	v_rcp_f32_e32 v31, v28
	v_pk_mul_f32 v[8:9], v[22:23], v[10:11]
	v_pk_mul_f32 v[10:11], v[24:25], v[12:13]
	v_pk_mul_f32 v[12:13], v[26:27], v[14:15]
	v_pk_mul_f32 v[14:15], v[30:31], v[16:17]
	v_mul_f32_e32 v2, v8, v9
	v_mul_f32_e32 v8, v10, v11
	v_mul_f32_e32 v9, v12, v13
	v_mul_f32_e32 v10, v14, v15
	v_cvt_pk_bf16_f32 v8, v2, v8
	v_cvt_pk_bf16_f32 v9, v9, v10
	global_store_dwordx2 v[0:1], v[8:9], off offset:1248
	v_mov_b64_e32 v[8:9], v[174:175]
	v_lshlrev_b32_e32 v10, 16, v156
	v_and_b32_e32 v12, 0xffff0000, v156
	v_lshlrev_b32_e32 v14, 16, v154
	v_and_b32_e32 v16, 0xffff0000, v154
	v_or_b32_e32 v18, 0x120, v32
	v_mov_b32_e32 v19, v33
	v_lshl_add_u64 v[18:19], v[4:5], 0, v[18:19]
	v_lshlrev_b32_e32 v11, 16, v8
	v_and_b32_e32 v13, 0xffff0000, v8
	v_lshlrev_b32_e32 v15, 16, v9
	v_and_b32_e32 v17, 0xffff0000, v9
	v_mul_f32_e32 v2, 0xbfb8aa3b, v11
	v_mul_f32_e32 v8, 0xbfb8aa3b, v13
	v_mul_f32_e32 v9, 0xbfb8aa3b, v15
	v_mul_f32_e32 v23, 0xbfb8aa3b, v17
	v_exp_f32_e32 v2, v2
	v_exp_f32_e32 v8, v8
	v_exp_f32_e32 v9, v9
	v_exp_f32_e32 v23, v23
	v_add_f32_e32 v2, 1.0, v2
	v_add_f32_e32 v8, 1.0, v8
	v_add_f32_e32 v9, 1.0, v9
	v_add_f32_e32 v28, 1.0, v23
	v_rcp_f32_e32 v23, v2
	v_rcp_f32_e32 v25, v8
	v_rcp_f32_e32 v27, v9
	v_rcp_f32_e32 v31, v28
	v_pk_mul_f32 v[8:9], v[22:23], v[10:11]
	v_pk_mul_f32 v[10:11], v[24:25], v[12:13]
	v_pk_mul_f32 v[12:13], v[26:27], v[14:15]
	v_pk_mul_f32 v[14:15], v[30:31], v[16:17]
	v_mul_f32_e32 v2, v8, v9
	v_mul_f32_e32 v8, v10, v11
	v_mul_f32_e32 v9, v12, v13
	v_mul_f32_e32 v10, v14, v15
	v_cvt_pk_bf16_f32 v8, v2, v8
	v_cvt_pk_bf16_f32 v9, v9, v10
	global_store_dwordx2 v[0:1], v[8:9], off offset:1280
	v_mov_b64_e32 v[8:9], v[176:177]
	v_lshlrev_b32_e32 v10, 16, v153
	v_and_b32_e32 v12, 0xffff0000, v153
	v_lshlrev_b32_e32 v14, 16, v151
	v_and_b32_e32 v16, 0xffff0000, v151
	v_or_b32_e32 v18, 0x140, v32
	v_mov_b32_e32 v19, v33
	v_lshl_add_u64 v[18:19], v[4:5], 0, v[18:19]
	v_lshlrev_b32_e32 v11, 16, v8
	v_and_b32_e32 v13, 0xffff0000, v8
	v_lshlrev_b32_e32 v15, 16, v9
	v_and_b32_e32 v17, 0xffff0000, v9
	v_mul_f32_e32 v2, 0xbfb8aa3b, v11
	v_mul_f32_e32 v8, 0xbfb8aa3b, v13
	v_mul_f32_e32 v9, 0xbfb8aa3b, v15
	v_mul_f32_e32 v23, 0xbfb8aa3b, v17
	v_exp_f32_e32 v2, v2
	v_exp_f32_e32 v8, v8
	v_exp_f32_e32 v9, v9
	v_exp_f32_e32 v23, v23
	v_add_f32_e32 v2, 1.0, v2
	v_add_f32_e32 v8, 1.0, v8
	v_add_f32_e32 v9, 1.0, v9
	v_add_f32_e32 v28, 1.0, v23
	v_rcp_f32_e32 v23, v2
	v_rcp_f32_e32 v25, v8
	v_rcp_f32_e32 v27, v9
	v_rcp_f32_e32 v31, v28
	v_pk_mul_f32 v[8:9], v[22:23], v[10:11]
	v_pk_mul_f32 v[10:11], v[24:25], v[12:13]
	v_pk_mul_f32 v[12:13], v[26:27], v[14:15]
	v_pk_mul_f32 v[14:15], v[30:31], v[16:17]
	v_mul_f32_e32 v2, v8, v9
	v_mul_f32_e32 v8, v10, v11
	v_mul_f32_e32 v9, v12, v13
	v_mul_f32_e32 v10, v14, v15
	v_cvt_pk_bf16_f32 v8, v2, v8
	v_cvt_pk_bf16_f32 v9, v9, v10
	global_store_dwordx2 v[0:1], v[8:9], off offset:1312
	v_mov_b64_e32 v[8:9], v[178:179]
	v_lshlrev_b32_e32 v10, 16, v149
	v_and_b32_e32 v12, 0xffff0000, v149
	v_lshlrev_b32_e32 v14, 16, v147
	v_and_b32_e32 v16, 0xffff0000, v147
	v_or_b32_e32 v18, 0x160, v32
	v_mov_b32_e32 v19, v33
	v_lshl_add_u64 v[18:19], v[4:5], 0, v[18:19]
	v_lshlrev_b32_e32 v11, 16, v8
	v_and_b32_e32 v13, 0xffff0000, v8
	v_lshlrev_b32_e32 v15, 16, v9
	v_and_b32_e32 v17, 0xffff0000, v9
	v_mul_f32_e32 v2, 0xbfb8aa3b, v11
	v_mul_f32_e32 v8, 0xbfb8aa3b, v13
	v_mul_f32_e32 v9, 0xbfb8aa3b, v15
	v_mul_f32_e32 v23, 0xbfb8aa3b, v17
	v_exp_f32_e32 v2, v2
	v_exp_f32_e32 v8, v8
	v_exp_f32_e32 v9, v9
	v_exp_f32_e32 v23, v23
	v_add_f32_e32 v2, 1.0, v2
	v_add_f32_e32 v8, 1.0, v8
	v_add_f32_e32 v9, 1.0, v9
	v_add_f32_e32 v28, 1.0, v23
	v_rcp_f32_e32 v23, v2
	v_rcp_f32_e32 v25, v8
	v_rcp_f32_e32 v27, v9
	v_rcp_f32_e32 v31, v28
	v_pk_mul_f32 v[8:9], v[22:23], v[10:11]
	v_pk_mul_f32 v[10:11], v[24:25], v[12:13]
	v_pk_mul_f32 v[12:13], v[26:27], v[14:15]
	v_pk_mul_f32 v[14:15], v[30:31], v[16:17]
	v_mul_f32_e32 v2, v8, v9
	v_mul_f32_e32 v8, v10, v11
	v_mul_f32_e32 v9, v12, v13
	v_mul_f32_e32 v10, v14, v15
	v_cvt_pk_bf16_f32 v8, v2, v8
	v_cvt_pk_bf16_f32 v9, v9, v10
	global_store_dwordx2 v[0:1], v[8:9], off offset:1344
	v_mov_b64_e32 v[8:9], v[180:181]
	v_lshlrev_b32_e32 v10, 16, v146
	v_and_b32_e32 v12, 0xffff0000, v146
	v_lshlrev_b32_e32 v14, 16, v143
	v_and_b32_e32 v16, 0xffff0000, v143
	v_or_b32_e32 v18, 0x180, v32
	v_mov_b32_e32 v19, v33
	v_lshl_add_u64 v[18:19], v[4:5], 0, v[18:19]
	v_lshlrev_b32_e32 v11, 16, v8
	v_and_b32_e32 v13, 0xffff0000, v8
	v_lshlrev_b32_e32 v15, 16, v9
	v_and_b32_e32 v17, 0xffff0000, v9
	v_mul_f32_e32 v2, 0xbfb8aa3b, v11
	v_mul_f32_e32 v8, 0xbfb8aa3b, v13
	v_mul_f32_e32 v9, 0xbfb8aa3b, v15
	v_mul_f32_e32 v23, 0xbfb8aa3b, v17
	v_exp_f32_e32 v2, v2
	v_exp_f32_e32 v8, v8
	v_exp_f32_e32 v9, v9
	v_exp_f32_e32 v23, v23
	v_add_f32_e32 v2, 1.0, v2
	v_add_f32_e32 v8, 1.0, v8
	v_add_f32_e32 v9, 1.0, v9
	v_add_f32_e32 v28, 1.0, v23
	v_rcp_f32_e32 v23, v2
	v_rcp_f32_e32 v25, v8
	v_rcp_f32_e32 v27, v9
	v_rcp_f32_e32 v31, v28
	v_pk_mul_f32 v[8:9], v[22:23], v[10:11]
	v_pk_mul_f32 v[10:11], v[24:25], v[12:13]
	v_pk_mul_f32 v[12:13], v[26:27], v[14:15]
	v_pk_mul_f32 v[14:15], v[30:31], v[16:17]
	v_mul_f32_e32 v2, v8, v9
	v_mul_f32_e32 v8, v10, v11
	v_mul_f32_e32 v9, v12, v13
	v_mul_f32_e32 v10, v14, v15
	v_cvt_pk_bf16_f32 v8, v2, v8
	v_cvt_pk_bf16_f32 v9, v9, v10
	global_store_dwordx2 v[0:1], v[8:9], off offset:1376
	v_mov_b64_e32 v[8:9], v[182:183]
	v_lshlrev_b32_e32 v10, 16, v144
	v_and_b32_e32 v12, 0xffff0000, v144
	v_lshlrev_b32_e32 v14, 16, v141
	v_and_b32_e32 v16, 0xffff0000, v141
	v_or_b32_e32 v18, 0x1a0, v32
	v_mov_b32_e32 v19, v33
	v_lshl_add_u64 v[18:19], v[4:5], 0, v[18:19]
	v_lshlrev_b32_e32 v11, 16, v8
	v_and_b32_e32 v13, 0xffff0000, v8
	v_lshlrev_b32_e32 v15, 16, v9
	v_and_b32_e32 v17, 0xffff0000, v9
	v_mul_f32_e32 v2, 0xbfb8aa3b, v11
	v_mul_f32_e32 v8, 0xbfb8aa3b, v13
	v_mul_f32_e32 v9, 0xbfb8aa3b, v15
	v_mul_f32_e32 v23, 0xbfb8aa3b, v17
	v_exp_f32_e32 v2, v2
	v_exp_f32_e32 v8, v8
	v_exp_f32_e32 v9, v9
	v_exp_f32_e32 v23, v23
	v_add_f32_e32 v2, 1.0, v2
	v_add_f32_e32 v8, 1.0, v8
	v_add_f32_e32 v9, 1.0, v9
	v_add_f32_e32 v28, 1.0, v23
	v_rcp_f32_e32 v23, v2
	v_rcp_f32_e32 v25, v8
	v_rcp_f32_e32 v27, v9
	v_rcp_f32_e32 v31, v28
	v_pk_mul_f32 v[8:9], v[22:23], v[10:11]
	v_pk_mul_f32 v[10:11], v[24:25], v[12:13]
	v_pk_mul_f32 v[12:13], v[26:27], v[14:15]
	v_pk_mul_f32 v[14:15], v[30:31], v[16:17]
	v_mul_f32_e32 v2, v8, v9
	v_mul_f32_e32 v8, v10, v11
	v_mul_f32_e32 v9, v12, v13
	v_mul_f32_e32 v10, v14, v15
	v_cvt_pk_bf16_f32 v8, v2, v8
	v_cvt_pk_bf16_f32 v9, v9, v10
	global_store_dwordx2 v[0:1], v[8:9], off offset:1408
	v_mov_b64_e32 v[8:9], v[184:185]
	v_lshlrev_b32_e32 v10, 16, v140
	v_and_b32_e32 v12, 0xffff0000, v140
	v_lshlrev_b32_e32 v14, 16, v138
	v_and_b32_e32 v16, 0xffff0000, v138
	v_or_b32_e32 v18, 0x1c0, v32
	v_mov_b32_e32 v19, v33
	v_lshl_add_u64 v[18:19], v[4:5], 0, v[18:19]
	v_lshlrev_b32_e32 v11, 16, v8
	v_and_b32_e32 v13, 0xffff0000, v8
	v_lshlrev_b32_e32 v15, 16, v9
	v_and_b32_e32 v17, 0xffff0000, v9
	v_mul_f32_e32 v2, 0xbfb8aa3b, v11
	v_mul_f32_e32 v8, 0xbfb8aa3b, v13
	v_mul_f32_e32 v9, 0xbfb8aa3b, v15
	v_mul_f32_e32 v23, 0xbfb8aa3b, v17
	v_exp_f32_e32 v2, v2
	v_exp_f32_e32 v8, v8
	v_exp_f32_e32 v9, v9
	v_exp_f32_e32 v23, v23
	v_add_f32_e32 v2, 1.0, v2
	v_add_f32_e32 v8, 1.0, v8
	v_add_f32_e32 v9, 1.0, v9
	v_add_f32_e32 v28, 1.0, v23
	v_rcp_f32_e32 v23, v2
	v_rcp_f32_e32 v25, v8
	v_rcp_f32_e32 v27, v9
	v_rcp_f32_e32 v31, v28
	v_pk_mul_f32 v[8:9], v[22:23], v[10:11]
	v_pk_mul_f32 v[10:11], v[24:25], v[12:13]
	v_pk_mul_f32 v[12:13], v[26:27], v[14:15]
	v_pk_mul_f32 v[14:15], v[30:31], v[16:17]
	v_mul_f32_e32 v2, v8, v9
	v_mul_f32_e32 v8, v10, v11
	v_mul_f32_e32 v9, v12, v13
	v_mul_f32_e32 v10, v14, v15
	v_cvt_pk_bf16_f32 v8, v2, v8
	v_cvt_pk_bf16_f32 v9, v9, v10
	global_store_dwordx2 v[0:1], v[8:9], off offset:1440
	v_mov_b64_e32 v[8:9], v[186:187]
	v_lshlrev_b32_e32 v10, 16, v135
	v_and_b32_e32 v12, 0xffff0000, v135
	v_lshlrev_b32_e32 v14, 16, v131
	v_and_b32_e32 v16, 0xffff0000, v131
	v_or_b32_e32 v18, 0x1e0, v32
	v_mov_b32_e32 v19, v33
	v_lshl_add_u64 v[18:19], v[4:5], 0, v[18:19]
	v_lshlrev_b32_e32 v11, 16, v8
	v_and_b32_e32 v13, 0xffff0000, v8
	v_lshlrev_b32_e32 v15, 16, v9
	v_and_b32_e32 v17, 0xffff0000, v9
	v_mul_f32_e32 v2, 0xbfb8aa3b, v11
	v_mul_f32_e32 v8, 0xbfb8aa3b, v13
	v_mul_f32_e32 v9, 0xbfb8aa3b, v15
	v_mul_f32_e32 v23, 0xbfb8aa3b, v17
	v_exp_f32_e32 v2, v2
	v_exp_f32_e32 v8, v8
	v_exp_f32_e32 v9, v9
	v_exp_f32_e32 v23, v23
	v_add_f32_e32 v2, 1.0, v2
	v_add_f32_e32 v8, 1.0, v8
	v_add_f32_e32 v9, 1.0, v9
	v_add_f32_e32 v28, 1.0, v23
	v_rcp_f32_e32 v23, v2
	v_rcp_f32_e32 v25, v8
	v_rcp_f32_e32 v27, v9
	v_rcp_f32_e32 v31, v28
	v_pk_mul_f32 v[8:9], v[22:23], v[10:11]
	v_pk_mul_f32 v[10:11], v[24:25], v[12:13]
	v_pk_mul_f32 v[12:13], v[26:27], v[14:15]
	v_pk_mul_f32 v[14:15], v[30:31], v[16:17]
	v_mul_f32_e32 v2, v8, v9
	v_mul_f32_e32 v8, v10, v11
	v_mul_f32_e32 v9, v12, v13
	v_mul_f32_e32 v10, v14, v15
	v_cvt_pk_bf16_f32 v8, v2, v8
	v_cvt_pk_bf16_f32 v9, v9, v10
	global_store_dwordx2 v[0:1], v[8:9], off offset:1472
	v_mov_b64_e32 v[8:9], v[188:189]
	v_lshlrev_b32_e32 v10, 16, v122
	v_and_b32_e32 v12, 0xffff0000, v122
	v_lshlrev_b32_e32 v14, 16, v120
	v_and_b32_e32 v16, 0xffff0000, v120
	v_or_b32_e32 v18, 0x200, v32
	v_mov_b32_e32 v19, v33
	v_lshl_add_u64 v[18:19], v[4:5], 0, v[18:19]
	v_lshlrev_b32_e32 v11, 16, v8
	v_and_b32_e32 v13, 0xffff0000, v8
	v_lshlrev_b32_e32 v15, 16, v9
	v_and_b32_e32 v17, 0xffff0000, v9
	v_mul_f32_e32 v2, 0xbfb8aa3b, v11
	v_mul_f32_e32 v8, 0xbfb8aa3b, v13
	v_mul_f32_e32 v9, 0xbfb8aa3b, v15
	v_mul_f32_e32 v23, 0xbfb8aa3b, v17
	v_exp_f32_e32 v2, v2
	v_exp_f32_e32 v8, v8
	v_exp_f32_e32 v9, v9
	v_exp_f32_e32 v23, v23
	v_add_f32_e32 v2, 1.0, v2
	v_add_f32_e32 v8, 1.0, v8
	v_add_f32_e32 v9, 1.0, v9
	v_add_f32_e32 v28, 1.0, v23
	v_rcp_f32_e32 v23, v2
	v_rcp_f32_e32 v25, v8
	v_rcp_f32_e32 v27, v9
	v_rcp_f32_e32 v31, v28
	v_pk_mul_f32 v[8:9], v[22:23], v[10:11]
	v_pk_mul_f32 v[10:11], v[24:25], v[12:13]
	v_pk_mul_f32 v[12:13], v[26:27], v[14:15]
	v_pk_mul_f32 v[14:15], v[30:31], v[16:17]
	v_mul_f32_e32 v2, v8, v9
	v_mul_f32_e32 v8, v10, v11
	v_mul_f32_e32 v9, v12, v13
	v_mul_f32_e32 v10, v14, v15
	v_cvt_pk_bf16_f32 v8, v2, v8
	v_cvt_pk_bf16_f32 v9, v9, v10
	global_store_dwordx2 v[0:1], v[8:9], off offset:1504
	v_mov_b64_e32 v[8:9], v[190:191]
	v_lshlrev_b32_e32 v10, 16, v159
	v_and_b32_e32 v12, 0xffff0000, v159
	v_lshlrev_b32_e32 v14, 16, v158
	v_and_b32_e32 v16, 0xffff0000, v158
	v_or_b32_e32 v18, 0x220, v32
	v_mov_b32_e32 v19, v33
	v_lshl_add_u64 v[18:19], v[4:5], 0, v[18:19]
	v_lshlrev_b32_e32 v11, 16, v8
	v_and_b32_e32 v13, 0xffff0000, v8
	v_lshlrev_b32_e32 v15, 16, v9
	v_and_b32_e32 v17, 0xffff0000, v9
	v_mul_f32_e32 v2, 0xbfb8aa3b, v11
	v_mul_f32_e32 v8, 0xbfb8aa3b, v13
	v_mul_f32_e32 v9, 0xbfb8aa3b, v15
	v_mul_f32_e32 v23, 0xbfb8aa3b, v17
	v_exp_f32_e32 v2, v2
	v_exp_f32_e32 v8, v8
	v_exp_f32_e32 v9, v9
	v_exp_f32_e32 v23, v23
	v_add_f32_e32 v2, 1.0, v2
	v_add_f32_e32 v8, 1.0, v8
	v_add_f32_e32 v9, 1.0, v9
	v_add_f32_e32 v28, 1.0, v23
	v_rcp_f32_e32 v23, v2
	v_rcp_f32_e32 v25, v8
	v_rcp_f32_e32 v27, v9
	v_rcp_f32_e32 v31, v28
	v_pk_mul_f32 v[8:9], v[22:23], v[10:11]
	v_pk_mul_f32 v[10:11], v[24:25], v[12:13]
	v_pk_mul_f32 v[12:13], v[26:27], v[14:15]
	v_pk_mul_f32 v[14:15], v[30:31], v[16:17]
	v_mul_f32_e32 v2, v8, v9
	v_mul_f32_e32 v8, v10, v11
	v_mul_f32_e32 v9, v12, v13
	v_mul_f32_e32 v10, v14, v15
	v_cvt_pk_bf16_f32 v8, v2, v8
	v_cvt_pk_bf16_f32 v9, v9, v10
	global_store_dwordx2 v[0:1], v[8:9], off offset:1536
	v_mov_b64_e32 v[8:9], v[192:193]
	v_lshlrev_b32_e32 v10, 16, v123
	v_and_b32_e32 v12, 0xffff0000, v123
	v_lshlrev_b32_e32 v14, 16, v121
	v_and_b32_e32 v16, 0xffff0000, v121
	v_or_b32_e32 v18, 0x240, v32
	v_mov_b32_e32 v19, v33
	v_lshl_add_u64 v[18:19], v[4:5], 0, v[18:19]
	v_lshlrev_b32_e32 v11, 16, v8
	v_and_b32_e32 v13, 0xffff0000, v8
	v_lshlrev_b32_e32 v15, 16, v9
	v_and_b32_e32 v17, 0xffff0000, v9
	v_mul_f32_e32 v2, 0xbfb8aa3b, v11
	v_mul_f32_e32 v8, 0xbfb8aa3b, v13
	v_mul_f32_e32 v9, 0xbfb8aa3b, v15
	v_mul_f32_e32 v23, 0xbfb8aa3b, v17
	v_exp_f32_e32 v2, v2
	v_exp_f32_e32 v8, v8
	v_exp_f32_e32 v9, v9
	v_exp_f32_e32 v23, v23
	v_add_f32_e32 v2, 1.0, v2
	v_add_f32_e32 v8, 1.0, v8
	v_add_f32_e32 v9, 1.0, v9
	v_add_f32_e32 v28, 1.0, v23
	v_rcp_f32_e32 v23, v2
	v_rcp_f32_e32 v25, v8
	v_rcp_f32_e32 v27, v9
	v_rcp_f32_e32 v31, v28
	v_pk_mul_f32 v[8:9], v[22:23], v[10:11]
	v_pk_mul_f32 v[10:11], v[24:25], v[12:13]
	v_pk_mul_f32 v[12:13], v[26:27], v[14:15]
	v_pk_mul_f32 v[14:15], v[30:31], v[16:17]
	v_mul_f32_e32 v2, v8, v9
	v_mul_f32_e32 v8, v10, v11
	v_mul_f32_e32 v9, v12, v13
	v_mul_f32_e32 v10, v14, v15
	v_cvt_pk_bf16_f32 v8, v2, v8
	v_cvt_pk_bf16_f32 v9, v9, v10
	global_store_dwordx2 v[0:1], v[8:9], off offset:1568
	v_mov_b64_e32 v[8:9], v[194:195]
	v_lshlrev_b32_e32 v10, 16, v119
	v_and_b32_e32 v12, 0xffff0000, v119
	v_lshlrev_b32_e32 v14, 16, v118
	v_and_b32_e32 v16, 0xffff0000, v118
	v_or_b32_e32 v18, 0x260, v32
	v_mov_b32_e32 v19, v33
	v_lshl_add_u64 v[18:19], v[4:5], 0, v[18:19]
	v_lshlrev_b32_e32 v11, 16, v8
	v_and_b32_e32 v13, 0xffff0000, v8
	v_lshlrev_b32_e32 v15, 16, v9
	v_and_b32_e32 v17, 0xffff0000, v9
	v_mul_f32_e32 v2, 0xbfb8aa3b, v11
	v_mul_f32_e32 v8, 0xbfb8aa3b, v13
	v_mul_f32_e32 v9, 0xbfb8aa3b, v15
	v_mul_f32_e32 v23, 0xbfb8aa3b, v17
	v_exp_f32_e32 v2, v2
	v_exp_f32_e32 v8, v8
	v_exp_f32_e32 v9, v9
	v_exp_f32_e32 v23, v23
	v_add_f32_e32 v2, 1.0, v2
	v_add_f32_e32 v8, 1.0, v8
	v_add_f32_e32 v9, 1.0, v9
	v_add_f32_e32 v28, 1.0, v23
	v_rcp_f32_e32 v23, v2
	v_rcp_f32_e32 v25, v8
	v_rcp_f32_e32 v27, v9
	v_rcp_f32_e32 v31, v28
	v_pk_mul_f32 v[8:9], v[22:23], v[10:11]
	v_pk_mul_f32 v[10:11], v[24:25], v[12:13]
	v_pk_mul_f32 v[12:13], v[26:27], v[14:15]
	v_pk_mul_f32 v[14:15], v[30:31], v[16:17]
	v_mul_f32_e32 v2, v8, v9
	v_mul_f32_e32 v8, v10, v11
	v_mul_f32_e32 v9, v12, v13
	v_mul_f32_e32 v10, v14, v15
	v_cvt_pk_bf16_f32 v8, v2, v8
	v_cvt_pk_bf16_f32 v9, v9, v10
	global_store_dwordx2 v[0:1], v[8:9], off offset:1600
	v_mov_b64_e32 v[8:9], v[196:197]
	v_lshlrev_b32_e32 v10, 16, v117
	v_and_b32_e32 v12, 0xffff0000, v117
	v_lshlrev_b32_e32 v14, 16, v115
	v_and_b32_e32 v16, 0xffff0000, v115
	v_or_b32_e32 v18, 0x280, v32
	v_mov_b32_e32 v19, v33
	v_lshl_add_u64 v[18:19], v[4:5], 0, v[18:19]
	v_lshlrev_b32_e32 v11, 16, v8
	v_and_b32_e32 v13, 0xffff0000, v8
	v_lshlrev_b32_e32 v15, 16, v9
	v_and_b32_e32 v17, 0xffff0000, v9
	v_mul_f32_e32 v2, 0xbfb8aa3b, v11
	v_mul_f32_e32 v8, 0xbfb8aa3b, v13
	v_mul_f32_e32 v9, 0xbfb8aa3b, v15
	v_mul_f32_e32 v23, 0xbfb8aa3b, v17
	v_exp_f32_e32 v2, v2
	v_exp_f32_e32 v8, v8
	v_exp_f32_e32 v9, v9
	v_exp_f32_e32 v23, v23
	v_add_f32_e32 v2, 1.0, v2
	v_add_f32_e32 v8, 1.0, v8
	v_add_f32_e32 v9, 1.0, v9
	v_add_f32_e32 v28, 1.0, v23
	v_rcp_f32_e32 v23, v2
	v_rcp_f32_e32 v25, v8
	v_rcp_f32_e32 v27, v9
	v_rcp_f32_e32 v31, v28
	v_pk_mul_f32 v[8:9], v[22:23], v[10:11]
	v_pk_mul_f32 v[10:11], v[24:25], v[12:13]
	v_pk_mul_f32 v[12:13], v[26:27], v[14:15]
	v_pk_mul_f32 v[14:15], v[30:31], v[16:17]
	v_mul_f32_e32 v2, v8, v9
	v_mul_f32_e32 v8, v10, v11
	v_mul_f32_e32 v9, v12, v13
	v_mul_f32_e32 v10, v14, v15
	v_cvt_pk_bf16_f32 v8, v2, v8
	v_cvt_pk_bf16_f32 v9, v9, v10
	global_store_dwordx2 v[0:1], v[8:9], off offset:1632
	v_mov_b64_e32 v[8:9], v[198:199]
	v_lshlrev_b32_e32 v10, 16, v116
	v_and_b32_e32 v12, 0xffff0000, v116
	v_lshlrev_b32_e32 v14, 16, v114
	v_and_b32_e32 v16, 0xffff0000, v114
	v_or_b32_e32 v18, 0x2a0, v32
	v_mov_b32_e32 v19, v33
	v_lshl_add_u64 v[18:19], v[4:5], 0, v[18:19]
	v_lshlrev_b32_e32 v11, 16, v8
	v_and_b32_e32 v13, 0xffff0000, v8
	v_lshlrev_b32_e32 v15, 16, v9
	v_and_b32_e32 v17, 0xffff0000, v9
	v_mul_f32_e32 v2, 0xbfb8aa3b, v11
	v_mul_f32_e32 v8, 0xbfb8aa3b, v13
	v_mul_f32_e32 v9, 0xbfb8aa3b, v15
	v_mul_f32_e32 v23, 0xbfb8aa3b, v17
	v_exp_f32_e32 v2, v2
	v_exp_f32_e32 v8, v8
	v_exp_f32_e32 v9, v9
	v_exp_f32_e32 v23, v23
	v_add_f32_e32 v2, 1.0, v2
	v_add_f32_e32 v8, 1.0, v8
	v_add_f32_e32 v9, 1.0, v9
	v_add_f32_e32 v28, 1.0, v23
	v_rcp_f32_e32 v23, v2
	v_rcp_f32_e32 v25, v8
	v_rcp_f32_e32 v27, v9
	v_rcp_f32_e32 v31, v28
	v_pk_mul_f32 v[8:9], v[22:23], v[10:11]
	v_pk_mul_f32 v[10:11], v[24:25], v[12:13]
	v_pk_mul_f32 v[12:13], v[26:27], v[14:15]
	v_pk_mul_f32 v[14:15], v[30:31], v[16:17]
	v_mul_f32_e32 v2, v8, v9
	v_mul_f32_e32 v8, v10, v11
	v_mul_f32_e32 v9, v12, v13
	v_mul_f32_e32 v10, v14, v15
	v_cvt_pk_bf16_f32 v8, v2, v8
	v_cvt_pk_bf16_f32 v9, v9, v10
	global_store_dwordx2 v[0:1], v[8:9], off offset:1664
	v_mov_b64_e32 v[8:9], v[200:201]
	v_lshlrev_b32_e32 v10, 16, v113
	v_and_b32_e32 v12, 0xffff0000, v113
	v_lshlrev_b32_e32 v14, 16, v112
	v_and_b32_e32 v16, 0xffff0000, v112
	v_or_b32_e32 v18, 0x2c0, v32
	v_mov_b32_e32 v19, v33
	v_lshl_add_u64 v[18:19], v[4:5], 0, v[18:19]
	v_lshlrev_b32_e32 v11, 16, v8
	v_and_b32_e32 v13, 0xffff0000, v8
	v_lshlrev_b32_e32 v15, 16, v9
	v_and_b32_e32 v17, 0xffff0000, v9
	v_mul_f32_e32 v2, 0xbfb8aa3b, v11
	v_mul_f32_e32 v8, 0xbfb8aa3b, v13
	v_mul_f32_e32 v9, 0xbfb8aa3b, v15
	v_mul_f32_e32 v23, 0xbfb8aa3b, v17
	v_exp_f32_e32 v2, v2
	v_exp_f32_e32 v8, v8
	v_exp_f32_e32 v9, v9
	v_exp_f32_e32 v23, v23
	v_add_f32_e32 v2, 1.0, v2
	v_add_f32_e32 v8, 1.0, v8
	v_add_f32_e32 v9, 1.0, v9
	v_add_f32_e32 v28, 1.0, v23
	v_rcp_f32_e32 v23, v2
	v_rcp_f32_e32 v25, v8
	v_rcp_f32_e32 v27, v9
	v_rcp_f32_e32 v31, v28
	v_pk_mul_f32 v[8:9], v[22:23], v[10:11]
	v_pk_mul_f32 v[10:11], v[24:25], v[12:13]
	v_pk_mul_f32 v[12:13], v[26:27], v[14:15]
	v_pk_mul_f32 v[14:15], v[30:31], v[16:17]
	v_mul_f32_e32 v2, v8, v9
	v_mul_f32_e32 v8, v10, v11
	v_mul_f32_e32 v9, v12, v13
	v_mul_f32_e32 v10, v14, v15
	v_cvt_pk_bf16_f32 v8, v2, v8
	v_cvt_pk_bf16_f32 v9, v9, v10
	global_store_dwordx2 v[0:1], v[8:9], off offset:1696
	v_mov_b64_e32 v[8:9], v[202:203]
	v_lshlrev_b32_e32 v10, 16, v111
	v_and_b32_e32 v12, 0xffff0000, v111
	v_lshlrev_b32_e32 v14, 16, v110
	v_and_b32_e32 v16, 0xffff0000, v110
	v_or_b32_e32 v18, 0x2e0, v32
	v_mov_b32_e32 v19, v33
	v_lshl_add_u64 v[18:19], v[4:5], 0, v[18:19]
	v_lshlrev_b32_e32 v11, 16, v8
	v_and_b32_e32 v13, 0xffff0000, v8
	v_lshlrev_b32_e32 v15, 16, v9
	v_and_b32_e32 v17, 0xffff0000, v9
	v_mul_f32_e32 v2, 0xbfb8aa3b, v11
	v_mul_f32_e32 v8, 0xbfb8aa3b, v13
	v_mul_f32_e32 v9, 0xbfb8aa3b, v15
	v_mul_f32_e32 v23, 0xbfb8aa3b, v17
	v_exp_f32_e32 v2, v2
	v_exp_f32_e32 v8, v8
	v_exp_f32_e32 v9, v9
	v_exp_f32_e32 v23, v23
	v_add_f32_e32 v2, 1.0, v2
	v_add_f32_e32 v8, 1.0, v8
	v_add_f32_e32 v9, 1.0, v9
	v_add_f32_e32 v28, 1.0, v23
	v_rcp_f32_e32 v23, v2
	v_rcp_f32_e32 v25, v8
	v_rcp_f32_e32 v27, v9
	v_rcp_f32_e32 v31, v28
	v_pk_mul_f32 v[8:9], v[22:23], v[10:11]
	v_pk_mul_f32 v[10:11], v[24:25], v[12:13]
	v_pk_mul_f32 v[12:13], v[26:27], v[14:15]
	v_pk_mul_f32 v[14:15], v[30:31], v[16:17]
	v_mul_f32_e32 v2, v8, v9
	v_mul_f32_e32 v8, v10, v11
	v_mul_f32_e32 v9, v12, v13
	v_mul_f32_e32 v10, v14, v15
	v_cvt_pk_bf16_f32 v8, v2, v8
	v_cvt_pk_bf16_f32 v9, v9, v10
	global_store_dwordx2 v[0:1], v[8:9], off offset:1728
	v_mov_b64_e32 v[8:9], v[204:205]
	v_lshlrev_b32_e32 v14, 16, v29
	v_and_b32_e32 v16, 0xffff0000, v29
	v_lshlrev_b32_e32 v10, 16, v106
	v_and_b32_e32 v12, 0xffff0000, v106
	v_mov_b32_e32 v28, v3
	v_or_b32_e32 v18, 0x300, v32
	v_mov_b32_e32 v19, v33
	v_lshl_add_u64 v[18:19], v[4:5], 0, v[18:19]
	v_lshlrev_b32_e32 v11, 16, v8
	v_and_b32_e32 v13, 0xffff0000, v8
	v_lshlrev_b32_e32 v15, 16, v9
	v_and_b32_e32 v17, 0xffff0000, v9
	v_mul_f32_e32 v2, 0xbfb8aa3b, v11
	v_mul_f32_e32 v8, 0xbfb8aa3b, v13
	v_mul_f32_e32 v9, 0xbfb8aa3b, v15
	v_mul_f32_e32 v23, 0xbfb8aa3b, v17
	v_exp_f32_e32 v2, v2
	v_exp_f32_e32 v8, v8
	v_exp_f32_e32 v9, v9
	v_exp_f32_e32 v23, v23
	v_add_f32_e32 v2, 1.0, v2
	v_add_f32_e32 v8, 1.0, v8
	v_add_f32_e32 v9, 1.0, v9
	v_add_f32_e32 v29, 1.0, v23
	v_rcp_f32_e32 v23, v2
	v_rcp_f32_e32 v25, v8
	v_rcp_f32_e32 v27, v9
	v_rcp_f32_e32 v29, v29
	v_pk_mul_f32 v[8:9], v[22:23], v[10:11]
	v_pk_mul_f32 v[10:11], v[24:25], v[12:13]
	v_pk_mul_f32 v[12:13], v[26:27], v[14:15]
	v_pk_mul_f32 v[14:15], v[28:29], v[16:17]
	v_mul_f32_e32 v2, v8, v9
	v_mul_f32_e32 v8, v10, v11
	v_mul_f32_e32 v9, v12, v13
	v_mul_f32_e32 v10, v14, v15
	v_cvt_pk_bf16_f32 v8, v2, v8
	v_cvt_pk_bf16_f32 v9, v9, v10
	global_store_dwordx2 v[0:1], v[8:9], off offset:1760
	v_mov_b64_e32 v[8:9], v[206:207]
	v_lshlrev_b32_e32 v10, 16, v77
	v_and_b32_e32 v12, 0xffff0000, v77
	v_lshlrev_b32_e32 v14, 16, v76
	v_and_b32_e32 v16, 0xffff0000, v76
	v_or_b32_e32 v18, 0x320, v32
	v_mov_b32_e32 v19, v33
	v_lshl_add_u64 v[18:19], v[4:5], 0, v[18:19]
	v_lshlrev_b32_e32 v11, 16, v8
	v_and_b32_e32 v13, 0xffff0000, v8
	v_lshlrev_b32_e32 v15, 16, v9
	v_and_b32_e32 v17, 0xffff0000, v9
	v_mul_f32_e32 v2, 0xbfb8aa3b, v11
	v_mul_f32_e32 v8, 0xbfb8aa3b, v13
	v_mul_f32_e32 v9, 0xbfb8aa3b, v15
	v_mul_f32_e32 v23, 0xbfb8aa3b, v17
	v_exp_f32_e32 v2, v2
	v_exp_f32_e32 v8, v8
	v_exp_f32_e32 v9, v9
	v_exp_f32_e32 v23, v23
	v_add_f32_e32 v2, 1.0, v2
	v_add_f32_e32 v8, 1.0, v8
	v_add_f32_e32 v9, 1.0, v9
	v_add_f32_e32 v29, 1.0, v23
	v_rcp_f32_e32 v23, v2
	v_rcp_f32_e32 v25, v8
	v_rcp_f32_e32 v27, v9
	v_rcp_f32_e32 v29, v29
	v_pk_mul_f32 v[8:9], v[22:23], v[10:11]
	v_pk_mul_f32 v[10:11], v[24:25], v[12:13]
	v_pk_mul_f32 v[12:13], v[26:27], v[14:15]
	v_pk_mul_f32 v[14:15], v[28:29], v[16:17]
	v_mul_f32_e32 v2, v8, v9
	v_mul_f32_e32 v8, v10, v11
	v_mul_f32_e32 v9, v12, v13
	v_mul_f32_e32 v10, v14, v15
	v_cvt_pk_bf16_f32 v8, v2, v8
	v_cvt_pk_bf16_f32 v9, v9, v10
	global_store_dwordx2 v[0:1], v[8:9], off offset:1792
	v_mov_b64_e32 v[8:9], v[208:209]
	v_lshlrev_b32_e32 v10, 16, v75
	v_and_b32_e32 v12, 0xffff0000, v75
	v_lshlrev_b32_e32 v14, 16, v74
	v_and_b32_e32 v16, 0xffff0000, v74
	v_or_b32_e32 v18, 0x340, v32
	v_mov_b32_e32 v19, v33
	v_lshl_add_u64 v[18:19], v[4:5], 0, v[18:19]
	v_lshlrev_b32_e32 v11, 16, v8
	v_and_b32_e32 v13, 0xffff0000, v8
	v_lshlrev_b32_e32 v15, 16, v9
	v_and_b32_e32 v17, 0xffff0000, v9
	v_mul_f32_e32 v2, 0xbfb8aa3b, v11
	v_mul_f32_e32 v8, 0xbfb8aa3b, v13
	v_mul_f32_e32 v9, 0xbfb8aa3b, v15
	v_mul_f32_e32 v23, 0xbfb8aa3b, v17
	v_exp_f32_e32 v2, v2
	v_exp_f32_e32 v8, v8
	v_exp_f32_e32 v9, v9
	v_exp_f32_e32 v23, v23
	v_add_f32_e32 v2, 1.0, v2
	v_add_f32_e32 v8, 1.0, v8
	v_add_f32_e32 v9, 1.0, v9
	v_add_f32_e32 v29, 1.0, v23
	v_rcp_f32_e32 v23, v2
	v_rcp_f32_e32 v25, v8
	v_rcp_f32_e32 v27, v9
	v_rcp_f32_e32 v29, v29
	v_pk_mul_f32 v[8:9], v[22:23], v[10:11]
	v_pk_mul_f32 v[10:11], v[24:25], v[12:13]
	v_pk_mul_f32 v[12:13], v[26:27], v[14:15]
	v_pk_mul_f32 v[14:15], v[28:29], v[16:17]
	v_mul_f32_e32 v2, v8, v9
	v_mul_f32_e32 v8, v10, v11
	v_mul_f32_e32 v9, v12, v13
	v_mul_f32_e32 v10, v14, v15
	v_cvt_pk_bf16_f32 v8, v2, v8
	v_cvt_pk_bf16_f32 v9, v9, v10
	global_store_dwordx2 v[0:1], v[8:9], off offset:1824
	v_mov_b64_e32 v[8:9], v[210:211]
	v_lshlrev_b32_e32 v10, 16, v73
	v_and_b32_e32 v12, 0xffff0000, v73
	v_lshlrev_b32_e32 v14, 16, v72
	v_and_b32_e32 v16, 0xffff0000, v72
	v_or_b32_e32 v18, 0x360, v32
	v_mov_b32_e32 v19, v33
	v_lshl_add_u64 v[18:19], v[4:5], 0, v[18:19]
	v_lshlrev_b32_e32 v11, 16, v8
	v_and_b32_e32 v13, 0xffff0000, v8
	v_lshlrev_b32_e32 v15, 16, v9
	v_and_b32_e32 v17, 0xffff0000, v9
	v_mul_f32_e32 v2, 0xbfb8aa3b, v11
	v_mul_f32_e32 v8, 0xbfb8aa3b, v13
	v_mul_f32_e32 v9, 0xbfb8aa3b, v15
	v_mul_f32_e32 v23, 0xbfb8aa3b, v17
	v_exp_f32_e32 v2, v2
	v_exp_f32_e32 v8, v8
	v_exp_f32_e32 v9, v9
	v_exp_f32_e32 v23, v23
	v_add_f32_e32 v2, 1.0, v2
	v_add_f32_e32 v8, 1.0, v8
	v_add_f32_e32 v9, 1.0, v9
	v_add_f32_e32 v29, 1.0, v23
	v_rcp_f32_e32 v23, v2
	v_rcp_f32_e32 v25, v8
	v_rcp_f32_e32 v27, v9
	v_rcp_f32_e32 v29, v29
	v_pk_mul_f32 v[8:9], v[22:23], v[10:11]
	v_pk_mul_f32 v[10:11], v[24:25], v[12:13]
	v_pk_mul_f32 v[12:13], v[26:27], v[14:15]
	v_pk_mul_f32 v[14:15], v[28:29], v[16:17]
	v_mul_f32_e32 v2, v8, v9
	v_mul_f32_e32 v8, v10, v11
	v_mul_f32_e32 v9, v12, v13
	v_mul_f32_e32 v10, v14, v15
	v_cvt_pk_bf16_f32 v8, v2, v8
	v_cvt_pk_bf16_f32 v9, v9, v10
	global_store_dwordx2 v[0:1], v[8:9], off offset:1856
	v_mov_b64_e32 v[8:9], v[212:213]
	v_lshlrev_b32_e32 v10, 16, v71
	v_and_b32_e32 v12, 0xffff0000, v71
	v_lshlrev_b32_e32 v14, 16, v69
	v_and_b32_e32 v16, 0xffff0000, v69
	v_or_b32_e32 v18, 0x380, v32
	v_mov_b32_e32 v19, v33
	v_lshl_add_u64 v[18:19], v[4:5], 0, v[18:19]
	v_lshlrev_b32_e32 v11, 16, v8
	v_and_b32_e32 v13, 0xffff0000, v8
	v_lshlrev_b32_e32 v15, 16, v9
	v_and_b32_e32 v17, 0xffff0000, v9
	v_mul_f32_e32 v2, 0xbfb8aa3b, v11
	v_mul_f32_e32 v8, 0xbfb8aa3b, v13
	v_mul_f32_e32 v9, 0xbfb8aa3b, v15
	v_mul_f32_e32 v23, 0xbfb8aa3b, v17
	v_exp_f32_e32 v2, v2
	v_exp_f32_e32 v8, v8
	v_exp_f32_e32 v9, v9
	v_exp_f32_e32 v23, v23
	v_add_f32_e32 v2, 1.0, v2
	v_add_f32_e32 v8, 1.0, v8
	v_add_f32_e32 v9, 1.0, v9
	v_add_f32_e32 v29, 1.0, v23
	v_rcp_f32_e32 v23, v2
	v_rcp_f32_e32 v25, v8
	v_rcp_f32_e32 v27, v9
	v_rcp_f32_e32 v29, v29
	v_pk_mul_f32 v[8:9], v[22:23], v[10:11]
	v_pk_mul_f32 v[10:11], v[24:25], v[12:13]
	v_pk_mul_f32 v[12:13], v[26:27], v[14:15]
	v_pk_mul_f32 v[14:15], v[28:29], v[16:17]
	v_mul_f32_e32 v2, v8, v9
	v_mul_f32_e32 v8, v10, v11
	v_mul_f32_e32 v9, v12, v13
	v_mul_f32_e32 v10, v14, v15
	v_cvt_pk_bf16_f32 v8, v2, v8
	v_cvt_pk_bf16_f32 v9, v9, v10
	global_store_dwordx2 v[0:1], v[8:9], off offset:1888
	v_mov_b64_e32 v[8:9], v[214:215]
	v_lshlrev_b32_e32 v10, 16, v70
	v_and_b32_e32 v12, 0xffff0000, v70
	v_lshlrev_b32_e32 v14, 16, v68
	v_and_b32_e32 v16, 0xffff0000, v68
	v_or_b32_e32 v18, 0x3a0, v32
	v_mov_b32_e32 v19, v33
	v_lshl_add_u64 v[18:19], v[4:5], 0, v[18:19]
	v_lshlrev_b32_e32 v11, 16, v8
	v_and_b32_e32 v13, 0xffff0000, v8
	v_lshlrev_b32_e32 v15, 16, v9
	v_and_b32_e32 v17, 0xffff0000, v9
	v_mul_f32_e32 v2, 0xbfb8aa3b, v11
	v_mul_f32_e32 v8, 0xbfb8aa3b, v13
	v_mul_f32_e32 v9, 0xbfb8aa3b, v15
	v_mul_f32_e32 v23, 0xbfb8aa3b, v17
	v_exp_f32_e32 v2, v2
	v_exp_f32_e32 v8, v8
	v_exp_f32_e32 v9, v9
	v_exp_f32_e32 v23, v23
	v_add_f32_e32 v2, 1.0, v2
	v_add_f32_e32 v8, 1.0, v8
	v_add_f32_e32 v9, 1.0, v9
	v_add_f32_e32 v29, 1.0, v23
	v_rcp_f32_e32 v23, v2
	v_rcp_f32_e32 v25, v8
	v_rcp_f32_e32 v27, v9
	v_rcp_f32_e32 v29, v29
	v_pk_mul_f32 v[8:9], v[22:23], v[10:11]
	v_pk_mul_f32 v[10:11], v[24:25], v[12:13]
	v_pk_mul_f32 v[12:13], v[26:27], v[14:15]
	v_pk_mul_f32 v[14:15], v[28:29], v[16:17]
	v_mul_f32_e32 v2, v8, v9
	v_mul_f32_e32 v8, v10, v11
	v_mul_f32_e32 v9, v12, v13
	v_mul_f32_e32 v10, v14, v15
	v_cvt_pk_bf16_f32 v8, v2, v8
	v_cvt_pk_bf16_f32 v9, v9, v10
	global_store_dwordx2 v[0:1], v[8:9], off offset:1920
	v_mov_b64_e32 v[8:9], v[216:217]
	v_lshlrev_b32_e32 v10, 16, v66
	v_and_b32_e32 v12, 0xffff0000, v66
	v_lshlrev_b32_e32 v14, 16, v64
	v_and_b32_e32 v16, 0xffff0000, v64
	v_or_b32_e32 v18, 0x3c0, v32
	v_mov_b32_e32 v19, v33
	v_lshl_add_u64 v[18:19], v[4:5], 0, v[18:19]
	v_or_b32_e32 v32, 0x3e0, v32
	v_lshl_add_u64 v[4:5], v[4:5], 0, v[32:33]
	v_lshlrev_b32_e32 v11, 16, v8
	v_and_b32_e32 v13, 0xffff0000, v8
	v_lshlrev_b32_e32 v15, 16, v9
	v_and_b32_e32 v17, 0xffff0000, v9
	v_mul_f32_e32 v2, 0xbfb8aa3b, v11
	v_mul_f32_e32 v8, 0xbfb8aa3b, v13
	v_mul_f32_e32 v9, 0xbfb8aa3b, v15
	v_mul_f32_e32 v23, 0xbfb8aa3b, v17
	v_exp_f32_e32 v2, v2
	v_exp_f32_e32 v8, v8
	v_exp_f32_e32 v9, v9
	v_exp_f32_e32 v23, v23
	v_add_f32_e32 v2, 1.0, v2
	v_add_f32_e32 v8, 1.0, v8
	v_add_f32_e32 v9, 1.0, v9
	v_add_f32_e32 v29, 1.0, v23
	v_rcp_f32_e32 v23, v2
	v_rcp_f32_e32 v25, v8
	v_rcp_f32_e32 v27, v9
	v_rcp_f32_e32 v29, v29
	v_pk_mul_f32 v[8:9], v[22:23], v[10:11]
	v_pk_mul_f32 v[10:11], v[24:25], v[12:13]
	v_pk_mul_f32 v[12:13], v[26:27], v[14:15]
	v_pk_mul_f32 v[14:15], v[28:29], v[16:17]
	v_mul_f32_e32 v2, v8, v9
	v_mul_f32_e32 v8, v10, v11
	v_mul_f32_e32 v9, v12, v13
	v_mul_f32_e32 v10, v14, v15
	v_cvt_pk_bf16_f32 v8, v2, v8
	v_cvt_pk_bf16_f32 v9, v9, v10
	global_store_dwordx2 v[0:1], v[8:9], off offset:1952
	v_mov_b64_e32 v[8:9], v[218:219]
	v_lshlrev_b32_e32 v10, 16, v21
	v_and_b32_e32 v12, 0xffff0000, v21
	v_lshlrev_b32_e32 v14, 16, v20
	v_and_b32_e32 v16, 0xffff0000, v20
	v_mov_b32_e32 v18, v3
	v_mov_b32_e32 v20, v3
	v_lshlrev_b32_e32 v11, 16, v8
	v_and_b32_e32 v13, 0xffff0000, v8
	v_lshlrev_b32_e32 v15, 16, v9
	v_and_b32_e32 v17, 0xffff0000, v9
	v_mul_f32_e32 v2, 0xbfb8aa3b, v11
	v_mul_f32_e32 v8, 0xbfb8aa3b, v13
	v_mul_f32_e32 v9, 0xbfb8aa3b, v15
	v_mul_f32_e32 v19, 0xbfb8aa3b, v17
	v_exp_f32_e32 v2, v2
	v_exp_f32_e32 v8, v8
	v_exp_f32_e32 v9, v9
	v_exp_f32_e32 v19, v19
	v_add_f32_e32 v2, 1.0, v2
	v_add_f32_e32 v8, 1.0, v8
	v_add_f32_e32 v9, 1.0, v9
	v_add_f32_e32 v25, 1.0, v19
	v_rcp_f32_e32 v19, v2
	v_rcp_f32_e32 v21, v8
	v_rcp_f32_e32 v23, v9
	v_rcp_f32_e32 v25, v25
	v_pk_mul_f32 v[8:9], v[18:19], v[10:11]
	v_pk_mul_f32 v[10:11], v[20:21], v[12:13]
	v_pk_mul_f32 v[12:13], v[22:23], v[14:15]
	v_pk_mul_f32 v[14:15], v[24:25], v[16:17]
	v_mul_f32_e32 v2, v8, v9
	v_mul_f32_e32 v8, v10, v11
	v_mul_f32_e32 v9, v12, v13
	v_mul_f32_e32 v10, v14, v15
	v_cvt_pk_bf16_f32 v8, v2, v8
	v_cvt_pk_bf16_f32 v9, v9, v10
	global_store_dwordx2 v[0:1], v[8:9], off offset:1984
	v_mov_b64_e32 v[4:5], v[220:221]
	v_mov_b32_e32 v12, v3
	v_mov_b32_e32 v14, v3
	v_mov_b32_e32 v16, v3
	v_lshlrev_b32_e32 v2, 16, v7
	v_and_b32_e32 v8, 0xffff0000, v7
	v_lshlrev_b32_e32 v10, 16, v6
	v_and_b32_e32 v6, 0xffff0000, v6
	v_lshlrev_b32_e32 v3, 16, v4
	v_and_b32_e32 v9, 0xffff0000, v4
	v_lshlrev_b32_e32 v11, 16, v5
	v_and_b32_e32 v7, 0xffff0000, v5
	v_mul_f32_e32 v4, 0xbfb8aa3b, v3
	v_mul_f32_e32 v5, 0xbfb8aa3b, v9
	v_mul_f32_e32 v13, 0xbfb8aa3b, v11
	v_mul_f32_e32 v15, 0xbfb8aa3b, v7
	v_exp_f32_e32 v4, v4
	v_exp_f32_e32 v5, v5
	v_exp_f32_e32 v13, v13
	v_exp_f32_e32 v15, v15
	v_add_f32_e32 v4, 1.0, v4
	v_add_f32_e32 v5, 1.0, v5
	v_add_f32_e32 v17, 1.0, v13
	v_add_f32_e32 v19, 1.0, v15
	v_rcp_f32_e32 v13, v4
	v_rcp_f32_e32 v15, v5
	v_rcp_f32_e32 v17, v17
	v_rcp_f32_e32 v19, v19
	v_pk_mul_f32 v[2:3], v[12:13], v[2:3]
	v_pk_mul_f32 v[4:5], v[14:15], v[8:9]
	v_pk_mul_f32 v[8:9], v[16:17], v[10:11]
	v_pk_mul_f32 v[6:7], v[18:19], v[6:7]
	v_mul_f32_e32 v2, v2, v3
	v_mul_f32_e32 v3, v4, v5
	v_mul_f32_e32 v4, v8, v9
	v_mul_f32_e32 v5, v6, v7
	v_cvt_pk_bf16_f32 v2, v2, v3
	v_cvt_pk_bf16_f32 v3, v4, v5
	global_store_dwordx2 v[0:1], v[2:3], off offset:2016
	s_cbranch_scc1 .LBB0_900
